# per-segment s_setprio flips removed from all GEMM loops; one static s_setprio 1 for waves 4-7 (trailing half) at kernel entry
# baseline (speedup 1.0000x reference)
; #define LAS __attribute__((address_space(3)))
; __global__ void __launch_bounds__(512, 2) mega(P parg) {
;     extern __shared__ __attribute__((aligned(16))) unsigned char lds_raw[];
;     LAS unsigned char* lds = (LAS unsigned char*)lds_raw;
;     PCP p = (PCP)__builtin_amdgcn_kernarg_segment_ptr();
;     if (parg.ws == nullptr) cg::this_grid().sync();
;     const int tid = threadIdx.x, bid = blockIdx.x, G = gridDim.x;
_Z4mega1P:
	s_mov_b64 s[52:53], s[0:1]
	s_load_dwordx2 s[0:1], s[0:1], 0xe8
	s_mov_b32 s92, s2
	v_readfirstlane_b32 s3, v0
	s_nop 3
	s_cmpk_lt_u32 s3, 0x100
	s_cbranch_scc1 .Lprio_done
	s_setprio 1
.Lprio_done:
	s_waitcnt lgkmcnt(0)
	s_cmp_eq_u64 s[0:1], 0
	s_mov_b64 s[0:1], 0
	s_cbranch_scc1 .LBB0_2
	v_and_b32_e32 v206, 0x3ff, v0
	s_andn2_b64 vcc, exec, s[0:1]
	s_cbranch_vccz .LBB0_3
	s_branch .LBB0_14

; #define PG8_STAGE(bufoff, gbase, voff) do { _Pragma("unroll") for (int _i = 0; _i < 2; ++_i) { \
;         const unsigned _m0 = ldsu + (unsigned)(bufoff) + ldsw + (unsigned)(_i * 8192); \
;         asm volatile("s_mov_b32 m0, %2\n\ts_nop 0\n\tglobal_load_lds_dwordx4 %0, %1" :: "v"((voff)[_i]), "s"((const char*)(gbase)), "s"(_m0) : "memory"); } } while (0)
; #define PG8_LDA(dst, b, h) do { _Pragma("unroll") for (int m = 0; m < 4; ++m) _Pragma("unroll") for (int k = 0; k < 2; ++k) dst[m][k] = *(const LAS bf16x8*)(lds + PG8_SA(b, h) + aoff + m * 2048 + k * 1024); } while (0)
; #define PG8_LDB(dst, b, h) do { _Pragma("unroll") for (int n = 0; n < 2; ++n) _Pragma("unroll") for (int k = 0; k < 2; ++k) dst[n][k] = *(const LAS bf16x8*)(lds + bbase[b][h] + n * 2048 + k * 1024); } while (0)
; #define PG8_WAIT_V(n) asm volatile("s_waitcnt vmcnt(" #n ")" ::: "memory")
; #define PG8_BAR __builtin_amdgcn_s_barrier()
; template <class Epi>
; __device__ __forceinline__ void gemm_phase(LAS unsigned char* lds, const Gemm g, const StaticOrder& S, const Epi& E) {
;     ...
;         for (int t = 0; t < nt; t += 2) {
;             const bool last = (t == nt - 2);
;             const char* a2 = last ? nA : cA + (size_t)(t + 2) * kstep; const char* b2 = last ? nB : cB + (size_t)(t + 2) * kstep;
;             const char* a3 = a2 + kstep; const char* b3 = b2 + kstep;
;             const char* b1 = cB + (size_t)(t + 1) * kstep;
;             PG8_LDB(B0, 0, 0); PG8_SCHED; PG8_LDA(At, 0, 0); PG8_LDA(At2, 0, 1); PG8_STAGE(PG8_SB(1, 1), b1 + hstepB, voffB);
;             PG8_WAIT_V(8); PG8_WAIT_L(0); PG8_BAR; PG8_MMA2B(0, At, At2, B0); PG8_BAR; PG8_SCHED;
;             PG8_LDB(B0, 0, 1); PG8_STAGE(PG8_SB(0, 0), b2, voffB); PG8_STAGE(PG8_SA(0, 0), a2, voffA); PG8_STAGE(PG8_SA(0, 1), a2 + hstepA, voffA);
;             PG8_WAIT_V(8); PG8_WAIT_L(0); PG8_BAR; PG8_MMA2B(1, At, At2, B0); PG8_BAR; PG8_SCHED;
;             PG8_LDB(B0, 1, 0); PG8_SCHED; PG8_LDA(At, 1, 0); PG8_LDA(At2, 1, 1); PG8_STAGE(PG8_SB(0, 1), b2 + hstepB, voffB);
;             PG8_WAIT_V(8); PG8_WAIT_L(0); PG8_BAR; PG8_MMA2B(0, At, At2, B0); PG8_BAR; PG8_SCHED;
;             PG8_LDB(B0, 1, 1); PG8_STAGE(PG8_SB(1, 0), b3, voffB); PG8_STAGE(PG8_SA(1, 0), a3, voffA); PG8_STAGE(PG8_SA(1, 1), a3 + hstepA, voffA);
;             PG8_WAIT_V(8); PG8_WAIT_L(0); PG8_BAR; PG8_MMA2B(1, At, At2, B0); PG8_BAR; PG8_SCHED;
;         }
.LBB0_233:
	ds_read_b128 v[130:133], v142
	ds_read_b128 v[148:151], v142 offset:1024
	ds_read_b128 v[152:155], v142 offset:2048
	ds_read_b128 v[156:159], v142 offset:3072
	s_add_u32 s8, s4, 0x100
	s_addc_u32 s9, s5, 0
	s_cmp_eq_u32 s62, 12
	s_cselect_b32 s10, s58, s60
	s_cselect_b32 s11, s15, s61
	s_cselect_b32 s80, s59, s8
	s_cselect_b32 s81, s13, s9
	s_add_u32 s38, s10, 0x80
	s_addc_u32 s39, s11, 0
	ds_read_b128 v[166:169], v143
	ds_read_b128 v[178:181], v143 offset:1024
	ds_read_b128 v[182:185], v143 offset:2048
	ds_read_b128 v[186:189], v143 offset:3072
	ds_read_b128 v[190:193], v143 offset:4096
	ds_read_b128 v[194:197], v143 offset:5120
	ds_read_b128 v[198:201], v143 offset:6144
	ds_read_b128 v[202:205], v143 offset:7168
	ds_read_b128 v[214:217], v143 offset:16384
	ds_read_b128 v[218:221], v143 offset:17408
	ds_read_b128 v[222:225], v143 offset:18432
	ds_read_b128 v[226:229], v143 offset:19456
	ds_read_b128 v[230:233], v143 offset:20480
	ds_read_b128 v[234:237], v143 offset:21504
	ds_read_b128 v[238:241], v143 offset:22528
	ds_read_b128 v[242:245], v143 offset:23552
	s_add_u32 s4, s4, 0x40080
	s_addc_u32 s5, s5, 0
	s_mov_b32 m0, s84
	s_nop 0
	global_load_lds_dwordx4 v137, s[4:5]
	s_mov_b32 m0, s85
	s_nop 0
	global_load_lds_dwordx4 v139, s[4:5]
	s_waitcnt vmcnt(8)
	s_waitcnt lgkmcnt(0)
	s_barrier
	s_waitcnt lgkmcnt(14)
	v_mfma_f32_16x16x32_bf16 v[124:127], v[130:133], v[166:169], v[124:127]
	v_mfma_f32_16x16x32_bf16 v[120:123], v[152:155], v[166:169], v[120:123]
	s_waitcnt lgkmcnt(13)
	v_mfma_f32_16x16x32_bf16 v[108:111], v[130:133], v[182:185], v[108:111]
	v_mfma_f32_16x16x32_bf16 v[104:107], v[152:155], v[182:185], v[104:107]
	s_waitcnt lgkmcnt(11)
	v_mfma_f32_16x16x32_bf16 v[92:95], v[130:133], v[190:193], v[92:95]
	v_mfma_f32_16x16x32_bf16 v[88:91], v[152:155], v[190:193], v[88:91]
	s_waitcnt lgkmcnt(9)
	v_mfma_f32_16x16x32_bf16 v[76:79], v[130:133], v[198:201], v[76:79]
	v_mfma_f32_16x16x32_bf16 v[72:75], v[152:155], v[198:201], v[72:75]
	s_waitcnt lgkmcnt(7)
	v_mfma_f32_16x16x32_bf16 v[60:63], v[130:133], v[214:217], v[60:63]
	v_mfma_f32_16x16x32_bf16 v[56:59], v[152:155], v[214:217], v[56:59]
	s_waitcnt lgkmcnt(5)
	v_mfma_f32_16x16x32_bf16 v[44:47], v[130:133], v[222:225], v[44:47]
	v_mfma_f32_16x16x32_bf16 v[40:43], v[152:155], v[222:225], v[40:43]
	s_waitcnt lgkmcnt(3)
	v_mfma_f32_16x16x32_bf16 v[28:31], v[130:133], v[230:233], v[28:31]
	v_mfma_f32_16x16x32_bf16 v[24:27], v[152:155], v[230:233], v[24:27]
	s_waitcnt lgkmcnt(1)
	v_mfma_f32_16x16x32_bf16 v[12:15], v[130:133], v[238:241], v[12:15]
	v_mfma_f32_16x16x32_bf16 v[8:11], v[152:155], v[238:241], v[8:11]
	v_mfma_f32_16x16x32_bf16 v[124:127], v[148:151], v[178:181], v[124:127]
	v_mfma_f32_16x16x32_bf16 v[120:123], v[156:159], v[178:181], v[120:123]
	v_mfma_f32_16x16x32_bf16 v[108:111], v[148:151], v[186:189], v[108:111]
	v_mfma_f32_16x16x32_bf16 v[104:107], v[156:159], v[186:189], v[104:107]
	v_mfma_f32_16x16x32_bf16 v[92:95], v[148:151], v[194:197], v[92:95]
	v_mfma_f32_16x16x32_bf16 v[88:91], v[156:159], v[194:197], v[88:91]
	v_mfma_f32_16x16x32_bf16 v[76:79], v[148:151], v[202:205], v[76:79]
	v_mfma_f32_16x16x32_bf16 v[72:75], v[156:159], v[202:205], v[72:75]
	v_mfma_f32_16x16x32_bf16 v[60:63], v[148:151], v[218:221], v[60:63]
	v_mfma_f32_16x16x32_bf16 v[56:59], v[156:159], v[218:221], v[56:59]
	v_mfma_f32_16x16x32_bf16 v[44:47], v[148:151], v[226:229], v[44:47]
	v_mfma_f32_16x16x32_bf16 v[40:43], v[156:159], v[226:229], v[40:43]
	v_mfma_f32_16x16x32_bf16 v[28:31], v[148:151], v[234:237], v[28:31]
	v_mfma_f32_16x16x32_bf16 v[24:27], v[156:159], v[234:237], v[24:27]
	s_waitcnt lgkmcnt(0)
	v_mfma_f32_16x16x32_bf16 v[12:15], v[148:151], v[242:245], v[12:15]
	v_mfma_f32_16x16x32_bf16 v[8:11], v[156:159], v[242:245], v[8:11]
	s_barrier
	ds_read_b128 v[130:133], v144
	ds_read_b128 v[148:151], v144 offset:1024
	ds_read_b128 v[152:155], v144 offset:2048
	ds_read_b128 v[156:159], v144 offset:3072
	s_mov_b32 m0, s29
	s_nop 0
	global_load_lds_dwordx4 v137, s[80:81]
	s_mov_b32 m0, s37
	s_nop 0
	global_load_lds_dwordx4 v139, s[80:81]
	s_mov_b32 m0, s28
	s_nop 0
	global_load_lds_dwordx4 v136, s[10:11]
	s_mov_b32 m0, s47
	s_nop 0
	global_load_lds_dwordx4 v138, s[10:11]
	s_add_u32 s4, s10, 0x40000
	s_addc_u32 s5, s11, 0
	s_mov_b32 m0, s48
	s_nop 0
	global_load_lds_dwordx4 v136, s[4:5]
	s_mov_b32 m0, s49
	s_nop 0
	global_load_lds_dwordx4 v138, s[4:5]
	s_waitcnt vmcnt(8)
	s_waitcnt lgkmcnt(0)
	s_barrier
	s_waitcnt lgkmcnt(3)
	v_mfma_f32_16x16x32_bf16 v[116:119], v[130:133], v[166:169], v[116:119]
	s_waitcnt lgkmcnt(1)
	v_mfma_f32_16x16x32_bf16 v[112:115], v[152:155], v[166:169], v[112:115]
	v_mfma_f32_16x16x32_bf16 v[100:103], v[130:133], v[182:185], v[100:103]
	v_mfma_f32_16x16x32_bf16 v[96:99], v[152:155], v[182:185], v[96:99]
	v_mfma_f32_16x16x32_bf16 v[84:87], v[130:133], v[190:193], v[84:87]
	v_mfma_f32_16x16x32_bf16 v[80:83], v[152:155], v[190:193], v[80:83]
	v_mfma_f32_16x16x32_bf16 v[68:71], v[130:133], v[198:201], v[68:71]
	v_mfma_f32_16x16x32_bf16 v[64:67], v[152:155], v[198:201], v[64:67]
	v_mfma_f32_16x16x32_bf16 v[52:55], v[130:133], v[214:217], v[52:55]
	v_mfma_f32_16x16x32_bf16 v[48:51], v[152:155], v[214:217], v[48:51]
	v_mfma_f32_16x16x32_bf16 v[36:39], v[130:133], v[222:225], v[36:39]
	v_mfma_f32_16x16x32_bf16 v[32:35], v[152:155], v[222:225], v[32:35]
	v_mfma_f32_16x16x32_bf16 v[20:23], v[130:133], v[230:233], v[20:23]
	v_mfma_f32_16x16x32_bf16 v[16:19], v[152:155], v[230:233], v[16:19]
	v_mfma_f32_16x16x32_bf16 v[4:7], v[130:133], v[238:241], v[4:7]
	v_mfma_f32_16x16x32_bf16 v[0:3], v[152:155], v[238:241], v[0:3]
	v_mfma_f32_16x16x32_bf16 v[116:119], v[148:151], v[178:181], v[116:119]
	s_waitcnt lgkmcnt(0)
	v_mfma_f32_16x16x32_bf16 v[112:115], v[156:159], v[178:181], v[112:115]
	v_mfma_f32_16x16x32_bf16 v[100:103], v[148:151], v[186:189], v[100:103]
	v_mfma_f32_16x16x32_bf16 v[96:99], v[156:159], v[186:189], v[96:99]
	v_mfma_f32_16x16x32_bf16 v[84:87], v[148:151], v[194:197], v[84:87]
	v_mfma_f32_16x16x32_bf16 v[80:83], v[156:159], v[194:197], v[80:83]
	v_mfma_f32_16x16x32_bf16 v[68:71], v[148:151], v[202:205], v[68:71]
	v_mfma_f32_16x16x32_bf16 v[64:67], v[156:159], v[202:205], v[64:67]
	v_mfma_f32_16x16x32_bf16 v[52:55], v[148:151], v[218:221], v[52:55]
	v_mfma_f32_16x16x32_bf16 v[48:51], v[156:159], v[218:221], v[48:51]
	v_mfma_f32_16x16x32_bf16 v[36:39], v[148:151], v[226:229], v[36:39]
	v_mfma_f32_16x16x32_bf16 v[32:35], v[156:159], v[226:229], v[32:35]
	v_mfma_f32_16x16x32_bf16 v[20:23], v[148:151], v[234:237], v[20:23]
	v_mfma_f32_16x16x32_bf16 v[16:19], v[156:159], v[234:237], v[16:19]
	v_mfma_f32_16x16x32_bf16 v[4:7], v[148:151], v[242:245], v[4:7]
	v_mfma_f32_16x16x32_bf16 v[0:3], v[156:159], v[242:245], v[0:3]
	s_barrier
; #define PG8_STAGE(bufoff, gbase, voff) do { _Pragma("unroll") for (int _i = 0; _i < 2; ++_i) { \
;         const unsigned _m0 = ldsu + (unsigned)(bufoff) + ldsw + (unsigned)(_i * 8192); \
;         asm volatile("s_mov_b32 m0, %2\n\ts_nop 0\n\tglobal_load_lds_dwordx4 %0, %1" :: "v"((voff)[_i]), "s"((const char*)(gbase)), "s"(_m0) : "memory"); } } while (0)
; #define PG8_LDA(dst, b, h) do { _Pragma("unroll") for (int m = 0; m < 4; ++m) _Pragma("unroll") for (int k = 0; k < 2; ++k) dst[m][k] = *(const LAS bf16x8*)(lds + PG8_SA(b, h) + aoff + m * 2048 + k * 1024); } while (0)
; #define PG8_LDB(dst, b, h) do { _Pragma("unroll") for (int n = 0; n < 2; ++n) _Pragma("unroll") for (int k = 0; k < 2; ++k) dst[n][k] = *(const LAS bf16x8*)(lds + bbase[b][h] + n * 2048 + k * 1024); } while (0)
; #define PG8_WAIT_V(n) asm volatile("s_waitcnt vmcnt(" #n ")" ::: "memory")
; template <class Epi>
; __device__ __forceinline__ void gemm_phase(LAS unsigned char* lds, const Gemm g, const StaticOrder& S, const Epi& E) {
;     ...
;         for (int t = 0; t < nt; t += 2) {
;             const bool last = (t == nt - 2);
;             const char* a2 = last ? nA : cA + (size_t)(t + 2) * kstep; const char* b2 = last ? nB : cB + (size_t)(t + 2) * kstep;
;             const char* a3 = a2 + kstep; const char* b3 = b2 + kstep;
;             const char* b1 = cB + (size_t)(t + 1) * kstep;
;             PG8_LDB(B0, 0, 0); PG8_SCHED; PG8_LDA(At, 0, 0); PG8_LDA(At2, 0, 1); PG8_STAGE(PG8_SB(1, 1), b1 + hstepB, voffB);
;             PG8_WAIT_V(8); PG8_WAIT_L(0); PG8_BAR; PG8_MMA2B(0, At, At2, B0); PG8_BAR; PG8_SCHED;
;             PG8_LDB(B0, 0, 1); PG8_STAGE(PG8_SB(0, 0), b2, voffB); PG8_STAGE(PG8_SA(0, 0), a2, voffA); PG8_STAGE(PG8_SA(0, 1), a2 + hstepA, voffA);
;             PG8_WAIT_V(8); PG8_WAIT_L(0); PG8_BAR; PG8_MMA2B(1, At, At2, B0); PG8_BAR; PG8_SCHED;
;             PG8_LDB(B0, 1, 0); PG8_SCHED; PG8_LDA(At, 1, 0); PG8_LDA(At2, 1, 1); PG8_STAGE(PG8_SB(0, 1), b2 + hstepB, voffB);
;             PG8_WAIT_V(8); PG8_WAIT_L(0); PG8_BAR; PG8_MMA2B(0, At, At2, B0); PG8_BAR; PG8_SCHED;
;             PG8_LDB(B0, 1, 1); PG8_STAGE(PG8_SB(1, 0), b3, voffB); PG8_STAGE(PG8_SA(1, 0), a3, voffA); PG8_STAGE(PG8_SA(1, 1), a3 + hstepA, voffA);
;             PG8_WAIT_V(8); PG8_WAIT_L(0); PG8_BAR; PG8_MMA2B(1, At, At2, B0); PG8_BAR; PG8_SCHED;
;         }
;         if (wr == 0) PG8_BAR;
	ds_read_b128 v[130:133], v145
	ds_read_b128 v[148:151], v145 offset:1024
	ds_read_b128 v[152:155], v145 offset:2048
	ds_read_b128 v[156:159], v145 offset:3072
	ds_read_b128 v[166:169], v143 offset:32768
	ds_read_b128 v[178:181], v143 offset:33792
	ds_read_b128 v[182:185], v143 offset:34816
	ds_read_b128 v[186:189], v143 offset:35840
	ds_read_b128 v[190:193], v143 offset:36864
	ds_read_b128 v[194:197], v143 offset:37888
	ds_read_b128 v[198:201], v143 offset:38912
	ds_read_b128 v[202:205], v143 offset:39936
	ds_read_b128 v[214:217], v143 offset:49152
	ds_read_b128 v[218:221], v143 offset:50176
	ds_read_b128 v[222:225], v143 offset:51200
	ds_read_b128 v[226:229], v143 offset:52224
	ds_read_b128 v[230:233], v143 offset:53248
	ds_read_b128 v[234:237], v143 offset:54272
	ds_read_b128 v[238:241], v143 offset:55296
	ds_read_b128 v[242:245], v143 offset:56320
	s_add_u32 s4, s80, 0x40000
	s_addc_u32 s5, s81, 0
	s_mov_b32 m0, s50
	s_nop 0
	global_load_lds_dwordx4 v137, s[4:5]
	s_mov_b32 m0, s51
	s_nop 0
	global_load_lds_dwordx4 v139, s[4:5]
	s_waitcnt vmcnt(8)
	s_waitcnt lgkmcnt(0)
	s_barrier
	s_waitcnt lgkmcnt(14)
	v_mfma_f32_16x16x32_bf16 v[124:127], v[130:133], v[166:169], v[124:127]
	v_mfma_f32_16x16x32_bf16 v[120:123], v[152:155], v[166:169], v[120:123]
	s_waitcnt lgkmcnt(13)
	v_mfma_f32_16x16x32_bf16 v[108:111], v[130:133], v[182:185], v[108:111]
	v_mfma_f32_16x16x32_bf16 v[104:107], v[152:155], v[182:185], v[104:107]
	s_waitcnt lgkmcnt(11)
	v_mfma_f32_16x16x32_bf16 v[92:95], v[130:133], v[190:193], v[92:95]
	v_mfma_f32_16x16x32_bf16 v[88:91], v[152:155], v[190:193], v[88:91]
	s_waitcnt lgkmcnt(9)
	v_mfma_f32_16x16x32_bf16 v[76:79], v[130:133], v[198:201], v[76:79]
	v_mfma_f32_16x16x32_bf16 v[72:75], v[152:155], v[198:201], v[72:75]
	s_waitcnt lgkmcnt(7)
	v_mfma_f32_16x16x32_bf16 v[60:63], v[130:133], v[214:217], v[60:63]
	v_mfma_f32_16x16x32_bf16 v[56:59], v[152:155], v[214:217], v[56:59]
	s_waitcnt lgkmcnt(5)
	v_mfma_f32_16x16x32_bf16 v[44:47], v[130:133], v[222:225], v[44:47]
	v_mfma_f32_16x16x32_bf16 v[40:43], v[152:155], v[222:225], v[40:43]
	s_waitcnt lgkmcnt(3)
	v_mfma_f32_16x16x32_bf16 v[28:31], v[130:133], v[230:233], v[28:31]
	v_mfma_f32_16x16x32_bf16 v[24:27], v[152:155], v[230:233], v[24:27]
	s_waitcnt lgkmcnt(1)
	v_mfma_f32_16x16x32_bf16 v[12:15], v[130:133], v[238:241], v[12:15]
	v_mfma_f32_16x16x32_bf16 v[8:11], v[152:155], v[238:241], v[8:11]
	v_mfma_f32_16x16x32_bf16 v[124:127], v[148:151], v[178:181], v[124:127]
	v_mfma_f32_16x16x32_bf16 v[120:123], v[156:159], v[178:181], v[120:123]
	v_mfma_f32_16x16x32_bf16 v[108:111], v[148:151], v[186:189], v[108:111]
	v_mfma_f32_16x16x32_bf16 v[104:107], v[156:159], v[186:189], v[104:107]
	v_mfma_f32_16x16x32_bf16 v[92:95], v[148:151], v[194:197], v[92:95]
	v_mfma_f32_16x16x32_bf16 v[88:91], v[156:159], v[194:197], v[88:91]
	v_mfma_f32_16x16x32_bf16 v[76:79], v[148:151], v[202:205], v[76:79]
	v_mfma_f32_16x16x32_bf16 v[72:75], v[156:159], v[202:205], v[72:75]
	v_mfma_f32_16x16x32_bf16 v[60:63], v[148:151], v[218:221], v[60:63]
	v_mfma_f32_16x16x32_bf16 v[56:59], v[156:159], v[218:221], v[56:59]
	v_mfma_f32_16x16x32_bf16 v[44:47], v[148:151], v[226:229], v[44:47]
	v_mfma_f32_16x16x32_bf16 v[40:43], v[156:159], v[226:229], v[40:43]
	v_mfma_f32_16x16x32_bf16 v[28:31], v[148:151], v[234:237], v[28:31]
	v_mfma_f32_16x16x32_bf16 v[24:27], v[156:159], v[234:237], v[24:27]
	s_waitcnt lgkmcnt(0)
	v_mfma_f32_16x16x32_bf16 v[12:15], v[148:151], v[242:245], v[12:15]
	v_mfma_f32_16x16x32_bf16 v[8:11], v[156:159], v[242:245], v[8:11]
	s_barrier
	s_add_u32 s4, s80, 0x80
	ds_read_b128 v[130:133], v146
	ds_read_b128 v[148:151], v146 offset:1024
	ds_read_b128 v[152:155], v146 offset:2048
	ds_read_b128 v[156:159], v146 offset:3072
	s_addc_u32 s5, s81, 0
	s_mov_b32 m0, s52
	s_nop 0
	global_load_lds_dwordx4 v137, s[4:5]
	s_mov_b32 m0, s53
	s_nop 0
	global_load_lds_dwordx4 v139, s[4:5]
	s_mov_b32 m0, s54
	s_nop 0
	global_load_lds_dwordx4 v136, s[38:39]
	s_mov_b32 m0, s55
	s_nop 0
	global_load_lds_dwordx4 v138, s[38:39]
	s_add_u32 s4, s10, 0x40080
	s_addc_u32 s5, s11, 0
	s_mov_b32 m0, s82
	s_nop 0
	global_load_lds_dwordx4 v136, s[4:5]
	s_mov_b32 m0, s83
	s_nop 0
	global_load_lds_dwordx4 v138, s[4:5]
	s_waitcnt vmcnt(8)
	s_waitcnt lgkmcnt(0)
	s_barrier
	s_waitcnt lgkmcnt(3)
	v_mfma_f32_16x16x32_bf16 v[116:119], v[130:133], v[166:169], v[116:119]
	s_waitcnt lgkmcnt(1)
	v_mfma_f32_16x16x32_bf16 v[112:115], v[152:155], v[166:169], v[112:115]
	v_mfma_f32_16x16x32_bf16 v[100:103], v[130:133], v[182:185], v[100:103]
	v_mfma_f32_16x16x32_bf16 v[96:99], v[152:155], v[182:185], v[96:99]
	v_mfma_f32_16x16x32_bf16 v[84:87], v[130:133], v[190:193], v[84:87]
	v_mfma_f32_16x16x32_bf16 v[80:83], v[152:155], v[190:193], v[80:83]
	v_mfma_f32_16x16x32_bf16 v[68:71], v[130:133], v[198:201], v[68:71]
	v_mfma_f32_16x16x32_bf16 v[64:67], v[152:155], v[198:201], v[64:67]
	v_mfma_f32_16x16x32_bf16 v[52:55], v[130:133], v[214:217], v[52:55]
	v_mfma_f32_16x16x32_bf16 v[48:51], v[152:155], v[214:217], v[48:51]
	v_mfma_f32_16x16x32_bf16 v[36:39], v[130:133], v[222:225], v[36:39]
	v_mfma_f32_16x16x32_bf16 v[32:35], v[152:155], v[222:225], v[32:35]
	v_mfma_f32_16x16x32_bf16 v[20:23], v[130:133], v[230:233], v[20:23]
	v_mfma_f32_16x16x32_bf16 v[16:19], v[152:155], v[230:233], v[16:19]
	v_mfma_f32_16x16x32_bf16 v[4:7], v[130:133], v[238:241], v[4:7]
	v_mfma_f32_16x16x32_bf16 v[0:3], v[152:155], v[238:241], v[0:3]
	v_mfma_f32_16x16x32_bf16 v[116:119], v[148:151], v[178:181], v[116:119]
	s_waitcnt lgkmcnt(0)
	v_mfma_f32_16x16x32_bf16 v[112:115], v[156:159], v[178:181], v[112:115]
	v_mfma_f32_16x16x32_bf16 v[100:103], v[148:151], v[186:189], v[100:103]
	v_mfma_f32_16x16x32_bf16 v[96:99], v[156:159], v[186:189], v[96:99]
	v_mfma_f32_16x16x32_bf16 v[84:87], v[148:151], v[194:197], v[84:87]
	v_mfma_f32_16x16x32_bf16 v[80:83], v[156:159], v[194:197], v[80:83]
	v_mfma_f32_16x16x32_bf16 v[68:71], v[148:151], v[202:205], v[68:71]
	v_mfma_f32_16x16x32_bf16 v[64:67], v[156:159], v[202:205], v[64:67]
	v_mfma_f32_16x16x32_bf16 v[52:55], v[148:151], v[218:221], v[52:55]
	v_mfma_f32_16x16x32_bf16 v[48:51], v[156:159], v[218:221], v[48:51]
	v_mfma_f32_16x16x32_bf16 v[36:39], v[148:151], v[226:229], v[36:39]
	v_mfma_f32_16x16x32_bf16 v[32:35], v[156:159], v[226:229], v[32:35]
	v_mfma_f32_16x16x32_bf16 v[20:23], v[148:151], v[234:237], v[20:23]
	v_mfma_f32_16x16x32_bf16 v[16:19], v[156:159], v[234:237], v[16:19]
	v_mfma_f32_16x16x32_bf16 v[4:7], v[148:151], v[242:245], v[4:7]
	v_mfma_f32_16x16x32_bf16 v[0:3], v[156:159], v[242:245], v[0:3]
	s_barrier
	s_add_i32 s62, s62, 2
	s_add_u32 s60, s60, 0x100
	s_addc_u32 s61, s61, 0
	s_cmp_gt_u32 s62, 13
	s_mov_b64 s[4:5], s[8:9]
	s_cbranch_scc0 .LBB0_233
	s_and_b64 vcc, exec, s[2:3]
	s_cbranch_vccz .LBB0_236
	s_barrier

; #define PG8_STAGE(bufoff, gbase, voff) do { _Pragma("unroll") for (int _i = 0; _i < 2; ++_i) { \
;         const unsigned _m0 = ldsu + (unsigned)(bufoff) + ldsw + (unsigned)(_i * 8192); \
;         asm volatile("s_mov_b32 m0, %2\n\ts_nop 0\n\tglobal_load_lds_dwordx4 %0, %1" :: "v"((voff)[_i]), "s"((const char*)(gbase)), "s"(_m0) : "memory"); } } while (0)
; #define PG8_LDA(dst, b, h) do { _Pragma("unroll") for (int m = 0; m < 4; ++m) _Pragma("unroll") for (int k = 0; k < 2; ++k) dst[m][k] = *(const LAS bf16x8*)(lds + PG8_SA(b, h) + aoff + m * 2048 + k * 1024); } while (0)
; #define PG8_LDB(dst, b, h) do { _Pragma("unroll") for (int n = 0; n < 2; ++n) _Pragma("unroll") for (int k = 0; k < 2; ++k) dst[n][k] = *(const LAS bf16x8*)(lds + bbase[b][h] + n * 2048 + k * 1024); } while (0)
; #define PG8_WAIT_V(n) asm volatile("s_waitcnt vmcnt(" #n ")" ::: "memory")
; #define PG8_BAR __builtin_amdgcn_s_barrier()
; template <class Epi>
; __device__ __forceinline__ void gemm_phase(LAS unsigned char* lds, const Gemm g, const StaticOrder& S, const Epi& E) {
;     ...
;         for (int t = 0; t < nt; t += 2) {
;             const bool last = (t == nt - 2);
;             const char* a2 = last ? nA : cA + (size_t)(t + 2) * kstep; const char* b2 = last ? nB : cB + (size_t)(t + 2) * kstep;
;             const char* a3 = a2 + kstep; const char* b3 = b2 + kstep;
;             const char* b1 = cB + (size_t)(t + 1) * kstep;
;             PG8_LDB(B0, 0, 0); PG8_SCHED; PG8_LDA(At, 0, 0); PG8_LDA(At2, 0, 1); PG8_STAGE(PG8_SB(1, 1), b1 + hstepB, voffB);
;             PG8_WAIT_V(8); PG8_WAIT_L(0); PG8_BAR; PG8_MMA2B(0, At, At2, B0); PG8_BAR; PG8_SCHED;
;             PG8_LDB(B0, 0, 1); PG8_STAGE(PG8_SB(0, 0), b2, voffB); PG8_STAGE(PG8_SA(0, 0), a2, voffA); PG8_STAGE(PG8_SA(0, 1), a2 + hstepA, voffA);
;             PG8_WAIT_V(8); PG8_WAIT_L(0); PG8_BAR; PG8_MMA2B(1, At, At2, B0); PG8_BAR; PG8_SCHED;
;             PG8_LDB(B0, 1, 0); PG8_SCHED; PG8_LDA(At, 1, 0); PG8_LDA(At2, 1, 1); PG8_STAGE(PG8_SB(0, 1), b2 + hstepB, voffB);
;             PG8_WAIT_V(8); PG8_WAIT_L(0); PG8_BAR; PG8_MMA2B(0, At, At2, B0); PG8_BAR; PG8_SCHED;
;             PG8_LDB(B0, 1, 1); PG8_STAGE(PG8_SB(1, 0), b3, voffB); PG8_STAGE(PG8_SA(1, 0), a3, voffA); PG8_STAGE(PG8_SA(1, 1), a3 + hstepA, voffA);
;             PG8_WAIT_V(8); PG8_WAIT_L(0); PG8_BAR; PG8_MMA2B(1, At, At2, B0); PG8_BAR; PG8_SCHED;
;         }
.LBB0_487:
	s_add_i32 s69, s68, 2
	s_add_u32 s6, s88, 0x80
	ds_read_b128 v[140:143], v134
	ds_read_b128 v[144:147], v134 offset:1024
	ds_read_b128 v[148:151], v134 offset:2048
	ds_read_b128 v[152:155], v134 offset:3072
	s_addc_u32 s7, s89, 0
	s_cmp_eq_u32 s62, s68
	s_cselect_b32 s80, s17, s95
	s_cselect_b32 s81, s15, s96
	s_cselect_b32 s90, s87, s6
	s_cselect_b32 s91, s86, s7
	s_add_u32 s82, s80, 0x80
	s_addc_u32 s83, s81, 0
	s_add_u32 s84, s90, 0x80
	s_addc_u32 s85, s91, 0
	ds_read_b128 v[156:159], v135
	ds_read_b128 v[166:169], v135 offset:1024
	ds_read_b128 v[178:181], v135 offset:2048
	ds_read_b128 v[182:185], v135 offset:3072
	ds_read_b128 v[186:189], v135 offset:4096
	ds_read_b128 v[190:193], v135 offset:5120
	ds_read_b128 v[194:197], v135 offset:6144
	ds_read_b128 v[198:201], v135 offset:7168
	ds_read_b128 v[202:205], v135 offset:16384
	ds_read_b128 v[214:217], v135 offset:17408
	ds_read_b128 v[218:221], v135 offset:18432
	ds_read_b128 v[222:225], v135 offset:19456
	ds_read_b128 v[226:229], v135 offset:20480
	ds_read_b128 v[230:233], v135 offset:21504
	ds_read_b128 v[234:237], v135 offset:22528
	ds_read_b128 v[238:241], v135 offset:23552
	s_add_u32 s6, s88, 0x20000
	s_addc_u32 s7, s89, 0
	s_mov_b32 m0, s63
	s_nop 0
	global_load_lds_dwordx4 v129, s[6:7]
	s_mov_b32 m0, s64
	s_nop 0
	global_load_lds_dwordx4 v131, s[6:7]
	s_waitcnt vmcnt(8)
	s_waitcnt lgkmcnt(0)
	s_barrier
	s_waitcnt lgkmcnt(14)
	v_mfma_f32_16x16x32_bf16 v[120:123], v[140:143], v[156:159], v[120:123]
	v_mfma_f32_16x16x32_bf16 v[124:127], v[148:151], v[156:159], v[124:127]
	s_waitcnt lgkmcnt(13)
	v_mfma_f32_16x16x32_bf16 v[108:111], v[140:143], v[178:181], v[108:111]
	v_mfma_f32_16x16x32_bf16 v[104:107], v[148:151], v[178:181], v[104:107]
	s_waitcnt lgkmcnt(11)
	v_mfma_f32_16x16x32_bf16 v[92:95], v[140:143], v[186:189], v[92:95]
	v_mfma_f32_16x16x32_bf16 v[88:91], v[148:151], v[186:189], v[88:91]
	s_waitcnt lgkmcnt(9)
	v_mfma_f32_16x16x32_bf16 v[76:79], v[140:143], v[194:197], v[76:79]
	v_mfma_f32_16x16x32_bf16 v[72:75], v[148:151], v[194:197], v[72:75]
	s_waitcnt lgkmcnt(7)
	v_mfma_f32_16x16x32_bf16 v[60:63], v[140:143], v[202:205], v[60:63]
	v_mfma_f32_16x16x32_bf16 v[56:59], v[148:151], v[202:205], v[56:59]
	s_waitcnt lgkmcnt(5)
	v_mfma_f32_16x16x32_bf16 v[44:47], v[140:143], v[218:221], v[44:47]
	v_mfma_f32_16x16x32_bf16 v[40:43], v[148:151], v[218:221], v[40:43]
	s_waitcnt lgkmcnt(3)
	v_mfma_f32_16x16x32_bf16 v[28:31], v[140:143], v[226:229], v[28:31]
	v_mfma_f32_16x16x32_bf16 v[24:27], v[148:151], v[226:229], v[24:27]
	s_waitcnt lgkmcnt(1)
	v_mfma_f32_16x16x32_bf16 v[12:15], v[140:143], v[234:237], v[12:15]
	v_mfma_f32_16x16x32_bf16 v[8:11], v[148:151], v[234:237], v[8:11]
	v_mfma_f32_16x16x32_bf16 v[120:123], v[144:147], v[166:169], v[120:123]
	v_mfma_f32_16x16x32_bf16 v[124:127], v[152:155], v[166:169], v[124:127]
	v_mfma_f32_16x16x32_bf16 v[108:111], v[144:147], v[182:185], v[108:111]
	v_mfma_f32_16x16x32_bf16 v[104:107], v[152:155], v[182:185], v[104:107]
	v_mfma_f32_16x16x32_bf16 v[92:95], v[144:147], v[190:193], v[92:95]
	v_mfma_f32_16x16x32_bf16 v[88:91], v[152:155], v[190:193], v[88:91]
	v_mfma_f32_16x16x32_bf16 v[76:79], v[144:147], v[198:201], v[76:79]
	v_mfma_f32_16x16x32_bf16 v[72:75], v[152:155], v[198:201], v[72:75]
	v_mfma_f32_16x16x32_bf16 v[60:63], v[144:147], v[214:217], v[60:63]
	v_mfma_f32_16x16x32_bf16 v[56:59], v[152:155], v[214:217], v[56:59]
	v_mfma_f32_16x16x32_bf16 v[44:47], v[144:147], v[222:225], v[44:47]
	v_mfma_f32_16x16x32_bf16 v[40:43], v[152:155], v[222:225], v[40:43]
	v_mfma_f32_16x16x32_bf16 v[28:31], v[144:147], v[230:233], v[28:31]
	v_mfma_f32_16x16x32_bf16 v[24:27], v[152:155], v[230:233], v[24:27]
	s_waitcnt lgkmcnt(0)
	v_mfma_f32_16x16x32_bf16 v[12:15], v[144:147], v[238:241], v[12:15]
	v_mfma_f32_16x16x32_bf16 v[8:11], v[152:155], v[238:241], v[8:11]
	s_barrier
	ds_read_b128 v[140:143], v136
	ds_read_b128 v[144:147], v136 offset:1024
	ds_read_b128 v[148:151], v136 offset:2048
	ds_read_b128 v[152:155], v136 offset:3072
	s_mov_b32 m0, s48
	s_nop 0
	global_load_lds_dwordx4 v129, s[90:91]
	s_mov_b32 m0, s49
	s_nop 0
	global_load_lds_dwordx4 v131, s[90:91]
	s_mov_b32 m0, s47
	s_nop 0
	global_load_lds_dwordx4 v128, s[80:81]
	s_mov_b32 m0, s50
	s_nop 0
	global_load_lds_dwordx4 v130, s[80:81]
	s_add_u32 s6, s80, 0x20000
	s_addc_u32 s7, s81, 0
	s_mov_b32 m0, s52
	s_nop 0
	global_load_lds_dwordx4 v128, s[6:7]
	s_mov_b32 m0, s53
	s_nop 0
	global_load_lds_dwordx4 v130, s[6:7]
	s_waitcnt vmcnt(8)
	s_waitcnt lgkmcnt(0)
	s_barrier
; #define PG8_STAGE(bufoff, gbase, voff) do { _Pragma("unroll") for (int _i = 0; _i < 2; ++_i) { \
;         const unsigned _m0 = ldsu + (unsigned)(bufoff) + ldsw + (unsigned)(_i * 8192); \
;         asm volatile("s_mov_b32 m0, %2\n\ts_nop 0\n\tglobal_load_lds_dwordx4 %0, %1" :: "v"((voff)[_i]), "s"((const char*)(gbase)), "s"(_m0) : "memory"); } } while (0)
; #define PG8_LDA(dst, b, h) do { _Pragma("unroll") for (int m = 0; m < 4; ++m) _Pragma("unroll") for (int k = 0; k < 2; ++k) dst[m][k] = *(const LAS bf16x8*)(lds + PG8_SA(b, h) + aoff + m * 2048 + k * 1024); } while (0)
; #define PG8_LDB(dst, b, h) do { _Pragma("unroll") for (int n = 0; n < 2; ++n) _Pragma("unroll") for (int k = 0; k < 2; ++k) dst[n][k] = *(const LAS bf16x8*)(lds + bbase[b][h] + n * 2048 + k * 1024); } while (0)
; #define PG8_WAIT_V(n) asm volatile("s_waitcnt vmcnt(" #n ")" ::: "memory")
; #define PG8_BAR __builtin_amdgcn_s_barrier()
; template <class Epi>
; __device__ __forceinline__ void gemm_phase(LAS unsigned char* lds, const Gemm g, const StaticOrder& S, const Epi& E) {
;     ...
;         for (int t = 0; t < nt; t += 2) {
;             const bool last = (t == nt - 2);
;             const char* a2 = last ? nA : cA + (size_t)(t + 2) * kstep; const char* b2 = last ? nB : cB + (size_t)(t + 2) * kstep;
;             const char* a3 = a2 + kstep; const char* b3 = b2 + kstep;
;             const char* b1 = cB + (size_t)(t + 1) * kstep;
;             PG8_LDB(B0, 0, 0); PG8_SCHED; PG8_LDA(At, 0, 0); PG8_LDA(At2, 0, 1); PG8_STAGE(PG8_SB(1, 1), b1 + hstepB, voffB);
;             PG8_WAIT_V(8); PG8_WAIT_L(0); PG8_BAR; PG8_MMA2B(0, At, At2, B0); PG8_BAR; PG8_SCHED;
;             PG8_LDB(B0, 0, 1); PG8_STAGE(PG8_SB(0, 0), b2, voffB); PG8_STAGE(PG8_SA(0, 0), a2, voffA); PG8_STAGE(PG8_SA(0, 1), a2 + hstepA, voffA);
;             PG8_WAIT_V(8); PG8_WAIT_L(0); PG8_BAR; PG8_MMA2B(1, At, At2, B0); PG8_BAR; PG8_SCHED;
;             PG8_LDB(B0, 1, 0); PG8_SCHED; PG8_LDA(At, 1, 0); PG8_LDA(At2, 1, 1); PG8_STAGE(PG8_SB(0, 1), b2 + hstepB, voffB);
;             PG8_WAIT_V(8); PG8_WAIT_L(0); PG8_BAR; PG8_MMA2B(0, At, At2, B0); PG8_BAR; PG8_SCHED;
;             PG8_LDB(B0, 1, 1); PG8_STAGE(PG8_SB(1, 0), b3, voffB); PG8_STAGE(PG8_SA(1, 0), a3, voffA); PG8_STAGE(PG8_SA(1, 1), a3 + hstepA, voffA);
;             PG8_WAIT_V(8); PG8_WAIT_L(0); PG8_BAR; PG8_MMA2B(1, At, At2, B0); PG8_BAR; PG8_SCHED;
;         }
	s_waitcnt lgkmcnt(3)
	v_mfma_f32_16x16x32_bf16 v[116:119], v[140:143], v[156:159], v[116:119]
	s_waitcnt lgkmcnt(1)
	v_mfma_f32_16x16x32_bf16 v[112:115], v[148:151], v[156:159], v[112:115]
	v_mfma_f32_16x16x32_bf16 v[100:103], v[140:143], v[178:181], v[100:103]
	v_mfma_f32_16x16x32_bf16 v[96:99], v[148:151], v[178:181], v[96:99]
	v_mfma_f32_16x16x32_bf16 v[84:87], v[140:143], v[186:189], v[84:87]
	v_mfma_f32_16x16x32_bf16 v[80:83], v[148:151], v[186:189], v[80:83]
	v_mfma_f32_16x16x32_bf16 v[68:71], v[140:143], v[194:197], v[68:71]
	v_mfma_f32_16x16x32_bf16 v[64:67], v[148:151], v[194:197], v[64:67]
	v_mfma_f32_16x16x32_bf16 v[52:55], v[140:143], v[202:205], v[52:55]
	v_mfma_f32_16x16x32_bf16 v[48:51], v[148:151], v[202:205], v[48:51]
	v_mfma_f32_16x16x32_bf16 v[36:39], v[140:143], v[218:221], v[36:39]
	v_mfma_f32_16x16x32_bf16 v[32:35], v[148:151], v[218:221], v[32:35]
	v_mfma_f32_16x16x32_bf16 v[20:23], v[140:143], v[226:229], v[20:23]
	v_mfma_f32_16x16x32_bf16 v[16:19], v[148:151], v[226:229], v[16:19]
	v_mfma_f32_16x16x32_bf16 v[4:7], v[140:143], v[234:237], v[4:7]
	v_mfma_f32_16x16x32_bf16 v[0:3], v[148:151], v[234:237], v[0:3]
	v_mfma_f32_16x16x32_bf16 v[116:119], v[144:147], v[166:169], v[116:119]
	s_waitcnt lgkmcnt(0)
	v_mfma_f32_16x16x32_bf16 v[112:115], v[152:155], v[166:169], v[112:115]
	v_mfma_f32_16x16x32_bf16 v[100:103], v[144:147], v[182:185], v[100:103]
	v_mfma_f32_16x16x32_bf16 v[96:99], v[152:155], v[182:185], v[96:99]
	v_mfma_f32_16x16x32_bf16 v[84:87], v[144:147], v[190:193], v[84:87]
	v_mfma_f32_16x16x32_bf16 v[80:83], v[152:155], v[190:193], v[80:83]
	v_mfma_f32_16x16x32_bf16 v[68:71], v[144:147], v[198:201], v[68:71]
	v_mfma_f32_16x16x32_bf16 v[64:67], v[152:155], v[198:201], v[64:67]
	v_mfma_f32_16x16x32_bf16 v[52:55], v[144:147], v[214:217], v[52:55]
	v_mfma_f32_16x16x32_bf16 v[48:51], v[152:155], v[214:217], v[48:51]
	v_mfma_f32_16x16x32_bf16 v[36:39], v[144:147], v[222:225], v[36:39]
	v_mfma_f32_16x16x32_bf16 v[32:35], v[152:155], v[222:225], v[32:35]
	v_mfma_f32_16x16x32_bf16 v[20:23], v[144:147], v[230:233], v[20:23]
	v_mfma_f32_16x16x32_bf16 v[16:19], v[152:155], v[230:233], v[16:19]
	v_mfma_f32_16x16x32_bf16 v[4:7], v[144:147], v[238:241], v[4:7]
	v_mfma_f32_16x16x32_bf16 v[0:3], v[152:155], v[238:241], v[0:3]
	s_barrier
	ds_read_b128 v[140:143], v137
	ds_read_b128 v[144:147], v137 offset:1024
	ds_read_b128 v[148:151], v137 offset:2048
	ds_read_b128 v[152:155], v137 offset:3072
	ds_read_b128 v[156:159], v135 offset:32768
	ds_read_b128 v[166:169], v135 offset:33792
	ds_read_b128 v[178:181], v135 offset:34816
	ds_read_b128 v[182:185], v135 offset:35840
	ds_read_b128 v[186:189], v135 offset:36864
	ds_read_b128 v[190:193], v135 offset:37888
	ds_read_b128 v[194:197], v135 offset:38912
	ds_read_b128 v[198:201], v135 offset:39936
	ds_read_b128 v[202:205], v135 offset:49152
	ds_read_b128 v[214:217], v135 offset:50176
	ds_read_b128 v[218:221], v135 offset:51200
	ds_read_b128 v[222:225], v135 offset:52224
	ds_read_b128 v[226:229], v135 offset:53248
	ds_read_b128 v[230:233], v135 offset:54272
	ds_read_b128 v[234:237], v135 offset:55296
	ds_read_b128 v[238:241], v135 offset:56320
	s_add_u32 s6, s90, 0x20000
	s_addc_u32 s7, s91, 0
	s_mov_b32 m0, s54
	s_nop 0
	global_load_lds_dwordx4 v129, s[6:7]
	s_mov_b32 m0, s55
	s_nop 0
	global_load_lds_dwordx4 v131, s[6:7]
	s_waitcnt vmcnt(8)
	s_waitcnt lgkmcnt(0)
	s_barrier
; #define PG8_STAGE(bufoff, gbase, voff) do { _Pragma("unroll") for (int _i = 0; _i < 2; ++_i) { \
;         const unsigned _m0 = ldsu + (unsigned)(bufoff) + ldsw + (unsigned)(_i * 8192); \
;         asm volatile("s_mov_b32 m0, %2\n\ts_nop 0\n\tglobal_load_lds_dwordx4 %0, %1" :: "v"((voff)[_i]), "s"((const char*)(gbase)), "s"(_m0) : "memory"); } } while (0)
; #define PG8_LDA(dst, b, h) do { _Pragma("unroll") for (int m = 0; m < 4; ++m) _Pragma("unroll") for (int k = 0; k < 2; ++k) dst[m][k] = *(const LAS bf16x8*)(lds + PG8_SA(b, h) + aoff + m * 2048 + k * 1024); } while (0)
; #define PG8_LDB(dst, b, h) do { _Pragma("unroll") for (int n = 0; n < 2; ++n) _Pragma("unroll") for (int k = 0; k < 2; ++k) dst[n][k] = *(const LAS bf16x8*)(lds + bbase[b][h] + n * 2048 + k * 1024); } while (0)
; #define PG8_WAIT_V(n) asm volatile("s_waitcnt vmcnt(" #n ")" ::: "memory")
; #define PG8_BAR __builtin_amdgcn_s_barrier()
; template <class Epi>
; __device__ __forceinline__ void gemm_phase(LAS unsigned char* lds, const Gemm g, const StaticOrder& S, const Epi& E) {
;     ...
;         for (int t = 0; t < nt; t += 2) {
;             const bool last = (t == nt - 2);
;             const char* a2 = last ? nA : cA + (size_t)(t + 2) * kstep; const char* b2 = last ? nB : cB + (size_t)(t + 2) * kstep;
;             const char* a3 = a2 + kstep; const char* b3 = b2 + kstep;
;             const char* b1 = cB + (size_t)(t + 1) * kstep;
;             PG8_LDB(B0, 0, 0); PG8_SCHED; PG8_LDA(At, 0, 0); PG8_LDA(At2, 0, 1); PG8_STAGE(PG8_SB(1, 1), b1 + hstepB, voffB);
;             PG8_WAIT_V(8); PG8_WAIT_L(0); PG8_BAR; PG8_MMA2B(0, At, At2, B0); PG8_BAR; PG8_SCHED;
;             PG8_LDB(B0, 0, 1); PG8_STAGE(PG8_SB(0, 0), b2, voffB); PG8_STAGE(PG8_SA(0, 0), a2, voffA); PG8_STAGE(PG8_SA(0, 1), a2 + hstepA, voffA);
;             PG8_WAIT_V(8); PG8_WAIT_L(0); PG8_BAR; PG8_MMA2B(1, At, At2, B0); PG8_BAR; PG8_SCHED;
;             PG8_LDB(B0, 1, 0); PG8_SCHED; PG8_LDA(At, 1, 0); PG8_LDA(At2, 1, 1); PG8_STAGE(PG8_SB(0, 1), b2 + hstepB, voffB);
;             PG8_WAIT_V(8); PG8_WAIT_L(0); PG8_BAR; PG8_MMA2B(0, At, At2, B0); PG8_BAR; PG8_SCHED;
;             PG8_LDB(B0, 1, 1); PG8_STAGE(PG8_SB(1, 0), b3, voffB); PG8_STAGE(PG8_SA(1, 0), a3, voffA); PG8_STAGE(PG8_SA(1, 1), a3 + hstepA, voffA);
;             PG8_WAIT_V(8); PG8_WAIT_L(0); PG8_BAR; PG8_MMA2B(1, At, At2, B0); PG8_BAR; PG8_SCHED;
;         }
	s_waitcnt lgkmcnt(14)
	v_mfma_f32_16x16x32_bf16 v[120:123], v[140:143], v[156:159], v[120:123]
	v_mfma_f32_16x16x32_bf16 v[124:127], v[148:151], v[156:159], v[124:127]
	s_waitcnt lgkmcnt(13)
	v_mfma_f32_16x16x32_bf16 v[108:111], v[140:143], v[178:181], v[108:111]
	v_mfma_f32_16x16x32_bf16 v[104:107], v[148:151], v[178:181], v[104:107]
	s_waitcnt lgkmcnt(11)
	v_mfma_f32_16x16x32_bf16 v[92:95], v[140:143], v[186:189], v[92:95]
	v_mfma_f32_16x16x32_bf16 v[88:91], v[148:151], v[186:189], v[88:91]
	s_waitcnt lgkmcnt(9)
	v_mfma_f32_16x16x32_bf16 v[76:79], v[140:143], v[194:197], v[76:79]
	v_mfma_f32_16x16x32_bf16 v[72:75], v[148:151], v[194:197], v[72:75]
	s_waitcnt lgkmcnt(7)
	v_mfma_f32_16x16x32_bf16 v[60:63], v[140:143], v[202:205], v[60:63]
	v_mfma_f32_16x16x32_bf16 v[56:59], v[148:151], v[202:205], v[56:59]
	s_waitcnt lgkmcnt(5)
	v_mfma_f32_16x16x32_bf16 v[44:47], v[140:143], v[218:221], v[44:47]
	v_mfma_f32_16x16x32_bf16 v[40:43], v[148:151], v[218:221], v[40:43]
	s_waitcnt lgkmcnt(3)
	v_mfma_f32_16x16x32_bf16 v[28:31], v[140:143], v[226:229], v[28:31]
	v_mfma_f32_16x16x32_bf16 v[24:27], v[148:151], v[226:229], v[24:27]
	s_waitcnt lgkmcnt(1)
	v_mfma_f32_16x16x32_bf16 v[12:15], v[140:143], v[234:237], v[12:15]
	v_mfma_f32_16x16x32_bf16 v[8:11], v[148:151], v[234:237], v[8:11]
	v_mfma_f32_16x16x32_bf16 v[120:123], v[144:147], v[166:169], v[120:123]
	v_mfma_f32_16x16x32_bf16 v[124:127], v[152:155], v[166:169], v[124:127]
	v_mfma_f32_16x16x32_bf16 v[108:111], v[144:147], v[182:185], v[108:111]
	v_mfma_f32_16x16x32_bf16 v[104:107], v[152:155], v[182:185], v[104:107]
	v_mfma_f32_16x16x32_bf16 v[92:95], v[144:147], v[190:193], v[92:95]
	v_mfma_f32_16x16x32_bf16 v[88:91], v[152:155], v[190:193], v[88:91]
	v_mfma_f32_16x16x32_bf16 v[76:79], v[144:147], v[198:201], v[76:79]
	v_mfma_f32_16x16x32_bf16 v[72:75], v[152:155], v[198:201], v[72:75]
	v_mfma_f32_16x16x32_bf16 v[60:63], v[144:147], v[214:217], v[60:63]
	v_mfma_f32_16x16x32_bf16 v[56:59], v[152:155], v[214:217], v[56:59]
	v_mfma_f32_16x16x32_bf16 v[44:47], v[144:147], v[222:225], v[44:47]
	v_mfma_f32_16x16x32_bf16 v[40:43], v[152:155], v[222:225], v[40:43]
	v_mfma_f32_16x16x32_bf16 v[28:31], v[144:147], v[230:233], v[28:31]
	v_mfma_f32_16x16x32_bf16 v[24:27], v[152:155], v[230:233], v[24:27]
	s_waitcnt lgkmcnt(0)
	v_mfma_f32_16x16x32_bf16 v[12:15], v[144:147], v[238:241], v[12:15]
	v_mfma_f32_16x16x32_bf16 v[8:11], v[152:155], v[238:241], v[8:11]
	s_barrier
	ds_read_b128 v[140:143], v138
	ds_read_b128 v[144:147], v138 offset:1024
	ds_read_b128 v[148:151], v138 offset:2048
	ds_read_b128 v[152:155], v138 offset:3072
	s_mov_b32 m0, s56
	s_nop 0
	global_load_lds_dwordx4 v129, s[84:85]
	s_mov_b32 m0, s57
	s_nop 0
	global_load_lds_dwordx4 v131, s[84:85]
	s_mov_b32 m0, s58
	s_nop 0
	global_load_lds_dwordx4 v128, s[82:83]
	s_mov_b32 m0, s59
	s_nop 0
	global_load_lds_dwordx4 v130, s[82:83]
	s_add_u32 s6, s80, 0x20080
	s_addc_u32 s7, s81, 0
	s_mov_b32 m0, s60
	s_nop 0
	global_load_lds_dwordx4 v128, s[6:7]
	s_mov_b32 m0, s61
	s_nop 0
	global_load_lds_dwordx4 v130, s[6:7]
	s_waitcnt vmcnt(8)
	s_waitcnt lgkmcnt(0)
	s_barrier
	s_waitcnt lgkmcnt(3)
	v_mfma_f32_16x16x32_bf16 v[116:119], v[140:143], v[156:159], v[116:119]
	s_waitcnt lgkmcnt(1)
	v_mfma_f32_16x16x32_bf16 v[112:115], v[148:151], v[156:159], v[112:115]
	v_mfma_f32_16x16x32_bf16 v[100:103], v[140:143], v[178:181], v[100:103]
	v_mfma_f32_16x16x32_bf16 v[96:99], v[148:151], v[178:181], v[96:99]
	v_mfma_f32_16x16x32_bf16 v[84:87], v[140:143], v[186:189], v[84:87]
	v_mfma_f32_16x16x32_bf16 v[80:83], v[148:151], v[186:189], v[80:83]
	v_mfma_f32_16x16x32_bf16 v[68:71], v[140:143], v[194:197], v[68:71]
	v_mfma_f32_16x16x32_bf16 v[64:67], v[148:151], v[194:197], v[64:67]
	v_mfma_f32_16x16x32_bf16 v[52:55], v[140:143], v[202:205], v[52:55]
	v_mfma_f32_16x16x32_bf16 v[48:51], v[148:151], v[202:205], v[48:51]
	v_mfma_f32_16x16x32_bf16 v[36:39], v[140:143], v[218:221], v[36:39]
	v_mfma_f32_16x16x32_bf16 v[32:35], v[148:151], v[218:221], v[32:35]
	v_mfma_f32_16x16x32_bf16 v[20:23], v[140:143], v[226:229], v[20:23]
	v_mfma_f32_16x16x32_bf16 v[16:19], v[148:151], v[226:229], v[16:19]
	v_mfma_f32_16x16x32_bf16 v[4:7], v[140:143], v[234:237], v[4:7]
	v_mfma_f32_16x16x32_bf16 v[0:3], v[148:151], v[234:237], v[0:3]
	v_mfma_f32_16x16x32_bf16 v[116:119], v[144:147], v[166:169], v[116:119]
	s_waitcnt lgkmcnt(0)
	v_mfma_f32_16x16x32_bf16 v[112:115], v[152:155], v[166:169], v[112:115]
	v_mfma_f32_16x16x32_bf16 v[100:103], v[144:147], v[182:185], v[100:103]
	v_mfma_f32_16x16x32_bf16 v[96:99], v[152:155], v[182:185], v[96:99]
	v_mfma_f32_16x16x32_bf16 v[84:87], v[144:147], v[190:193], v[84:87]
	v_mfma_f32_16x16x32_bf16 v[80:83], v[152:155], v[190:193], v[80:83]
	v_mfma_f32_16x16x32_bf16 v[68:71], v[144:147], v[198:201], v[68:71]
	v_mfma_f32_16x16x32_bf16 v[64:67], v[152:155], v[198:201], v[64:67]
	v_mfma_f32_16x16x32_bf16 v[52:55], v[144:147], v[214:217], v[52:55]
	v_mfma_f32_16x16x32_bf16 v[48:51], v[152:155], v[214:217], v[48:51]
	v_mfma_f32_16x16x32_bf16 v[36:39], v[144:147], v[222:225], v[36:39]
	v_mfma_f32_16x16x32_bf16 v[32:35], v[152:155], v[222:225], v[32:35]
	v_mfma_f32_16x16x32_bf16 v[20:23], v[144:147], v[230:233], v[20:23]
	v_mfma_f32_16x16x32_bf16 v[16:19], v[152:155], v[230:233], v[16:19]
	v_mfma_f32_16x16x32_bf16 v[4:7], v[144:147], v[238:241], v[4:7]
	v_mfma_f32_16x16x32_bf16 v[0:3], v[152:155], v[238:241], v[0:3]
	s_barrier
	s_add_u32 s88, s88, 0x100
	s_addc_u32 s89, s89, 0
	s_add_u32 s95, s95, 0x100
	s_addc_u32 s96, s96, 0
	s_cmp_ge_i32 s69, s28
	s_mov_b32 s68, s69
	s_cbranch_scc0 .LBB0_487
	v_readlane_b32 s96, v252, 29
	v_readlane_b32 s97, v252, 30
	v_readlane_b32 s89, v255, 4
	v_readlane_b32 s95, v255, 2

; #define PG8_STAGE(bufoff, gbase, voff) do { _Pragma("unroll") for (int _i = 0; _i < 2; ++_i) { \
;         const unsigned _m0 = ldsu + (unsigned)(bufoff) + ldsw + (unsigned)(_i * 8192); \
;         asm volatile("s_mov_b32 m0, %2\n\ts_nop 0\n\tglobal_load_lds_dwordx4 %0, %1" :: "v"((voff)[_i]), "s"((const char*)(gbase)), "s"(_m0) : "memory"); } } while (0)
; #define PG8_LDA(dst, b, h) do { _Pragma("unroll") for (int m = 0; m < 4; ++m) _Pragma("unroll") for (int k = 0; k < 2; ++k) dst[m][k] = *(const LAS bf16x8*)(lds + PG8_SA(b, h) + aoff + m * 2048 + k * 1024); } while (0)
; #define PG8_LDB(dst, b, h) do { _Pragma("unroll") for (int n = 0; n < 2; ++n) _Pragma("unroll") for (int k = 0; k < 2; ++k) dst[n][k] = *(const LAS bf16x8*)(lds + bbase[b][h] + n * 2048 + k * 1024); } while (0)
; #define PG8_WAIT_V(n) asm volatile("s_waitcnt vmcnt(" #n ")" ::: "memory")
; #define PG8_BAR __builtin_amdgcn_s_barrier()
; template <class Epi>
; __device__ __forceinline__ void gemm_phase(LAS unsigned char* lds, const Gemm g, const StaticOrder& S, const Epi& E) {
;     ...
;         for (int t = 0; t < nt; t += 2) {
;             const bool last = (t == nt - 2);
;             const char* a2 = last ? nA : cA + (size_t)(t + 2) * kstep; const char* b2 = last ? nB : cB + (size_t)(t + 2) * kstep;
;             const char* a3 = a2 + kstep; const char* b3 = b2 + kstep;
;             const char* b1 = cB + (size_t)(t + 1) * kstep;
;             PG8_LDB(B0, 0, 0); PG8_SCHED; PG8_LDA(At, 0, 0); PG8_LDA(At2, 0, 1); PG8_STAGE(PG8_SB(1, 1), b1 + hstepB, voffB);
;             PG8_WAIT_V(8); PG8_WAIT_L(0); PG8_BAR; PG8_MMA2B(0, At, At2, B0); PG8_BAR; PG8_SCHED;
;             PG8_LDB(B0, 0, 1); PG8_STAGE(PG8_SB(0, 0), b2, voffB); PG8_STAGE(PG8_SA(0, 0), a2, voffA); PG8_STAGE(PG8_SA(0, 1), a2 + hstepA, voffA);
;             PG8_WAIT_V(8); PG8_WAIT_L(0); PG8_BAR; PG8_MMA2B(1, At, At2, B0); PG8_BAR; PG8_SCHED;
;             PG8_LDB(B0, 1, 0); PG8_SCHED; PG8_LDA(At, 1, 0); PG8_LDA(At2, 1, 1); PG8_STAGE(PG8_SB(0, 1), b2 + hstepB, voffB);
;             PG8_WAIT_V(8); PG8_WAIT_L(0); PG8_BAR; PG8_MMA2B(0, At, At2, B0); PG8_BAR; PG8_SCHED;
;             PG8_LDB(B0, 1, 1); PG8_STAGE(PG8_SB(1, 0), b3, voffB); PG8_STAGE(PG8_SA(1, 0), a3, voffA); PG8_STAGE(PG8_SA(1, 1), a3 + hstepA, voffA);
;             PG8_WAIT_V(8); PG8_WAIT_L(0); PG8_BAR; PG8_MMA2B(1, At, At2, B0); PG8_BAR; PG8_SCHED;
;         }
.LBB0_509:
	s_add_i32 s63, s4, 2
	s_add_u32 s38, s59, 0x80
	ds_read_b128 v[128:131], v144
	ds_read_b128 v[132:135], v144 offset:1024
	ds_read_b128 v[150:153], v144 offset:2048
	ds_read_b128 v[154:157], v144 offset:3072
	s_addc_u32 s39, s60, 0
	s_cmp_eq_u32 s51, s4
	s_cselect_b32 s4, s15, s61
	s_cselect_b32 s5, s13, s62
	s_cselect_b32 s82, s58, s38
	s_cselect_b32 s83, s57, s39
	s_add_u32 s38, s4, 0x80
	s_addc_u32 s39, s5, 0
	s_add_u32 s80, s82, 0x80
	s_addc_u32 s81, s83, 0
	ds_read_b128 v[166:169], v145
	ds_read_b128 v[178:181], v145 offset:1024
	ds_read_b128 v[182:185], v145 offset:2048
	ds_read_b128 v[186:189], v145 offset:3072
	ds_read_b128 v[190:193], v145 offset:4096
	ds_read_b128 v[194:197], v145 offset:5120
	ds_read_b128 v[198:201], v145 offset:6144
	ds_read_b128 v[202:205], v145 offset:7168
	ds_read_b128 v[214:217], v145 offset:16384
	ds_read_b128 v[218:221], v145 offset:17408
	ds_read_b128 v[222:225], v145 offset:18432
	ds_read_b128 v[226:229], v145 offset:19456
	ds_read_b128 v[230:233], v145 offset:20480
	ds_read_b128 v[234:237], v145 offset:21504
	ds_read_b128 v[238:241], v145 offset:22528
	ds_read_b128 v[242:245], v145 offset:23552
	s_add_u32 s64, s59, 0x20000
	s_addc_u32 s65, s60, 0
	s_mov_b32 m0, s52
	s_nop 0
	global_load_lds_dwordx4 v141, s[64:65]
	s_mov_b32 m0, s53
	s_nop 0
	global_load_lds_dwordx4 v143, s[64:65]
	s_waitcnt vmcnt(8)
	s_waitcnt lgkmcnt(0)
	s_barrier
	s_waitcnt lgkmcnt(14)
	v_mfma_f32_16x16x32_bf16 v[120:123], v[128:131], v[166:169], v[120:123]
	v_mfma_f32_16x16x32_bf16 v[124:127], v[150:153], v[166:169], v[124:127]
	s_waitcnt lgkmcnt(13)
	v_mfma_f32_16x16x32_bf16 v[108:111], v[128:131], v[182:185], v[108:111]
	v_mfma_f32_16x16x32_bf16 v[104:107], v[150:153], v[182:185], v[104:107]
	s_waitcnt lgkmcnt(11)
	v_mfma_f32_16x16x32_bf16 v[92:95], v[128:131], v[190:193], v[92:95]
	v_mfma_f32_16x16x32_bf16 v[88:91], v[150:153], v[190:193], v[88:91]
	s_waitcnt lgkmcnt(9)
	v_mfma_f32_16x16x32_bf16 v[76:79], v[128:131], v[198:201], v[76:79]
	v_mfma_f32_16x16x32_bf16 v[72:75], v[150:153], v[198:201], v[72:75]
	s_waitcnt lgkmcnt(7)
	v_mfma_f32_16x16x32_bf16 v[60:63], v[128:131], v[214:217], v[60:63]
	v_mfma_f32_16x16x32_bf16 v[56:59], v[150:153], v[214:217], v[56:59]
	s_waitcnt lgkmcnt(5)
	v_mfma_f32_16x16x32_bf16 v[44:47], v[128:131], v[222:225], v[44:47]
	v_mfma_f32_16x16x32_bf16 v[40:43], v[150:153], v[222:225], v[40:43]
	s_waitcnt lgkmcnt(3)
	v_mfma_f32_16x16x32_bf16 v[28:31], v[128:131], v[230:233], v[28:31]
	v_mfma_f32_16x16x32_bf16 v[24:27], v[150:153], v[230:233], v[24:27]
	s_waitcnt lgkmcnt(1)
	v_mfma_f32_16x16x32_bf16 v[12:15], v[128:131], v[238:241], v[12:15]
	v_mfma_f32_16x16x32_bf16 v[8:11], v[150:153], v[238:241], v[8:11]
	v_mfma_f32_16x16x32_bf16 v[120:123], v[132:135], v[178:181], v[120:123]
	v_mfma_f32_16x16x32_bf16 v[124:127], v[154:157], v[178:181], v[124:127]
	v_mfma_f32_16x16x32_bf16 v[108:111], v[132:135], v[186:189], v[108:111]
	v_mfma_f32_16x16x32_bf16 v[104:107], v[154:157], v[186:189], v[104:107]
	v_mfma_f32_16x16x32_bf16 v[92:95], v[132:135], v[194:197], v[92:95]
	v_mfma_f32_16x16x32_bf16 v[88:91], v[154:157], v[194:197], v[88:91]
	v_mfma_f32_16x16x32_bf16 v[76:79], v[132:135], v[202:205], v[76:79]
	v_mfma_f32_16x16x32_bf16 v[72:75], v[154:157], v[202:205], v[72:75]
	v_mfma_f32_16x16x32_bf16 v[60:63], v[132:135], v[218:221], v[60:63]
	v_mfma_f32_16x16x32_bf16 v[56:59], v[154:157], v[218:221], v[56:59]
	v_mfma_f32_16x16x32_bf16 v[44:47], v[132:135], v[226:229], v[44:47]
	v_mfma_f32_16x16x32_bf16 v[40:43], v[154:157], v[226:229], v[40:43]
	v_mfma_f32_16x16x32_bf16 v[28:31], v[132:135], v[234:237], v[28:31]
	v_mfma_f32_16x16x32_bf16 v[24:27], v[154:157], v[234:237], v[24:27]
	s_waitcnt lgkmcnt(0)
	v_mfma_f32_16x16x32_bf16 v[12:15], v[132:135], v[242:245], v[12:15]
	v_mfma_f32_16x16x32_bf16 v[8:11], v[154:157], v[242:245], v[8:11]
	s_barrier
	ds_read_b128 v[128:131], v146
	ds_read_b128 v[132:135], v146 offset:1024
	ds_read_b128 v[150:153], v146 offset:2048
	ds_read_b128 v[154:157], v146 offset:3072
	s_mov_b32 m0, s85
	s_nop 0
	global_load_lds_dwordx4 v141, s[82:83]
	s_mov_b32 m0, s86
	s_nop 0
	global_load_lds_dwordx4 v143, s[82:83]
	s_mov_b32 m0, s84
	s_nop 0
	global_load_lds_dwordx4 v140, s[4:5]
	s_mov_b32 m0, s87
	s_nop 0
	global_load_lds_dwordx4 v142, s[4:5]
	s_add_u32 s64, s4, 0x20000
	s_addc_u32 s65, s5, 0
	s_mov_b32 m0, s88
	s_nop 0
	global_load_lds_dwordx4 v140, s[64:65]
	s_mov_b32 m0, s89
	s_nop 0
	global_load_lds_dwordx4 v142, s[64:65]
	s_waitcnt vmcnt(8)
	s_waitcnt lgkmcnt(0)
	s_barrier
; #define PG8_STAGE(bufoff, gbase, voff) do { _Pragma("unroll") for (int _i = 0; _i < 2; ++_i) { \
;         const unsigned _m0 = ldsu + (unsigned)(bufoff) + ldsw + (unsigned)(_i * 8192); \
;         asm volatile("s_mov_b32 m0, %2\n\ts_nop 0\n\tglobal_load_lds_dwordx4 %0, %1" :: "v"((voff)[_i]), "s"((const char*)(gbase)), "s"(_m0) : "memory"); } } while (0)
; #define PG8_LDA(dst, b, h) do { _Pragma("unroll") for (int m = 0; m < 4; ++m) _Pragma("unroll") for (int k = 0; k < 2; ++k) dst[m][k] = *(const LAS bf16x8*)(lds + PG8_SA(b, h) + aoff + m * 2048 + k * 1024); } while (0)
; #define PG8_LDB(dst, b, h) do { _Pragma("unroll") for (int n = 0; n < 2; ++n) _Pragma("unroll") for (int k = 0; k < 2; ++k) dst[n][k] = *(const LAS bf16x8*)(lds + bbase[b][h] + n * 2048 + k * 1024); } while (0)
; #define PG8_WAIT_V(n) asm volatile("s_waitcnt vmcnt(" #n ")" ::: "memory")
; #define PG8_BAR __builtin_amdgcn_s_barrier()
; template <class Epi>
; __device__ __forceinline__ void gemm_phase(LAS unsigned char* lds, const Gemm g, const StaticOrder& S, const Epi& E) {
;     ...
;         for (int t = 0; t < nt; t += 2) {
;             const bool last = (t == nt - 2);
;             const char* a2 = last ? nA : cA + (size_t)(t + 2) * kstep; const char* b2 = last ? nB : cB + (size_t)(t + 2) * kstep;
;             const char* a3 = a2 + kstep; const char* b3 = b2 + kstep;
;             const char* b1 = cB + (size_t)(t + 1) * kstep;
;             PG8_LDB(B0, 0, 0); PG8_SCHED; PG8_LDA(At, 0, 0); PG8_LDA(At2, 0, 1); PG8_STAGE(PG8_SB(1, 1), b1 + hstepB, voffB);
;             PG8_WAIT_V(8); PG8_WAIT_L(0); PG8_BAR; PG8_MMA2B(0, At, At2, B0); PG8_BAR; PG8_SCHED;
;             PG8_LDB(B0, 0, 1); PG8_STAGE(PG8_SB(0, 0), b2, voffB); PG8_STAGE(PG8_SA(0, 0), a2, voffA); PG8_STAGE(PG8_SA(0, 1), a2 + hstepA, voffA);
;             PG8_WAIT_V(8); PG8_WAIT_L(0); PG8_BAR; PG8_MMA2B(1, At, At2, B0); PG8_BAR; PG8_SCHED;
;             PG8_LDB(B0, 1, 0); PG8_SCHED; PG8_LDA(At, 1, 0); PG8_LDA(At2, 1, 1); PG8_STAGE(PG8_SB(0, 1), b2 + hstepB, voffB);
;             PG8_WAIT_V(8); PG8_WAIT_L(0); PG8_BAR; PG8_MMA2B(0, At, At2, B0); PG8_BAR; PG8_SCHED;
;             PG8_LDB(B0, 1, 1); PG8_STAGE(PG8_SB(1, 0), b3, voffB); PG8_STAGE(PG8_SA(1, 0), a3, voffA); PG8_STAGE(PG8_SA(1, 1), a3 + hstepA, voffA);
;             PG8_WAIT_V(8); PG8_WAIT_L(0); PG8_BAR; PG8_MMA2B(1, At, At2, B0); PG8_BAR; PG8_SCHED;
;         }
	s_waitcnt lgkmcnt(3)
	v_mfma_f32_16x16x32_bf16 v[116:119], v[128:131], v[166:169], v[116:119]
	s_waitcnt lgkmcnt(1)
	v_mfma_f32_16x16x32_bf16 v[112:115], v[150:153], v[166:169], v[112:115]
	v_mfma_f32_16x16x32_bf16 v[100:103], v[128:131], v[182:185], v[100:103]
	v_mfma_f32_16x16x32_bf16 v[96:99], v[150:153], v[182:185], v[96:99]
	v_mfma_f32_16x16x32_bf16 v[84:87], v[128:131], v[190:193], v[84:87]
	v_mfma_f32_16x16x32_bf16 v[80:83], v[150:153], v[190:193], v[80:83]
	v_mfma_f32_16x16x32_bf16 v[68:71], v[128:131], v[198:201], v[68:71]
	v_mfma_f32_16x16x32_bf16 v[64:67], v[150:153], v[198:201], v[64:67]
	v_mfma_f32_16x16x32_bf16 v[52:55], v[128:131], v[214:217], v[52:55]
	v_mfma_f32_16x16x32_bf16 v[48:51], v[150:153], v[214:217], v[48:51]
	v_mfma_f32_16x16x32_bf16 v[36:39], v[128:131], v[222:225], v[36:39]
	v_mfma_f32_16x16x32_bf16 v[32:35], v[150:153], v[222:225], v[32:35]
	v_mfma_f32_16x16x32_bf16 v[20:23], v[128:131], v[230:233], v[20:23]
	v_mfma_f32_16x16x32_bf16 v[16:19], v[150:153], v[230:233], v[16:19]
	v_mfma_f32_16x16x32_bf16 v[4:7], v[128:131], v[238:241], v[4:7]
	v_mfma_f32_16x16x32_bf16 v[0:3], v[150:153], v[238:241], v[0:3]
	v_mfma_f32_16x16x32_bf16 v[116:119], v[132:135], v[178:181], v[116:119]
	s_waitcnt lgkmcnt(0)
	v_mfma_f32_16x16x32_bf16 v[112:115], v[154:157], v[178:181], v[112:115]
	v_mfma_f32_16x16x32_bf16 v[100:103], v[132:135], v[186:189], v[100:103]
	v_mfma_f32_16x16x32_bf16 v[96:99], v[154:157], v[186:189], v[96:99]
	v_mfma_f32_16x16x32_bf16 v[84:87], v[132:135], v[194:197], v[84:87]
	v_mfma_f32_16x16x32_bf16 v[80:83], v[154:157], v[194:197], v[80:83]
	v_mfma_f32_16x16x32_bf16 v[68:71], v[132:135], v[202:205], v[68:71]
	v_mfma_f32_16x16x32_bf16 v[64:67], v[154:157], v[202:205], v[64:67]
	v_mfma_f32_16x16x32_bf16 v[52:55], v[132:135], v[218:221], v[52:55]
	v_mfma_f32_16x16x32_bf16 v[48:51], v[154:157], v[218:221], v[48:51]
	v_mfma_f32_16x16x32_bf16 v[36:39], v[132:135], v[226:229], v[36:39]
	v_mfma_f32_16x16x32_bf16 v[32:35], v[154:157], v[226:229], v[32:35]
	v_mfma_f32_16x16x32_bf16 v[20:23], v[132:135], v[234:237], v[20:23]
	v_mfma_f32_16x16x32_bf16 v[16:19], v[154:157], v[234:237], v[16:19]
	v_mfma_f32_16x16x32_bf16 v[4:7], v[132:135], v[242:245], v[4:7]
	v_mfma_f32_16x16x32_bf16 v[0:3], v[154:157], v[242:245], v[0:3]
	s_barrier
	ds_read_b128 v[128:131], v147
	ds_read_b128 v[132:135], v147 offset:1024
	ds_read_b128 v[150:153], v147 offset:2048
	ds_read_b128 v[154:157], v147 offset:3072
	ds_read_b128 v[166:169], v145 offset:32768
	ds_read_b128 v[178:181], v145 offset:33792
	ds_read_b128 v[182:185], v145 offset:34816
	ds_read_b128 v[186:189], v145 offset:35840
	ds_read_b128 v[190:193], v145 offset:36864
	ds_read_b128 v[194:197], v145 offset:37888
	ds_read_b128 v[198:201], v145 offset:38912
	ds_read_b128 v[202:205], v145 offset:39936
	ds_read_b128 v[214:217], v145 offset:49152
	ds_read_b128 v[218:221], v145 offset:50176
	ds_read_b128 v[222:225], v145 offset:51200
	ds_read_b128 v[226:229], v145 offset:52224
	ds_read_b128 v[230:233], v145 offset:53248
	ds_read_b128 v[234:237], v145 offset:54272
	ds_read_b128 v[238:241], v145 offset:55296
	ds_read_b128 v[242:245], v145 offset:56320
	s_add_u32 s64, s82, 0x20000
	s_addc_u32 s65, s83, 0
	s_mov_b32 m0, s90
	s_nop 0
	global_load_lds_dwordx4 v141, s[64:65]
	s_mov_b32 m0, s91
	s_nop 0
	global_load_lds_dwordx4 v143, s[64:65]
	s_waitcnt vmcnt(8)
	s_waitcnt lgkmcnt(0)
	s_barrier
; #define PG8_STAGE(bufoff, gbase, voff) do { _Pragma("unroll") for (int _i = 0; _i < 2; ++_i) { \
;         const unsigned _m0 = ldsu + (unsigned)(bufoff) + ldsw + (unsigned)(_i * 8192); \
;         asm volatile("s_mov_b32 m0, %2\n\ts_nop 0\n\tglobal_load_lds_dwordx4 %0, %1" :: "v"((voff)[_i]), "s"((const char*)(gbase)), "s"(_m0) : "memory"); } } while (0)
; #define PG8_LDA(dst, b, h) do { _Pragma("unroll") for (int m = 0; m < 4; ++m) _Pragma("unroll") for (int k = 0; k < 2; ++k) dst[m][k] = *(const LAS bf16x8*)(lds + PG8_SA(b, h) + aoff + m * 2048 + k * 1024); } while (0)
; #define PG8_LDB(dst, b, h) do { _Pragma("unroll") for (int n = 0; n < 2; ++n) _Pragma("unroll") for (int k = 0; k < 2; ++k) dst[n][k] = *(const LAS bf16x8*)(lds + bbase[b][h] + n * 2048 + k * 1024); } while (0)
; #define PG8_WAIT_V(n) asm volatile("s_waitcnt vmcnt(" #n ")" ::: "memory")
; #define PG8_BAR __builtin_amdgcn_s_barrier()
; template <class Epi>
; __device__ __forceinline__ void gemm_phase(LAS unsigned char* lds, const Gemm g, const StaticOrder& S, const Epi& E) {
;     ...
;         for (int t = 0; t < nt; t += 2) {
;             const bool last = (t == nt - 2);
;             const char* a2 = last ? nA : cA + (size_t)(t + 2) * kstep; const char* b2 = last ? nB : cB + (size_t)(t + 2) * kstep;
;             const char* a3 = a2 + kstep; const char* b3 = b2 + kstep;
;             const char* b1 = cB + (size_t)(t + 1) * kstep;
;             PG8_LDB(B0, 0, 0); PG8_SCHED; PG8_LDA(At, 0, 0); PG8_LDA(At2, 0, 1); PG8_STAGE(PG8_SB(1, 1), b1 + hstepB, voffB);
;             PG8_WAIT_V(8); PG8_WAIT_L(0); PG8_BAR; PG8_MMA2B(0, At, At2, B0); PG8_BAR; PG8_SCHED;
;             PG8_LDB(B0, 0, 1); PG8_STAGE(PG8_SB(0, 0), b2, voffB); PG8_STAGE(PG8_SA(0, 0), a2, voffA); PG8_STAGE(PG8_SA(0, 1), a2 + hstepA, voffA);
;             PG8_WAIT_V(8); PG8_WAIT_L(0); PG8_BAR; PG8_MMA2B(1, At, At2, B0); PG8_BAR; PG8_SCHED;
;             PG8_LDB(B0, 1, 0); PG8_SCHED; PG8_LDA(At, 1, 0); PG8_LDA(At2, 1, 1); PG8_STAGE(PG8_SB(0, 1), b2 + hstepB, voffB);
;             PG8_WAIT_V(8); PG8_WAIT_L(0); PG8_BAR; PG8_MMA2B(0, At, At2, B0); PG8_BAR; PG8_SCHED;
;             PG8_LDB(B0, 1, 1); PG8_STAGE(PG8_SB(1, 0), b3, voffB); PG8_STAGE(PG8_SA(1, 0), a3, voffA); PG8_STAGE(PG8_SA(1, 1), a3 + hstepA, voffA);
;             PG8_WAIT_V(8); PG8_WAIT_L(0); PG8_BAR; PG8_MMA2B(1, At, At2, B0); PG8_BAR; PG8_SCHED;
;         }
	s_waitcnt lgkmcnt(14)
	v_mfma_f32_16x16x32_bf16 v[120:123], v[128:131], v[166:169], v[120:123]
	v_mfma_f32_16x16x32_bf16 v[124:127], v[150:153], v[166:169], v[124:127]
	s_waitcnt lgkmcnt(13)
	v_mfma_f32_16x16x32_bf16 v[108:111], v[128:131], v[182:185], v[108:111]
	v_mfma_f32_16x16x32_bf16 v[104:107], v[150:153], v[182:185], v[104:107]
	s_waitcnt lgkmcnt(11)
	v_mfma_f32_16x16x32_bf16 v[92:95], v[128:131], v[190:193], v[92:95]
	v_mfma_f32_16x16x32_bf16 v[88:91], v[150:153], v[190:193], v[88:91]
	s_waitcnt lgkmcnt(9)
	v_mfma_f32_16x16x32_bf16 v[76:79], v[128:131], v[198:201], v[76:79]
	v_mfma_f32_16x16x32_bf16 v[72:75], v[150:153], v[198:201], v[72:75]
	s_waitcnt lgkmcnt(7)
	v_mfma_f32_16x16x32_bf16 v[60:63], v[128:131], v[214:217], v[60:63]
	v_mfma_f32_16x16x32_bf16 v[56:59], v[150:153], v[214:217], v[56:59]
	s_waitcnt lgkmcnt(5)
	v_mfma_f32_16x16x32_bf16 v[44:47], v[128:131], v[222:225], v[44:47]
	v_mfma_f32_16x16x32_bf16 v[40:43], v[150:153], v[222:225], v[40:43]
	s_waitcnt lgkmcnt(3)
	v_mfma_f32_16x16x32_bf16 v[28:31], v[128:131], v[230:233], v[28:31]
	v_mfma_f32_16x16x32_bf16 v[24:27], v[150:153], v[230:233], v[24:27]
	s_waitcnt lgkmcnt(1)
	v_mfma_f32_16x16x32_bf16 v[12:15], v[128:131], v[238:241], v[12:15]
	v_mfma_f32_16x16x32_bf16 v[8:11], v[150:153], v[238:241], v[8:11]
	v_mfma_f32_16x16x32_bf16 v[120:123], v[132:135], v[178:181], v[120:123]
	v_mfma_f32_16x16x32_bf16 v[124:127], v[154:157], v[178:181], v[124:127]
	v_mfma_f32_16x16x32_bf16 v[108:111], v[132:135], v[186:189], v[108:111]
	v_mfma_f32_16x16x32_bf16 v[104:107], v[154:157], v[186:189], v[104:107]
	v_mfma_f32_16x16x32_bf16 v[92:95], v[132:135], v[194:197], v[92:95]
	v_mfma_f32_16x16x32_bf16 v[88:91], v[154:157], v[194:197], v[88:91]
	v_mfma_f32_16x16x32_bf16 v[76:79], v[132:135], v[202:205], v[76:79]
	v_mfma_f32_16x16x32_bf16 v[72:75], v[154:157], v[202:205], v[72:75]
	v_mfma_f32_16x16x32_bf16 v[60:63], v[132:135], v[218:221], v[60:63]
	v_mfma_f32_16x16x32_bf16 v[56:59], v[154:157], v[218:221], v[56:59]
	v_mfma_f32_16x16x32_bf16 v[44:47], v[132:135], v[226:229], v[44:47]
	v_mfma_f32_16x16x32_bf16 v[40:43], v[154:157], v[226:229], v[40:43]
	v_mfma_f32_16x16x32_bf16 v[28:31], v[132:135], v[234:237], v[28:31]
	v_mfma_f32_16x16x32_bf16 v[24:27], v[154:157], v[234:237], v[24:27]
	s_waitcnt lgkmcnt(0)
	v_mfma_f32_16x16x32_bf16 v[12:15], v[132:135], v[242:245], v[12:15]
	v_mfma_f32_16x16x32_bf16 v[8:11], v[154:157], v[242:245], v[8:11]
	s_barrier
	ds_read_b128 v[128:131], v148
	ds_read_b128 v[132:135], v148 offset:1024
	ds_read_b128 v[150:153], v148 offset:2048
	ds_read_b128 v[154:157], v148 offset:3072
	s_mov_b32 m0, s97
	s_nop 0
	global_load_lds_dwordx4 v141, s[80:81]
	s_mov_b32 m0, s37
	s_nop 0
	global_load_lds_dwordx4 v143, s[80:81]
	s_mov_b32 m0, s95
	s_nop 0
	global_load_lds_dwordx4 v140, s[38:39]
	s_mov_b32 m0, s48
	s_nop 0
	global_load_lds_dwordx4 v142, s[38:39]
	s_add_u32 s4, s4, 0x20080
	s_addc_u32 s5, s5, 0
	s_mov_b32 m0, s49
	s_nop 0
	global_load_lds_dwordx4 v140, s[4:5]
	s_mov_b32 m0, s50
	s_nop 0
	global_load_lds_dwordx4 v142, s[4:5]
	s_waitcnt vmcnt(8)
	s_waitcnt lgkmcnt(0)
	s_barrier
	s_waitcnt lgkmcnt(3)
	v_mfma_f32_16x16x32_bf16 v[116:119], v[128:131], v[166:169], v[116:119]
	s_waitcnt lgkmcnt(1)
	v_mfma_f32_16x16x32_bf16 v[112:115], v[150:153], v[166:169], v[112:115]
	v_mfma_f32_16x16x32_bf16 v[100:103], v[128:131], v[182:185], v[100:103]
	v_mfma_f32_16x16x32_bf16 v[96:99], v[150:153], v[182:185], v[96:99]
	v_mfma_f32_16x16x32_bf16 v[84:87], v[128:131], v[190:193], v[84:87]
	v_mfma_f32_16x16x32_bf16 v[80:83], v[150:153], v[190:193], v[80:83]
	v_mfma_f32_16x16x32_bf16 v[68:71], v[128:131], v[198:201], v[68:71]
	v_mfma_f32_16x16x32_bf16 v[64:67], v[150:153], v[198:201], v[64:67]
	v_mfma_f32_16x16x32_bf16 v[52:55], v[128:131], v[214:217], v[52:55]
	v_mfma_f32_16x16x32_bf16 v[48:51], v[150:153], v[214:217], v[48:51]
	v_mfma_f32_16x16x32_bf16 v[36:39], v[128:131], v[222:225], v[36:39]
	v_mfma_f32_16x16x32_bf16 v[32:35], v[150:153], v[222:225], v[32:35]
	v_mfma_f32_16x16x32_bf16 v[20:23], v[128:131], v[230:233], v[20:23]
	v_mfma_f32_16x16x32_bf16 v[16:19], v[150:153], v[230:233], v[16:19]
	v_mfma_f32_16x16x32_bf16 v[4:7], v[128:131], v[238:241], v[4:7]
	v_mfma_f32_16x16x32_bf16 v[0:3], v[150:153], v[238:241], v[0:3]
	v_mfma_f32_16x16x32_bf16 v[116:119], v[132:135], v[178:181], v[116:119]
	s_waitcnt lgkmcnt(0)
	v_mfma_f32_16x16x32_bf16 v[112:115], v[154:157], v[178:181], v[112:115]
	v_mfma_f32_16x16x32_bf16 v[100:103], v[132:135], v[186:189], v[100:103]
	v_mfma_f32_16x16x32_bf16 v[96:99], v[154:157], v[186:189], v[96:99]
	v_mfma_f32_16x16x32_bf16 v[84:87], v[132:135], v[194:197], v[84:87]
	v_mfma_f32_16x16x32_bf16 v[80:83], v[154:157], v[194:197], v[80:83]
	v_mfma_f32_16x16x32_bf16 v[68:71], v[132:135], v[202:205], v[68:71]
	v_mfma_f32_16x16x32_bf16 v[64:67], v[154:157], v[202:205], v[64:67]
	v_mfma_f32_16x16x32_bf16 v[52:55], v[132:135], v[218:221], v[52:55]
	v_mfma_f32_16x16x32_bf16 v[48:51], v[154:157], v[218:221], v[48:51]
	v_mfma_f32_16x16x32_bf16 v[36:39], v[132:135], v[226:229], v[36:39]
	v_mfma_f32_16x16x32_bf16 v[32:35], v[154:157], v[226:229], v[32:35]
	v_mfma_f32_16x16x32_bf16 v[20:23], v[132:135], v[234:237], v[20:23]
	v_mfma_f32_16x16x32_bf16 v[16:19], v[154:157], v[234:237], v[16:19]
	v_mfma_f32_16x16x32_bf16 v[4:7], v[132:135], v[242:245], v[4:7]
	v_mfma_f32_16x16x32_bf16 v[0:3], v[154:157], v[242:245], v[0:3]
	s_barrier
	s_add_u32 s59, s59, 0x100
	s_addc_u32 s60, s60, 0
	s_add_u32 s61, s61, 0x100
	s_addc_u32 s62, s62, 0
	s_cmp_ge_i32 s63, s28
	s_mov_b32 s4, s63
	s_cbranch_scc0 .LBB0_509
	v_readlane_b32 s60, v252, 25
	v_readlane_b32 s62, v252, 27
	v_readlane_b32 s64, v252, 9
	v_readlane_b32 s61, v252, 26
	v_readlane_b32 s63, v252, 28
	v_readlane_b32 s65, v252, 10

; #define PG8_STAGE(bufoff, gbase, voff) do { _Pragma("unroll") for (int _i = 0; _i < 2; ++_i) { \
;         const unsigned _m0 = ldsu + (unsigned)(bufoff) + ldsw + (unsigned)(_i * 8192); \
;         asm volatile("s_mov_b32 m0, %2\n\ts_nop 0\n\tglobal_load_lds_dwordx4 %0, %1" :: "v"((voff)[_i]), "s"((const char*)(gbase)), "s"(_m0) : "memory"); } } while (0)
; #define PG8_LDA(dst, b, h) do { _Pragma("unroll") for (int m = 0; m < 4; ++m) _Pragma("unroll") for (int k = 0; k < 2; ++k) dst[m][k] = *(const LAS bf16x8*)(lds + PG8_SA(b, h) + aoff + m * 2048 + k * 1024); } while (0)
; #define PG8_LDB(dst, b, h) do { _Pragma("unroll") for (int n = 0; n < 2; ++n) _Pragma("unroll") for (int k = 0; k < 2; ++k) dst[n][k] = *(const LAS bf16x8*)(lds + bbase[b][h] + n * 2048 + k * 1024); } while (0)
; #define PG8_WAIT_V(n) asm volatile("s_waitcnt vmcnt(" #n ")" ::: "memory")
; #define PG8_BAR __builtin_amdgcn_s_barrier()
; template <class Epi>
; __device__ __forceinline__ void gemm_phase(LAS unsigned char* lds, const Gemm g, const StaticOrder& S, const Epi& E) {
;     ...
;         for (int t = 0; t < nt; t += 2) {
;             const bool last = (t == nt - 2);
;             const char* a2 = last ? nA : cA + (size_t)(t + 2) * kstep; const char* b2 = last ? nB : cB + (size_t)(t + 2) * kstep;
;             const char* a3 = a2 + kstep; const char* b3 = b2 + kstep;
;             const char* b1 = cB + (size_t)(t + 1) * kstep;
;             PG8_LDB(B0, 0, 0); PG8_SCHED; PG8_LDA(At, 0, 0); PG8_LDA(At2, 0, 1); PG8_STAGE(PG8_SB(1, 1), b1 + hstepB, voffB);
;             PG8_WAIT_V(8); PG8_WAIT_L(0); PG8_BAR; PG8_MMA2B(0, At, At2, B0); PG8_BAR; PG8_SCHED;
;             PG8_LDB(B0, 0, 1); PG8_STAGE(PG8_SB(0, 0), b2, voffB); PG8_STAGE(PG8_SA(0, 0), a2, voffA); PG8_STAGE(PG8_SA(0, 1), a2 + hstepA, voffA);
;             PG8_WAIT_V(8); PG8_WAIT_L(0); PG8_BAR; PG8_MMA2B(1, At, At2, B0); PG8_BAR; PG8_SCHED;
;             PG8_LDB(B0, 1, 0); PG8_SCHED; PG8_LDA(At, 1, 0); PG8_LDA(At2, 1, 1); PG8_STAGE(PG8_SB(0, 1), b2 + hstepB, voffB);
;             PG8_WAIT_V(8); PG8_WAIT_L(0); PG8_BAR; PG8_MMA2B(0, At, At2, B0); PG8_BAR; PG8_SCHED;
;             PG8_LDB(B0, 1, 1); PG8_STAGE(PG8_SB(1, 0), b3, voffB); PG8_STAGE(PG8_SA(1, 0), a3, voffA); PG8_STAGE(PG8_SA(1, 1), a3 + hstepA, voffA);
;             PG8_WAIT_V(8); PG8_WAIT_L(0); PG8_BAR; PG8_MMA2B(1, At, At2, B0); PG8_BAR; PG8_SCHED;
;         }
.LBB0_584:
	ds_read_b128 v[128:131], v155
	ds_read_b128 v[132:135], v155 offset:1024
	ds_read_b128 v[136:139], v155 offset:2048
	ds_read_b128 v[140:143], v155 offset:3072
	s_add_u32 s10, s8, 0x100
	s_addc_u32 s11, s9, 0
	s_cmp_eq_u32 s68, 12
	s_cselect_b32 s84, s67, s87
	s_cselect_b32 s85, s43, s88
	s_cselect_b32 s90, s86, s10
	s_cselect_b32 s91, s39, s11
	s_add_u32 s96, s84, 0x80
	s_addc_u32 s97, s85, 0
	ds_read_b128 v[144:147], v156
	ds_read_b128 v[178:181], v156 offset:1024
	ds_read_b128 v[182:185], v156 offset:2048
	ds_read_b128 v[186:189], v156 offset:3072
	ds_read_b128 v[190:193], v156 offset:4096
	ds_read_b128 v[194:197], v156 offset:5120
	ds_read_b128 v[198:201], v156 offset:6144
	ds_read_b128 v[202:205], v156 offset:7168
	ds_read_b128 v[214:217], v156 offset:16384
	ds_read_b128 v[218:221], v156 offset:17408
	ds_read_b128 v[222:225], v156 offset:18432
	ds_read_b128 v[226:229], v156 offset:19456
	ds_read_b128 v[230:233], v156 offset:20480
	ds_read_b128 v[234:237], v156 offset:21504
	ds_read_b128 v[238:241], v156 offset:22528
	ds_read_b128 v[242:245], v156 offset:23552
	s_add_u32 s8, s8, 0x40080
	s_addc_u32 s9, s9, 0
	s_mov_b32 m0, s61
	s_nop 0
	global_load_lds_dwordx4 v151, s[8:9]
	s_mov_b32 m0, s64
	s_nop 0
	global_load_lds_dwordx4 v153, s[8:9]
	s_waitcnt vmcnt(8)
	s_waitcnt lgkmcnt(0)
	s_barrier
	s_waitcnt lgkmcnt(14)
	v_mfma_f32_16x16x32_bf16 v[76:79], v[128:131], v[144:147], v[76:79]
	v_mfma_f32_16x16x32_bf16 v[72:75], v[136:139], v[144:147], v[72:75]
	s_waitcnt lgkmcnt(13)
	v_mfma_f32_16x16x32_bf16 v[64:67], v[128:131], v[182:185], v[64:67]
	v_mfma_f32_16x16x32_bf16 v[60:63], v[136:139], v[182:185], v[60:63]
	s_waitcnt lgkmcnt(11)
	v_mfma_f32_16x16x32_bf16 v[56:59], v[128:131], v[190:193], v[56:59]
	v_mfma_f32_16x16x32_bf16 v[52:55], v[136:139], v[190:193], v[52:55]
	s_waitcnt lgkmcnt(9)
	v_mfma_f32_16x16x32_bf16 v[112:115], v[128:131], v[198:201], v[112:115]
	v_mfma_f32_16x16x32_bf16 v[104:107], v[136:139], v[198:201], v[104:107]
	s_waitcnt lgkmcnt(7)
	v_mfma_f32_16x16x32_bf16 v[36:39], v[128:131], v[214:217], v[36:39]
	v_mfma_f32_16x16x32_bf16 v[32:35], v[136:139], v[214:217], v[32:35]
	s_waitcnt lgkmcnt(5)
	v_mfma_f32_16x16x32_bf16 v[28:31], v[128:131], v[222:225], v[28:31]
	v_mfma_f32_16x16x32_bf16 v[24:27], v[136:139], v[222:225], v[24:27]
	s_waitcnt lgkmcnt(3)
	v_mfma_f32_16x16x32_bf16 v[16:19], v[128:131], v[230:233], v[16:19]
	v_mfma_f32_16x16x32_bf16 v[12:15], v[136:139], v[230:233], v[12:15]
	s_waitcnt lgkmcnt(1)
	v_mfma_f32_16x16x32_bf16 v[88:91], v[128:131], v[238:241], v[88:91]
	v_mfma_f32_16x16x32_bf16 v[84:87], v[136:139], v[238:241], v[84:87]
	v_mfma_f32_16x16x32_bf16 v[76:79], v[132:135], v[178:181], v[76:79]
	v_mfma_f32_16x16x32_bf16 v[72:75], v[140:143], v[178:181], v[72:75]
	v_mfma_f32_16x16x32_bf16 v[64:67], v[132:135], v[186:189], v[64:67]
	v_mfma_f32_16x16x32_bf16 v[60:63], v[140:143], v[186:189], v[60:63]
	v_mfma_f32_16x16x32_bf16 v[56:59], v[132:135], v[194:197], v[56:59]
	v_mfma_f32_16x16x32_bf16 v[52:55], v[140:143], v[194:197], v[52:55]
	v_mfma_f32_16x16x32_bf16 v[112:115], v[132:135], v[202:205], v[112:115]
	v_mfma_f32_16x16x32_bf16 v[104:107], v[140:143], v[202:205], v[104:107]
	v_mfma_f32_16x16x32_bf16 v[36:39], v[132:135], v[218:221], v[36:39]
	v_mfma_f32_16x16x32_bf16 v[32:35], v[140:143], v[218:221], v[32:35]
	v_mfma_f32_16x16x32_bf16 v[28:31], v[132:135], v[226:229], v[28:31]
	v_mfma_f32_16x16x32_bf16 v[24:27], v[140:143], v[226:229], v[24:27]
	v_mfma_f32_16x16x32_bf16 v[16:19], v[132:135], v[234:237], v[16:19]
	v_mfma_f32_16x16x32_bf16 v[12:15], v[140:143], v[234:237], v[12:15]
	s_waitcnt lgkmcnt(0)
	v_mfma_f32_16x16x32_bf16 v[88:91], v[132:135], v[242:245], v[88:91]
	v_mfma_f32_16x16x32_bf16 v[84:87], v[140:143], v[242:245], v[84:87]
	s_barrier
	ds_read_b128 v[128:131], v157
	ds_read_b128 v[132:135], v157 offset:1024
	ds_read_b128 v[136:139], v157 offset:2048
	ds_read_b128 v[140:143], v157 offset:3072
	s_mov_b32 m0, s47
	s_nop 0
	global_load_lds_dwordx4 v151, s[90:91]
	s_mov_b32 m0, s48
	s_nop 0
	global_load_lds_dwordx4 v153, s[90:91]
	s_mov_b32 m0, s37
	s_nop 0
	global_load_lds_dwordx4 v150, s[84:85]
	s_mov_b32 m0, s49
	s_nop 0
	global_load_lds_dwordx4 v152, s[84:85]
	s_add_u32 s8, s84, 0x40000
	s_addc_u32 s9, s85, 0
	s_mov_b32 m0, s50
	s_nop 0
	global_load_lds_dwordx4 v150, s[8:9]
	s_mov_b32 m0, s51
	s_nop 0
	global_load_lds_dwordx4 v152, s[8:9]
	s_waitcnt vmcnt(8)
	s_waitcnt lgkmcnt(0)
	s_barrier
	s_waitcnt lgkmcnt(3)
	v_mfma_f32_16x16x32_bf16 v[68:71], v[128:131], v[144:147], v[68:71]
	s_waitcnt lgkmcnt(1)
	v_mfma_f32_16x16x32_bf16 v[124:127], v[136:139], v[144:147], v[124:127]
	v_mfma_f32_16x16x32_bf16 v[48:51], v[128:131], v[182:185], v[48:51]
	v_mfma_f32_16x16x32_bf16 v[120:123], v[136:139], v[182:185], v[120:123]
	v_mfma_f32_16x16x32_bf16 v[44:47], v[128:131], v[190:193], v[44:47]
	v_mfma_f32_16x16x32_bf16 v[116:119], v[136:139], v[190:193], v[116:119]
	v_mfma_f32_16x16x32_bf16 v[40:43], v[128:131], v[198:201], v[40:43]
	v_mfma_f32_16x16x32_bf16 v[108:111], v[136:139], v[198:201], v[108:111]
	v_mfma_f32_16x16x32_bf16 v[20:23], v[128:131], v[214:217], v[20:23]
	v_mfma_f32_16x16x32_bf16 v[100:103], v[136:139], v[214:217], v[100:103]
	v_mfma_f32_16x16x32_bf16 v[8:11], v[128:131], v[222:225], v[8:11]
	v_mfma_f32_16x16x32_bf16 v[96:99], v[136:139], v[222:225], v[96:99]
	v_mfma_f32_16x16x32_bf16 v[4:7], v[128:131], v[230:233], v[4:7]
	v_mfma_f32_16x16x32_bf16 v[92:95], v[136:139], v[230:233], v[92:95]
	v_mfma_f32_16x16x32_bf16 v[0:3], v[128:131], v[238:241], v[0:3]
	v_mfma_f32_16x16x32_bf16 v[80:83], v[136:139], v[238:241], v[80:83]
	v_mfma_f32_16x16x32_bf16 v[68:71], v[132:135], v[178:181], v[68:71]
	s_waitcnt lgkmcnt(0)
	v_mfma_f32_16x16x32_bf16 v[124:127], v[140:143], v[178:181], v[124:127]
	v_mfma_f32_16x16x32_bf16 v[48:51], v[132:135], v[186:189], v[48:51]
	v_mfma_f32_16x16x32_bf16 v[120:123], v[140:143], v[186:189], v[120:123]
	v_mfma_f32_16x16x32_bf16 v[44:47], v[132:135], v[194:197], v[44:47]
	v_mfma_f32_16x16x32_bf16 v[116:119], v[140:143], v[194:197], v[116:119]
	v_mfma_f32_16x16x32_bf16 v[40:43], v[132:135], v[202:205], v[40:43]
	v_mfma_f32_16x16x32_bf16 v[108:111], v[140:143], v[202:205], v[108:111]
	v_mfma_f32_16x16x32_bf16 v[20:23], v[132:135], v[218:221], v[20:23]
	v_mfma_f32_16x16x32_bf16 v[100:103], v[140:143], v[218:221], v[100:103]
	v_mfma_f32_16x16x32_bf16 v[8:11], v[132:135], v[226:229], v[8:11]
	v_mfma_f32_16x16x32_bf16 v[96:99], v[140:143], v[226:229], v[96:99]
	v_mfma_f32_16x16x32_bf16 v[4:7], v[132:135], v[234:237], v[4:7]
	v_mfma_f32_16x16x32_bf16 v[92:95], v[140:143], v[234:237], v[92:95]
	v_mfma_f32_16x16x32_bf16 v[0:3], v[132:135], v[242:245], v[0:3]
	v_mfma_f32_16x16x32_bf16 v[80:83], v[140:143], v[242:245], v[80:83]
	s_barrier
; #define PG8_STAGE(bufoff, gbase, voff) do { _Pragma("unroll") for (int _i = 0; _i < 2; ++_i) { \
;         const unsigned _m0 = ldsu + (unsigned)(bufoff) + ldsw + (unsigned)(_i * 8192); \
;         asm volatile("s_mov_b32 m0, %2\n\ts_nop 0\n\tglobal_load_lds_dwordx4 %0, %1" :: "v"((voff)[_i]), "s"((const char*)(gbase)), "s"(_m0) : "memory"); } } while (0)
; #define PG8_LDA(dst, b, h) do { _Pragma("unroll") for (int m = 0; m < 4; ++m) _Pragma("unroll") for (int k = 0; k < 2; ++k) dst[m][k] = *(const LAS bf16x8*)(lds + PG8_SA(b, h) + aoff + m * 2048 + k * 1024); } while (0)
; #define PG8_LDB(dst, b, h) do { _Pragma("unroll") for (int n = 0; n < 2; ++n) _Pragma("unroll") for (int k = 0; k < 2; ++k) dst[n][k] = *(const LAS bf16x8*)(lds + bbase[b][h] + n * 2048 + k * 1024); } while (0)
; #define PG8_WAIT_V(n) asm volatile("s_waitcnt vmcnt(" #n ")" ::: "memory")
; #define PG8_WAIT_L(n) asm volatile("s_waitcnt lgkmcnt(" #n ")" ::: "memory")
; #define PG8_BAR __builtin_amdgcn_s_barrier()
; #define PG8_SCHED __builtin_amdgcn_sched_barrier(0)
; template <class Epi>
; __device__ __forceinline__ void gemm_phase(LAS unsigned char* lds, const Gemm g, const StaticOrder& S, const Epi& E) {
;     ...
;             PG8_LDB(B0, 1, 0); PG8_SCHED; PG8_LDA(At, 1, 0); PG8_LDA(At2, 1, 1); PG8_STAGE(PG8_SB(0, 1), b2 + hstepB, voffB);
;             PG8_WAIT_V(8); PG8_WAIT_L(0); PG8_BAR; PG8_MMA2B(0, At, At2, B0); PG8_BAR; PG8_SCHED;
;             PG8_LDB(B0, 1, 1); PG8_STAGE(PG8_SB(1, 0), b3, voffB); PG8_STAGE(PG8_SA(1, 0), a3, voffA); PG8_STAGE(PG8_SA(1, 1), a3 + hstepA, voffA);
;             PG8_WAIT_V(8); PG8_WAIT_L(0); PG8_BAR; PG8_MMA2B(1, At, At2, B0); PG8_BAR; PG8_SCHED;
;         }
;         if (wr == 0) PG8_BAR;
	ds_read_b128 v[128:131], v158
	ds_read_b128 v[132:135], v158 offset:1024
	ds_read_b128 v[136:139], v158 offset:2048
	ds_read_b128 v[140:143], v158 offset:3072
	ds_read_b128 v[144:147], v156 offset:32768
	ds_read_b128 v[178:181], v156 offset:33792
	ds_read_b128 v[182:185], v156 offset:34816
	ds_read_b128 v[186:189], v156 offset:35840
	ds_read_b128 v[190:193], v156 offset:36864
	ds_read_b128 v[194:197], v156 offset:37888
	ds_read_b128 v[198:201], v156 offset:38912
	ds_read_b128 v[202:205], v156 offset:39936
	ds_read_b128 v[214:217], v156 offset:49152
	ds_read_b128 v[218:221], v156 offset:50176
	ds_read_b128 v[222:225], v156 offset:51200
	ds_read_b128 v[226:229], v156 offset:52224
	ds_read_b128 v[230:233], v156 offset:53248
	ds_read_b128 v[234:237], v156 offset:54272
	ds_read_b128 v[238:241], v156 offset:55296
	ds_read_b128 v[242:245], v156 offset:56320
	s_add_u32 s8, s90, 0x40000
	s_addc_u32 s9, s91, 0
	s_mov_b32 m0, s52
	s_nop 0
	global_load_lds_dwordx4 v151, s[8:9]
	s_mov_b32 m0, s53
	s_nop 0
	global_load_lds_dwordx4 v153, s[8:9]
	s_waitcnt vmcnt(8)
	s_waitcnt lgkmcnt(0)
	s_barrier
	s_waitcnt lgkmcnt(14)
	v_mfma_f32_16x16x32_bf16 v[76:79], v[128:131], v[144:147], v[76:79]
	v_mfma_f32_16x16x32_bf16 v[72:75], v[136:139], v[144:147], v[72:75]
	s_waitcnt lgkmcnt(13)
	v_mfma_f32_16x16x32_bf16 v[64:67], v[128:131], v[182:185], v[64:67]
	v_mfma_f32_16x16x32_bf16 v[60:63], v[136:139], v[182:185], v[60:63]
	s_waitcnt lgkmcnt(11)
	v_mfma_f32_16x16x32_bf16 v[56:59], v[128:131], v[190:193], v[56:59]
	v_mfma_f32_16x16x32_bf16 v[52:55], v[136:139], v[190:193], v[52:55]
	s_waitcnt lgkmcnt(9)
	v_mfma_f32_16x16x32_bf16 v[112:115], v[128:131], v[198:201], v[112:115]
	v_mfma_f32_16x16x32_bf16 v[104:107], v[136:139], v[198:201], v[104:107]
	s_waitcnt lgkmcnt(7)
	v_mfma_f32_16x16x32_bf16 v[36:39], v[128:131], v[214:217], v[36:39]
	v_mfma_f32_16x16x32_bf16 v[32:35], v[136:139], v[214:217], v[32:35]
	s_waitcnt lgkmcnt(5)
	v_mfma_f32_16x16x32_bf16 v[28:31], v[128:131], v[222:225], v[28:31]
	v_mfma_f32_16x16x32_bf16 v[24:27], v[136:139], v[222:225], v[24:27]
	s_waitcnt lgkmcnt(3)
	v_mfma_f32_16x16x32_bf16 v[16:19], v[128:131], v[230:233], v[16:19]
	v_mfma_f32_16x16x32_bf16 v[12:15], v[136:139], v[230:233], v[12:15]
	s_waitcnt lgkmcnt(1)
	v_mfma_f32_16x16x32_bf16 v[88:91], v[128:131], v[238:241], v[88:91]
	v_mfma_f32_16x16x32_bf16 v[84:87], v[136:139], v[238:241], v[84:87]
	v_mfma_f32_16x16x32_bf16 v[76:79], v[132:135], v[178:181], v[76:79]
	v_mfma_f32_16x16x32_bf16 v[72:75], v[140:143], v[178:181], v[72:75]
	v_mfma_f32_16x16x32_bf16 v[64:67], v[132:135], v[186:189], v[64:67]
	v_mfma_f32_16x16x32_bf16 v[60:63], v[140:143], v[186:189], v[60:63]
	v_mfma_f32_16x16x32_bf16 v[56:59], v[132:135], v[194:197], v[56:59]
	v_mfma_f32_16x16x32_bf16 v[52:55], v[140:143], v[194:197], v[52:55]
	v_mfma_f32_16x16x32_bf16 v[112:115], v[132:135], v[202:205], v[112:115]
	v_mfma_f32_16x16x32_bf16 v[104:107], v[140:143], v[202:205], v[104:107]
	v_mfma_f32_16x16x32_bf16 v[36:39], v[132:135], v[218:221], v[36:39]
	v_mfma_f32_16x16x32_bf16 v[32:35], v[140:143], v[218:221], v[32:35]
	v_mfma_f32_16x16x32_bf16 v[28:31], v[132:135], v[226:229], v[28:31]
	v_mfma_f32_16x16x32_bf16 v[24:27], v[140:143], v[226:229], v[24:27]
	v_mfma_f32_16x16x32_bf16 v[16:19], v[132:135], v[234:237], v[16:19]
	v_mfma_f32_16x16x32_bf16 v[12:15], v[140:143], v[234:237], v[12:15]
	s_waitcnt lgkmcnt(0)
	v_mfma_f32_16x16x32_bf16 v[88:91], v[132:135], v[242:245], v[88:91]
	v_mfma_f32_16x16x32_bf16 v[84:87], v[140:143], v[242:245], v[84:87]
	s_barrier
	s_add_u32 s8, s90, 0x80
	ds_read_b128 v[128:131], v159
	ds_read_b128 v[132:135], v159 offset:1024
	ds_read_b128 v[136:139], v159 offset:2048
	ds_read_b128 v[140:143], v159 offset:3072
	s_addc_u32 s9, s91, 0
	s_mov_b32 m0, s55
	s_nop 0
	global_load_lds_dwordx4 v151, s[8:9]
	s_mov_b32 m0, s56
	s_nop 0
	global_load_lds_dwordx4 v153, s[8:9]
	s_mov_b32 m0, s57
	s_nop 0
	global_load_lds_dwordx4 v150, s[96:97]
	s_mov_b32 m0, s58
	s_nop 0
	global_load_lds_dwordx4 v152, s[96:97]
	s_add_u32 s8, s84, 0x40080
	s_addc_u32 s9, s85, 0
	s_mov_b32 m0, s59
	s_nop 0
	global_load_lds_dwordx4 v150, s[8:9]
	s_mov_b32 m0, s60
	s_nop 0
	global_load_lds_dwordx4 v152, s[8:9]
	s_waitcnt vmcnt(8)
	s_waitcnt lgkmcnt(0)
	s_barrier
	s_waitcnt lgkmcnt(3)
	v_mfma_f32_16x16x32_bf16 v[68:71], v[128:131], v[144:147], v[68:71]
	s_waitcnt lgkmcnt(1)
	v_mfma_f32_16x16x32_bf16 v[124:127], v[136:139], v[144:147], v[124:127]
	v_mfma_f32_16x16x32_bf16 v[48:51], v[128:131], v[182:185], v[48:51]
	v_mfma_f32_16x16x32_bf16 v[120:123], v[136:139], v[182:185], v[120:123]
	v_mfma_f32_16x16x32_bf16 v[44:47], v[128:131], v[190:193], v[44:47]
	v_mfma_f32_16x16x32_bf16 v[116:119], v[136:139], v[190:193], v[116:119]
	v_mfma_f32_16x16x32_bf16 v[40:43], v[128:131], v[198:201], v[40:43]
	v_mfma_f32_16x16x32_bf16 v[108:111], v[136:139], v[198:201], v[108:111]
	v_mfma_f32_16x16x32_bf16 v[20:23], v[128:131], v[214:217], v[20:23]
	v_mfma_f32_16x16x32_bf16 v[100:103], v[136:139], v[214:217], v[100:103]
	v_mfma_f32_16x16x32_bf16 v[8:11], v[128:131], v[222:225], v[8:11]
	v_mfma_f32_16x16x32_bf16 v[96:99], v[136:139], v[222:225], v[96:99]
	v_mfma_f32_16x16x32_bf16 v[4:7], v[128:131], v[230:233], v[4:7]
	v_mfma_f32_16x16x32_bf16 v[92:95], v[136:139], v[230:233], v[92:95]
	v_mfma_f32_16x16x32_bf16 v[0:3], v[128:131], v[238:241], v[0:3]
	v_mfma_f32_16x16x32_bf16 v[80:83], v[136:139], v[238:241], v[80:83]
	v_mfma_f32_16x16x32_bf16 v[68:71], v[132:135], v[178:181], v[68:71]
	s_waitcnt lgkmcnt(0)
	v_mfma_f32_16x16x32_bf16 v[124:127], v[140:143], v[178:181], v[124:127]
	v_mfma_f32_16x16x32_bf16 v[48:51], v[132:135], v[186:189], v[48:51]
	v_mfma_f32_16x16x32_bf16 v[120:123], v[140:143], v[186:189], v[120:123]
	v_mfma_f32_16x16x32_bf16 v[44:47], v[132:135], v[194:197], v[44:47]
	v_mfma_f32_16x16x32_bf16 v[116:119], v[140:143], v[194:197], v[116:119]
	v_mfma_f32_16x16x32_bf16 v[40:43], v[132:135], v[202:205], v[40:43]
	v_mfma_f32_16x16x32_bf16 v[108:111], v[140:143], v[202:205], v[108:111]
	v_mfma_f32_16x16x32_bf16 v[20:23], v[132:135], v[218:221], v[20:23]
	v_mfma_f32_16x16x32_bf16 v[100:103], v[140:143], v[218:221], v[100:103]
	v_mfma_f32_16x16x32_bf16 v[8:11], v[132:135], v[226:229], v[8:11]
	v_mfma_f32_16x16x32_bf16 v[96:99], v[140:143], v[226:229], v[96:99]
	v_mfma_f32_16x16x32_bf16 v[4:7], v[132:135], v[234:237], v[4:7]
	v_mfma_f32_16x16x32_bf16 v[92:95], v[140:143], v[234:237], v[92:95]
	v_mfma_f32_16x16x32_bf16 v[0:3], v[132:135], v[242:245], v[0:3]
	v_mfma_f32_16x16x32_bf16 v[80:83], v[140:143], v[242:245], v[80:83]
	s_barrier
	s_add_i32 s68, s68, 2
	s_add_u32 s87, s87, 0x100
	s_addc_u32 s88, s88, 0
	s_cmp_gt_u32 s68, 13
	s_mov_b64 s[8:9], s[10:11]
	s_cbranch_scc0 .LBB0_584
	s_and_b64 vcc, exec, s[4:5]
	s_cbranch_vccz .LBB0_587
	s_barrier

; #define PG8_STAGE(bufoff, gbase, voff) do { _Pragma("unroll") for (int _i = 0; _i < 2; ++_i) { \
;         const unsigned _m0 = ldsu + (unsigned)(bufoff) + ldsw + (unsigned)(_i * 8192); \
;         asm volatile("s_mov_b32 m0, %2\n\ts_nop 0\n\tglobal_load_lds_dwordx4 %0, %1" :: "v"((voff)[_i]), "s"((const char*)(gbase)), "s"(_m0) : "memory"); } } while (0)
; #define PG8_LDA(dst, b, h) do { _Pragma("unroll") for (int m = 0; m < 4; ++m) _Pragma("unroll") for (int k = 0; k < 2; ++k) dst[m][k] = *(const LAS bf16x8*)(lds + PG8_SA(b, h) + aoff + m * 2048 + k * 1024); } while (0)
; #define PG8_LDB(dst, b, h) do { _Pragma("unroll") for (int n = 0; n < 2; ++n) _Pragma("unroll") for (int k = 0; k < 2; ++k) dst[n][k] = *(const LAS bf16x8*)(lds + bbase[b][h] + n * 2048 + k * 1024); } while (0)
; #define PG8_WAIT_V(n) asm volatile("s_waitcnt vmcnt(" #n ")" ::: "memory")
; #define PG8_WAIT_L(n) asm volatile("s_waitcnt lgkmcnt(" #n ")" ::: "memory")
; #define PG8_BAR __builtin_amdgcn_s_barrier()
; #define PG8_SCHED __builtin_amdgcn_sched_barrier(0)
; template <class Epi>
; __device__ __forceinline__ void gemm_phase(LAS unsigned char* lds, const Gemm g, const StaticOrder& S, const Epi& E) {
;     ...
;             PG8_LDB(B0, 0, 0); PG8_SCHED; PG8_LDA(At, 0, 0); PG8_LDA(At2, 0, 1); PG8_STAGE(PG8_SB(1, 1), b1 + hstepB, voffB);
;             PG8_WAIT_V(8); PG8_WAIT_L(0); PG8_BAR; PG8_MMA2B(0, At, At2, B0); PG8_BAR; PG8_SCHED;
;             PG8_LDB(B0, 0, 1); PG8_STAGE(PG8_SB(0, 0), b2, voffB); PG8_STAGE(PG8_SA(0, 0), a2, voffA); PG8_STAGE(PG8_SA(0, 1), a2 + hstepA, voffA);
;             PG8_WAIT_V(8); PG8_WAIT_L(0); PG8_BAR; PG8_MMA2B(1, At, At2, B0); PG8_BAR; PG8_SCHED;
.LBB0_662:
	s_add_i32 s85, s38, 2
	s_add_u32 s42, s67, 0x80
	ds_read_b128 v[74:77], v71
	ds_read_b128 v[78:81], v71 offset:1024
	ds_read_b128 v[82:85], v71 offset:2048
	ds_read_b128 v[86:89], v71 offset:3072
	s_addc_u32 s43, s68, 0
	s_cmp_eq_u32 s62, s38
	s_cselect_b32 s38, s10, s69
	s_cselect_b32 s39, s11, s84
	s_cselect_b32 s82, s37, s42
	s_cselect_b32 s83, s13, s43
	s_add_u32 s42, s38, 0x80
	s_addc_u32 s43, s39, 0
	s_add_u32 s80, s82, 0x80
	s_addc_u32 s81, s83, 0
	ds_read_b128 v[90:93], v72
	ds_read_b128 v[94:97], v72 offset:1024
	ds_read_b128 v[98:101], v72 offset:2048
	ds_read_b128 v[102:105], v72 offset:3072
	ds_read_b128 v[106:109], v72 offset:4096
	ds_read_b128 v[110:113], v72 offset:5120
	ds_read_b128 v[114:117], v72 offset:6144
	ds_read_b128 v[118:121], v72 offset:7168
	ds_read_b128 v[122:125], v72 offset:16384
	ds_read_b128 v[126:129], v72 offset:17408
	ds_read_b128 v[130:133], v72 offset:18432
	ds_read_b128 v[134:137], v72 offset:19456
	ds_read_b128 v[138:141], v72 offset:20480
	ds_read_b128 v[142:145], v72 offset:21504
	ds_read_b128 v[146:149], v72 offset:22528
	ds_read_b128 v[150:153], v72 offset:23552
	s_add_u32 s86, s67, 0x10000
	s_addc_u32 s87, s68, 0
	s_mov_b32 m0, s63
	s_nop 0
	global_load_lds_dwordx4 v67, s[86:87]
	s_mov_b32 m0, s64
	s_nop 0
	global_load_lds_dwordx4 v69, s[86:87]
	s_waitcnt vmcnt(8)
	s_waitcnt lgkmcnt(0)
	s_barrier
	s_waitcnt lgkmcnt(14)
	v_mfma_f32_16x16x32_bf16 v[60:63], v[74:77], v[90:93], v[60:63]
	v_mfma_f32_16x16x32_bf16 v[56:59], v[82:85], v[90:93], v[56:59]
	s_waitcnt lgkmcnt(13)
	v_mfma_f32_16x16x32_bf16 v[52:55], v[74:77], v[98:101], v[52:55]
	v_mfma_f32_16x16x32_bf16 v[48:51], v[82:85], v[98:101], v[48:51]
	s_waitcnt lgkmcnt(11)
	v_mfma_f32_16x16x32_bf16 v[44:47], v[74:77], v[106:109], v[44:47]
	v_mfma_f32_16x16x32_bf16 v[40:43], v[82:85], v[106:109], v[40:43]
	s_waitcnt lgkmcnt(9)
	v_mfma_f32_16x16x32_bf16 v[36:39], v[74:77], v[114:117], v[36:39]
	v_mfma_f32_16x16x32_bf16 v[32:35], v[82:85], v[114:117], v[32:35]
	s_waitcnt lgkmcnt(7)
	v_mfma_f32_16x16x32_bf16 v[28:31], v[74:77], v[122:125], v[28:31]
	v_mfma_f32_16x16x32_bf16 v[24:27], v[82:85], v[122:125], v[24:27]
	s_waitcnt lgkmcnt(5)
	v_mfma_f32_16x16x32_bf16 v[20:23], v[74:77], v[130:133], v[20:23]
	v_mfma_f32_16x16x32_bf16 v[16:19], v[82:85], v[130:133], v[16:19]
	s_waitcnt lgkmcnt(3)
	v_mfma_f32_16x16x32_bf16 v[12:15], v[74:77], v[138:141], v[12:15]
	v_mfma_f32_16x16x32_bf16 v[8:11], v[82:85], v[138:141], v[8:11]
	s_waitcnt lgkmcnt(1)
	v_mfma_f32_16x16x32_bf16 v[4:7], v[74:77], v[146:149], v[4:7]
	v_mfma_f32_16x16x32_bf16 v[0:3], v[82:85], v[146:149], v[0:3]
	v_mfma_f32_16x16x32_bf16 v[60:63], v[78:81], v[94:97], v[60:63]
	v_mfma_f32_16x16x32_bf16 v[56:59], v[86:89], v[94:97], v[56:59]
	v_mfma_f32_16x16x32_bf16 v[52:55], v[78:81], v[102:105], v[52:55]
	v_mfma_f32_16x16x32_bf16 v[48:51], v[86:89], v[102:105], v[48:51]
	v_mfma_f32_16x16x32_bf16 v[44:47], v[78:81], v[110:113], v[44:47]
	v_mfma_f32_16x16x32_bf16 v[40:43], v[86:89], v[110:113], v[40:43]
	v_mfma_f32_16x16x32_bf16 v[36:39], v[78:81], v[118:121], v[36:39]
	v_mfma_f32_16x16x32_bf16 v[32:35], v[86:89], v[118:121], v[32:35]
	v_mfma_f32_16x16x32_bf16 v[28:31], v[78:81], v[126:129], v[28:31]
	v_mfma_f32_16x16x32_bf16 v[24:27], v[86:89], v[126:129], v[24:27]
	v_mfma_f32_16x16x32_bf16 v[20:23], v[78:81], v[134:137], v[20:23]
	v_mfma_f32_16x16x32_bf16 v[16:19], v[86:89], v[134:137], v[16:19]
	v_mfma_f32_16x16x32_bf16 v[12:15], v[78:81], v[142:145], v[12:15]
	v_mfma_f32_16x16x32_bf16 v[8:11], v[86:89], v[142:145], v[8:11]
	s_waitcnt lgkmcnt(0)
	v_mfma_f32_16x16x32_bf16 v[4:7], v[78:81], v[150:153], v[4:7]
	v_mfma_f32_16x16x32_bf16 v[0:3], v[86:89], v[150:153], v[0:3]
	s_barrier
	s_mov_b32 m0, s48
	s_nop 0
	global_load_lds_dwordx4 v67, s[82:83]
	s_mov_b32 m0, s49
	s_nop 0
	global_load_lds_dwordx4 v69, s[82:83]
	s_mov_b32 m0, s47
	s_nop 0
	global_load_lds_dwordx4 v66, s[38:39]
	s_mov_b32 m0, s50
	s_nop 0
	global_load_lds_dwordx4 v68, s[38:39]
	s_add_u32 s86, s38, 0x18000
	s_addc_u32 s87, s39, 0
	s_mov_b32 m0, s51
	s_nop 0
	global_load_lds_dwordx4 v66, s[86:87]
	s_mov_b32 m0, s52
	s_nop 0
	global_load_lds_dwordx4 v68, s[86:87]
	s_waitcnt vmcnt(8)
	s_waitcnt lgkmcnt(0)
	s_barrier
; #define PG8_STAGE(bufoff, gbase, voff) do { _Pragma("unroll") for (int _i = 0; _i < 2; ++_i) { \
;         const unsigned _m0 = ldsu + (unsigned)(bufoff) + ldsw + (unsigned)(_i * 8192); \
;         asm volatile("s_mov_b32 m0, %2\n\ts_nop 0\n\tglobal_load_lds_dwordx4 %0, %1" :: "v"((voff)[_i]), "s"((const char*)(gbase)), "s"(_m0) : "memory"); } } while (0)
; #define PG8_LDA(dst, b, h) do { _Pragma("unroll") for (int m = 0; m < 4; ++m) _Pragma("unroll") for (int k = 0; k < 2; ++k) dst[m][k] = *(const LAS bf16x8*)(lds + PG8_SA(b, h) + aoff + m * 2048 + k * 1024); } while (0)
; #define PG8_LDB(dst, b, h) do { _Pragma("unroll") for (int n = 0; n < 2; ++n) _Pragma("unroll") for (int k = 0; k < 2; ++k) dst[n][k] = *(const LAS bf16x8*)(lds + bbase[b][h] + n * 2048 + k * 1024); } while (0)
; #define PG8_WAIT_V(n) asm volatile("s_waitcnt vmcnt(" #n ")" ::: "memory")
; #define PG8_WAIT_L(n) asm volatile("s_waitcnt lgkmcnt(" #n ")" ::: "memory")
; #define PG8_BAR __builtin_amdgcn_s_barrier()
; #define PG8_SCHED __builtin_amdgcn_sched_barrier(0)
; template <class Epi>
; __device__ __forceinline__ void gemm_phase(LAS unsigned char* lds, const Gemm g, const StaticOrder& S, const Epi& E) {
;     ...
;             PG8_WAIT_V(8); PG8_WAIT_L(0); PG8_BAR; PG8_MMA2B(1, At, At2, B0); PG8_BAR; PG8_SCHED;
;             PG8_LDB(B0, 1, 0); PG8_SCHED; PG8_LDA(At, 1, 0); PG8_LDA(At2, 1, 1); PG8_STAGE(PG8_SB(0, 1), b2 + hstepB, voffB);
;             PG8_WAIT_V(8); PG8_WAIT_L(0); PG8_BAR; PG8_MMA2B(0, At, At2, B0); PG8_BAR; PG8_SCHED;
;             PG8_LDB(B0, 1, 1); PG8_STAGE(PG8_SB(1, 0), b3, voffB); PG8_STAGE(PG8_SA(1, 0), a3, voffA); PG8_STAGE(PG8_SA(1, 1), a3 + hstepA, voffA);
;             PG8_WAIT_V(8); PG8_WAIT_L(0); PG8_BAR; PG8_MMA2B(1, At, At2, B0); PG8_BAR; PG8_SCHED;
	s_barrier
	ds_read_b128 v[74:77], v73
	ds_read_b128 v[78:81], v73 offset:1024
	ds_read_b128 v[82:85], v73 offset:2048
	ds_read_b128 v[86:89], v73 offset:3072
	ds_read_b128 v[90:93], v72 offset:32768
	ds_read_b128 v[94:97], v72 offset:33792
	ds_read_b128 v[98:101], v72 offset:34816
	ds_read_b128 v[102:105], v72 offset:35840
	ds_read_b128 v[106:109], v72 offset:36864
	ds_read_b128 v[110:113], v72 offset:37888
	ds_read_b128 v[114:117], v72 offset:38912
	ds_read_b128 v[118:121], v72 offset:39936
	ds_read_b128 v[122:125], v72 offset:49152
	ds_read_b128 v[126:129], v72 offset:50176
	ds_read_b128 v[130:133], v72 offset:51200
	ds_read_b128 v[134:137], v72 offset:52224
	ds_read_b128 v[138:141], v72 offset:53248
	ds_read_b128 v[142:145], v72 offset:54272
	ds_read_b128 v[146:149], v72 offset:55296
	ds_read_b128 v[150:153], v72 offset:56320
	s_add_u32 s82, s82, 0x10000
	s_addc_u32 s83, s83, 0
	s_mov_b32 m0, s53
	s_nop 0
	global_load_lds_dwordx4 v67, s[82:83]
	s_mov_b32 m0, s54
	s_nop 0
	global_load_lds_dwordx4 v69, s[82:83]
	s_waitcnt vmcnt(8)
	s_waitcnt lgkmcnt(0)
	s_barrier
	s_waitcnt lgkmcnt(14)
	v_mfma_f32_16x16x32_bf16 v[60:63], v[74:77], v[90:93], v[60:63]
	v_mfma_f32_16x16x32_bf16 v[56:59], v[82:85], v[90:93], v[56:59]
	s_waitcnt lgkmcnt(13)
	v_mfma_f32_16x16x32_bf16 v[52:55], v[74:77], v[98:101], v[52:55]
	v_mfma_f32_16x16x32_bf16 v[48:51], v[82:85], v[98:101], v[48:51]
	s_waitcnt lgkmcnt(11)
	v_mfma_f32_16x16x32_bf16 v[44:47], v[74:77], v[106:109], v[44:47]
	v_mfma_f32_16x16x32_bf16 v[40:43], v[82:85], v[106:109], v[40:43]
	s_waitcnt lgkmcnt(9)
	v_mfma_f32_16x16x32_bf16 v[36:39], v[74:77], v[114:117], v[36:39]
	v_mfma_f32_16x16x32_bf16 v[32:35], v[82:85], v[114:117], v[32:35]
	s_waitcnt lgkmcnt(7)
	v_mfma_f32_16x16x32_bf16 v[28:31], v[74:77], v[122:125], v[28:31]
	v_mfma_f32_16x16x32_bf16 v[24:27], v[82:85], v[122:125], v[24:27]
	s_waitcnt lgkmcnt(5)
	v_mfma_f32_16x16x32_bf16 v[20:23], v[74:77], v[130:133], v[20:23]
	v_mfma_f32_16x16x32_bf16 v[16:19], v[82:85], v[130:133], v[16:19]
	s_waitcnt lgkmcnt(3)
	v_mfma_f32_16x16x32_bf16 v[12:15], v[74:77], v[138:141], v[12:15]
	v_mfma_f32_16x16x32_bf16 v[8:11], v[82:85], v[138:141], v[8:11]
	s_waitcnt lgkmcnt(1)
	v_mfma_f32_16x16x32_bf16 v[4:7], v[74:77], v[146:149], v[4:7]
	v_mfma_f32_16x16x32_bf16 v[0:3], v[82:85], v[146:149], v[0:3]
	v_mfma_f32_16x16x32_bf16 v[60:63], v[78:81], v[94:97], v[60:63]
	v_mfma_f32_16x16x32_bf16 v[56:59], v[86:89], v[94:97], v[56:59]
	v_mfma_f32_16x16x32_bf16 v[52:55], v[78:81], v[102:105], v[52:55]
	v_mfma_f32_16x16x32_bf16 v[48:51], v[86:89], v[102:105], v[48:51]
	v_mfma_f32_16x16x32_bf16 v[44:47], v[78:81], v[110:113], v[44:47]
	v_mfma_f32_16x16x32_bf16 v[40:43], v[86:89], v[110:113], v[40:43]
	v_mfma_f32_16x16x32_bf16 v[36:39], v[78:81], v[118:121], v[36:39]
	v_mfma_f32_16x16x32_bf16 v[32:35], v[86:89], v[118:121], v[32:35]
	v_mfma_f32_16x16x32_bf16 v[28:31], v[78:81], v[126:129], v[28:31]
	v_mfma_f32_16x16x32_bf16 v[24:27], v[86:89], v[126:129], v[24:27]
	v_mfma_f32_16x16x32_bf16 v[20:23], v[78:81], v[134:137], v[20:23]
	v_mfma_f32_16x16x32_bf16 v[16:19], v[86:89], v[134:137], v[16:19]
	v_mfma_f32_16x16x32_bf16 v[12:15], v[78:81], v[142:145], v[12:15]
	v_mfma_f32_16x16x32_bf16 v[8:11], v[86:89], v[142:145], v[8:11]
	s_waitcnt lgkmcnt(0)
	v_mfma_f32_16x16x32_bf16 v[4:7], v[78:81], v[150:153], v[4:7]
	v_mfma_f32_16x16x32_bf16 v[0:3], v[86:89], v[150:153], v[0:3]
	s_barrier
	s_mov_b32 m0, s56
	s_nop 0
	global_load_lds_dwordx4 v67, s[80:81]
	s_mov_b32 m0, s57
	s_nop 0
	global_load_lds_dwordx4 v69, s[80:81]
	s_mov_b32 m0, s58
	s_nop 0
	global_load_lds_dwordx4 v66, s[42:43]
	s_mov_b32 m0, s59
	s_nop 0
	global_load_lds_dwordx4 v68, s[42:43]
	s_add_u32 s38, s38, 0x18080
	s_addc_u32 s39, s39, 0
	s_mov_b32 m0, s60
	s_nop 0
	global_load_lds_dwordx4 v66, s[38:39]
	s_mov_b32 m0, s61
	s_nop 0
	global_load_lds_dwordx4 v68, s[38:39]
	s_waitcnt vmcnt(8)
	s_waitcnt lgkmcnt(0)
	s_barrier
	s_barrier
	s_add_u32 s67, s67, 0x100
	s_addc_u32 s68, s68, 0
	s_add_u32 s69, s69, 0x100
	s_addc_u32 s84, s84, 0
	s_cmp_ge_i32 s85, s55
	s_mov_b32 s38, s85
	s_cbranch_scc0 .LBB0_662

; #define PG8_STAGE(bufoff, gbase, voff) do { _Pragma("unroll") for (int _i = 0; _i < 2; ++_i) { \
;         const unsigned _m0 = ldsu + (unsigned)(bufoff) + ldsw + (unsigned)(_i * 8192); \
;         asm volatile("s_mov_b32 m0, %2\n\ts_nop 0\n\tglobal_load_lds_dwordx4 %0, %1" :: "v"((voff)[_i]), "s"((const char*)(gbase)), "s"(_m0) : "memory"); } } while (0)
; #define PG8_LDA(dst, b, h) do { _Pragma("unroll") for (int m = 0; m < 4; ++m) _Pragma("unroll") for (int k = 0; k < 2; ++k) dst[m][k] = *(const LAS bf16x8*)(lds + PG8_SA(b, h) + aoff + m * 2048 + k * 1024); } while (0)
; #define PG8_LDB(dst, b, h) do { _Pragma("unroll") for (int n = 0; n < 2; ++n) _Pragma("unroll") for (int k = 0; k < 2; ++k) dst[n][k] = *(const LAS bf16x8*)(lds + bbase[b][h] + n * 2048 + k * 1024); } while (0)
; #define PG8_WAIT_V(n) asm volatile("s_waitcnt vmcnt(" #n ")" ::: "memory")
; #define PG8_WAIT_L(n) asm volatile("s_waitcnt lgkmcnt(" #n ")" ::: "memory")
; #define PG8_BAR __builtin_amdgcn_s_barrier()
; #define PG8_SCHED __builtin_amdgcn_sched_barrier(0)
; template <class Epi>
; __device__ __forceinline__ void gemm_phase(LAS unsigned char* lds, const Gemm g, const StaticOrder& S, const Epi& E) {
;     ...
;             PG8_LDB(B0, 0, 0); PG8_SCHED; PG8_LDA(At, 0, 0); PG8_LDA(At2, 0, 1); PG8_STAGE(PG8_SB(1, 1), b1 + hstepB, voffB);
;             PG8_WAIT_V(8); PG8_WAIT_L(0); PG8_BAR; PG8_MMA2B(0, At, At2, B0); PG8_BAR; PG8_SCHED;
;             PG8_LDB(B0, 0, 1); PG8_STAGE(PG8_SB(0, 0), b2, voffB); PG8_STAGE(PG8_SA(0, 0), a2, voffA); PG8_STAGE(PG8_SA(0, 1), a2 + hstepA, voffA);
;             PG8_WAIT_V(8); PG8_WAIT_L(0); PG8_BAR; PG8_MMA2B(1, At, At2, B0); PG8_BAR; PG8_SCHED;
.LBB0_797:
	s_add_i32 s52, s4, 2
	s_add_u32 s38, s1, 0x80
	ds_read_b128 v[128:131], v153
	ds_read_b128 v[132:135], v153 offset:1024
	ds_read_b128 v[142:145], v153 offset:2048
	ds_read_b128 v[178:181], v153 offset:3072
	s_addc_u32 s39, s43, 0
	s_cmp_eq_u32 s47, s4
	s_cselect_b32 s4, s16, s50
	s_cselect_b32 s5, s17, s51
	s_cselect_b32 s82, s10, s38
	s_cselect_b32 s83, s11, s39
	s_add_u32 s38, s4, 0x80
	s_addc_u32 s39, s5, 0
	s_add_u32 s80, s82, 0x80
	s_addc_u32 s81, s83, 0
	ds_read_b128 v[182:185], v154
	ds_read_b128 v[186:189], v154 offset:1024
	ds_read_b128 v[190:193], v154 offset:2048
	ds_read_b128 v[194:197], v154 offset:3072
	ds_read_b128 v[198:201], v154 offset:4096
	ds_read_b128 v[202:205], v154 offset:5120
	ds_read_b128 v[214:217], v154 offset:6144
	ds_read_b128 v[218:221], v154 offset:7168
	ds_read_b128 v[222:225], v154 offset:16384
	ds_read_b128 v[226:229], v154 offset:17408
	ds_read_b128 v[230:233], v154 offset:18432
	ds_read_b128 v[234:237], v154 offset:19456
	ds_read_b128 v[238:241], v154 offset:20480
	ds_read_b128 v[242:245], v154 offset:21504
	ds_read_b128 v[246:249], v154 offset:22528
	ds_read_b128 v[166:169], v154 offset:23552
	s_add_u32 s54, s1, 0x18000
	s_addc_u32 s55, s43, 0
	s_mov_b32 m0, s87
	s_nop 0
	global_load_lds_dwordx4 v147, s[54:55]
	s_mov_b32 m0, s28
	s_nop 0
	global_load_lds_dwordx4 v149, s[54:55]
	s_waitcnt vmcnt(8)
	s_waitcnt lgkmcnt(0)
	s_barrier
	s_waitcnt lgkmcnt(14)
	v_mfma_f32_16x16x32_bf16 v[124:127], v[128:131], v[182:185], v[124:127]
	v_mfma_f32_16x16x32_bf16 v[120:123], v[142:145], v[182:185], v[120:123]
	s_waitcnt lgkmcnt(13)
	v_mfma_f32_16x16x32_bf16 v[108:111], v[128:131], v[190:193], v[108:111]
	v_mfma_f32_16x16x32_bf16 v[104:107], v[142:145], v[190:193], v[104:107]
	s_waitcnt lgkmcnt(11)
	v_mfma_f32_16x16x32_bf16 v[92:95], v[128:131], v[198:201], v[92:95]
	v_mfma_f32_16x16x32_bf16 v[88:91], v[142:145], v[198:201], v[88:91]
	s_waitcnt lgkmcnt(9)
	v_mfma_f32_16x16x32_bf16 v[76:79], v[128:131], v[214:217], v[76:79]
	v_mfma_f32_16x16x32_bf16 v[72:75], v[142:145], v[214:217], v[72:75]
	s_waitcnt lgkmcnt(7)
	v_mfma_f32_16x16x32_bf16 v[60:63], v[128:131], v[222:225], v[60:63]
	v_mfma_f32_16x16x32_bf16 v[56:59], v[142:145], v[222:225], v[56:59]
	s_waitcnt lgkmcnt(5)
	v_mfma_f32_16x16x32_bf16 v[44:47], v[128:131], v[230:233], v[44:47]
	v_mfma_f32_16x16x32_bf16 v[40:43], v[142:145], v[230:233], v[40:43]
	s_waitcnt lgkmcnt(3)
	v_mfma_f32_16x16x32_bf16 v[28:31], v[128:131], v[238:241], v[28:31]
	v_mfma_f32_16x16x32_bf16 v[24:27], v[142:145], v[238:241], v[24:27]
	s_waitcnt lgkmcnt(1)
	v_mfma_f32_16x16x32_bf16 v[12:15], v[128:131], v[246:249], v[12:15]
	v_mfma_f32_16x16x32_bf16 v[8:11], v[142:145], v[246:249], v[8:11]
	v_mfma_f32_16x16x32_bf16 v[124:127], v[132:135], v[186:189], v[124:127]
	v_mfma_f32_16x16x32_bf16 v[120:123], v[178:181], v[186:189], v[120:123]
	v_mfma_f32_16x16x32_bf16 v[108:111], v[132:135], v[194:197], v[108:111]
	v_mfma_f32_16x16x32_bf16 v[104:107], v[178:181], v[194:197], v[104:107]
	v_mfma_f32_16x16x32_bf16 v[92:95], v[132:135], v[202:205], v[92:95]
	v_mfma_f32_16x16x32_bf16 v[88:91], v[178:181], v[202:205], v[88:91]
	v_mfma_f32_16x16x32_bf16 v[76:79], v[132:135], v[218:221], v[76:79]
	v_mfma_f32_16x16x32_bf16 v[72:75], v[178:181], v[218:221], v[72:75]
	v_mfma_f32_16x16x32_bf16 v[60:63], v[132:135], v[226:229], v[60:63]
	v_mfma_f32_16x16x32_bf16 v[56:59], v[178:181], v[226:229], v[56:59]
	v_mfma_f32_16x16x32_bf16 v[44:47], v[132:135], v[234:237], v[44:47]
	v_mfma_f32_16x16x32_bf16 v[40:43], v[178:181], v[234:237], v[40:43]
	v_mfma_f32_16x16x32_bf16 v[28:31], v[132:135], v[242:245], v[28:31]
	v_mfma_f32_16x16x32_bf16 v[24:27], v[178:181], v[242:245], v[24:27]
	s_waitcnt lgkmcnt(0)
	v_mfma_f32_16x16x32_bf16 v[12:15], v[132:135], v[166:169], v[12:15]
	v_mfma_f32_16x16x32_bf16 v[8:11], v[178:181], v[166:169], v[8:11]
	s_barrier
	ds_read_b128 v[128:131], v155
	ds_read_b128 v[132:135], v155 offset:1024
	ds_read_b128 v[142:145], v155 offset:2048
	ds_read_b128 v[178:181], v155 offset:3072
	s_mov_b32 m0, s90
	s_nop 0
	global_load_lds_dwordx4 v147, s[82:83]
	s_mov_b32 m0, s91
	s_nop 0
	global_load_lds_dwordx4 v149, s[82:83]
	s_mov_b32 m0, s85
	s_nop 0
	global_load_lds_dwordx4 v146, s[4:5]
	s_mov_b32 m0, s95
	s_nop 0
	global_load_lds_dwordx4 v148, s[4:5]
	s_add_u32 s54, s4, 0x18000
	s_addc_u32 s55, s5, 0
	s_mov_b32 m0, s96
	s_nop 0
	global_load_lds_dwordx4 v146, s[54:55]
	s_mov_b32 m0, s97
	s_nop 0
	global_load_lds_dwordx4 v148, s[54:55]
	s_waitcnt vmcnt(8)
	s_waitcnt lgkmcnt(0)
	s_barrier
; #define PG8_STAGE(bufoff, gbase, voff) do { _Pragma("unroll") for (int _i = 0; _i < 2; ++_i) { \
;         const unsigned _m0 = ldsu + (unsigned)(bufoff) + ldsw + (unsigned)(_i * 8192); \
;         asm volatile("s_mov_b32 m0, %2\n\ts_nop 0\n\tglobal_load_lds_dwordx4 %0, %1" :: "v"((voff)[_i]), "s"((const char*)(gbase)), "s"(_m0) : "memory"); } } while (0)
; #define PG8_LDA(dst, b, h) do { _Pragma("unroll") for (int m = 0; m < 4; ++m) _Pragma("unroll") for (int k = 0; k < 2; ++k) dst[m][k] = *(const LAS bf16x8*)(lds + PG8_SA(b, h) + aoff + m * 2048 + k * 1024); } while (0)
; #define PG8_LDB(dst, b, h) do { _Pragma("unroll") for (int n = 0; n < 2; ++n) _Pragma("unroll") for (int k = 0; k < 2; ++k) dst[n][k] = *(const LAS bf16x8*)(lds + bbase[b][h] + n * 2048 + k * 1024); } while (0)
; #define PG8_WAIT_V(n) asm volatile("s_waitcnt vmcnt(" #n ")" ::: "memory")
; #define PG8_WAIT_L(n) asm volatile("s_waitcnt lgkmcnt(" #n ")" ::: "memory")
; #define PG8_BAR __builtin_amdgcn_s_barrier()
; #define PG8_SCHED __builtin_amdgcn_sched_barrier(0)
; template <class Epi>
; __device__ __forceinline__ void gemm_phase(LAS unsigned char* lds, const Gemm g, const StaticOrder& S, const Epi& E) {
;     ...
;             PG8_WAIT_V(8); PG8_WAIT_L(0); PG8_BAR; PG8_MMA2B(1, At, At2, B0); PG8_BAR; PG8_SCHED;
;             PG8_LDB(B0, 1, 0); PG8_SCHED; PG8_LDA(At, 1, 0); PG8_LDA(At2, 1, 1); PG8_STAGE(PG8_SB(0, 1), b2 + hstepB, voffB);
;             PG8_WAIT_V(8); PG8_WAIT_L(0); PG8_BAR; PG8_MMA2B(0, At, At2, B0); PG8_BAR; PG8_SCHED;
	s_waitcnt lgkmcnt(3)
	v_mfma_f32_16x16x32_bf16 v[116:119], v[128:131], v[182:185], v[116:119]
	s_waitcnt lgkmcnt(1)
	v_mfma_f32_16x16x32_bf16 v[112:115], v[142:145], v[182:185], v[112:115]
	v_mfma_f32_16x16x32_bf16 v[100:103], v[128:131], v[190:193], v[100:103]
	v_mfma_f32_16x16x32_bf16 v[96:99], v[142:145], v[190:193], v[96:99]
	v_mfma_f32_16x16x32_bf16 v[84:87], v[128:131], v[198:201], v[84:87]
	v_mfma_f32_16x16x32_bf16 v[80:83], v[142:145], v[198:201], v[80:83]
	v_mfma_f32_16x16x32_bf16 v[68:71], v[128:131], v[214:217], v[68:71]
	v_mfma_f32_16x16x32_bf16 v[64:67], v[142:145], v[214:217], v[64:67]
	v_mfma_f32_16x16x32_bf16 v[52:55], v[128:131], v[222:225], v[52:55]
	v_mfma_f32_16x16x32_bf16 v[48:51], v[142:145], v[222:225], v[48:51]
	v_mfma_f32_16x16x32_bf16 v[36:39], v[128:131], v[230:233], v[36:39]
	v_mfma_f32_16x16x32_bf16 v[32:35], v[142:145], v[230:233], v[32:35]
	v_mfma_f32_16x16x32_bf16 v[20:23], v[128:131], v[238:241], v[20:23]
	v_mfma_f32_16x16x32_bf16 v[16:19], v[142:145], v[238:241], v[16:19]
	v_mfma_f32_16x16x32_bf16 v[4:7], v[128:131], v[246:249], v[4:7]
	v_mfma_f32_16x16x32_bf16 v[0:3], v[142:145], v[246:249], v[0:3]
	v_mfma_f32_16x16x32_bf16 v[116:119], v[132:135], v[186:189], v[116:119]
	s_waitcnt lgkmcnt(0)
	v_mfma_f32_16x16x32_bf16 v[112:115], v[178:181], v[186:189], v[112:115]
	v_mfma_f32_16x16x32_bf16 v[100:103], v[132:135], v[194:197], v[100:103]
	v_mfma_f32_16x16x32_bf16 v[96:99], v[178:181], v[194:197], v[96:99]
	v_mfma_f32_16x16x32_bf16 v[84:87], v[132:135], v[202:205], v[84:87]
	v_mfma_f32_16x16x32_bf16 v[80:83], v[178:181], v[202:205], v[80:83]
	v_mfma_f32_16x16x32_bf16 v[68:71], v[132:135], v[218:221], v[68:71]
	v_mfma_f32_16x16x32_bf16 v[64:67], v[178:181], v[218:221], v[64:67]
	v_mfma_f32_16x16x32_bf16 v[52:55], v[132:135], v[226:229], v[52:55]
	v_mfma_f32_16x16x32_bf16 v[48:51], v[178:181], v[226:229], v[48:51]
	v_mfma_f32_16x16x32_bf16 v[36:39], v[132:135], v[234:237], v[36:39]
	v_mfma_f32_16x16x32_bf16 v[32:35], v[178:181], v[234:237], v[32:35]
	v_mfma_f32_16x16x32_bf16 v[20:23], v[132:135], v[242:245], v[20:23]
	v_mfma_f32_16x16x32_bf16 v[16:19], v[178:181], v[242:245], v[16:19]
	v_mfma_f32_16x16x32_bf16 v[4:7], v[132:135], v[166:169], v[4:7]
	v_mfma_f32_16x16x32_bf16 v[0:3], v[178:181], v[166:169], v[0:3]
	s_barrier
	ds_read_b128 v[128:131], v156
	ds_read_b128 v[132:135], v156 offset:1024
	ds_read_b128 v[142:145], v156 offset:2048
	ds_read_b128 v[166:169], v156 offset:3072
	ds_read_b128 v[178:181], v154 offset:32768
	ds_read_b128 v[182:185], v154 offset:33792
	ds_read_b128 v[186:189], v154 offset:34816
	ds_read_b128 v[190:193], v154 offset:35840
	ds_read_b128 v[194:197], v154 offset:36864
	ds_read_b128 v[198:201], v154 offset:37888
	ds_read_b128 v[202:205], v154 offset:38912
	ds_read_b128 v[214:217], v154 offset:39936
	ds_read_b128 v[218:221], v154 offset:49152
	ds_read_b128 v[222:225], v154 offset:50176
	ds_read_b128 v[226:229], v154 offset:51200
	ds_read_b128 v[230:233], v154 offset:52224
	ds_read_b128 v[234:237], v154 offset:53248
	ds_read_b128 v[238:241], v154 offset:54272
	ds_read_b128 v[242:245], v154 offset:55296
	ds_read_b128 v[246:249], v154 offset:56320
	s_add_u32 s54, s82, 0x18000
	s_addc_u32 s55, s83, 0
	s_mov_b32 m0, s6
	s_nop 0
	global_load_lds_dwordx4 v147, s[54:55]
	s_mov_b32 m0, s7
	s_nop 0
	global_load_lds_dwordx4 v149, s[54:55]
	s_waitcnt vmcnt(8)
	s_waitcnt lgkmcnt(0)
	s_barrier
; #define PG8_STAGE(bufoff, gbase, voff) do { _Pragma("unroll") for (int _i = 0; _i < 2; ++_i) { \
;         const unsigned _m0 = ldsu + (unsigned)(bufoff) + ldsw + (unsigned)(_i * 8192); \
;         asm volatile("s_mov_b32 m0, %2\n\ts_nop 0\n\tglobal_load_lds_dwordx4 %0, %1" :: "v"((voff)[_i]), "s"((const char*)(gbase)), "s"(_m0) : "memory"); } } while (0)
; #define PG8_LDB(dst, b, h) do { _Pragma("unroll") for (int n = 0; n < 2; ++n) _Pragma("unroll") for (int k = 0; k < 2; ++k) dst[n][k] = *(const LAS bf16x8*)(lds + bbase[b][h] + n * 2048 + k * 1024); } while (0)
; #define PG8_WAIT_V(n) asm volatile("s_waitcnt vmcnt(" #n ")" ::: "memory")
; #define PG8_WAIT_L(n) asm volatile("s_waitcnt lgkmcnt(" #n ")" ::: "memory")
; #define PG8_BAR __builtin_amdgcn_s_barrier()
; #define PG8_SCHED __builtin_amdgcn_sched_barrier(0)
; template <class Epi>
; __device__ __forceinline__ void gemm_phase(LAS unsigned char* lds, const Gemm g, const StaticOrder& S, const Epi& E) {
;     ...
;             PG8_WAIT_V(8); PG8_WAIT_L(0); PG8_BAR; PG8_MMA2B(0, At, At2, B0); PG8_BAR; PG8_SCHED;
;             PG8_LDB(B0, 1, 1); PG8_STAGE(PG8_SB(1, 0), b3, voffB); PG8_STAGE(PG8_SA(1, 0), a3, voffA); PG8_STAGE(PG8_SA(1, 1), a3 + hstepA, voffA);
;             PG8_WAIT_V(8); PG8_WAIT_L(0); PG8_BAR; PG8_MMA2B(1, At, At2, B0); PG8_BAR; PG8_SCHED;
;         }
	s_waitcnt lgkmcnt(14)
	v_mfma_f32_16x16x32_bf16 v[124:127], v[128:131], v[178:181], v[124:127]
	v_mfma_f32_16x16x32_bf16 v[120:123], v[142:145], v[178:181], v[120:123]
	s_waitcnt lgkmcnt(13)
	v_mfma_f32_16x16x32_bf16 v[108:111], v[128:131], v[186:189], v[108:111]
	v_mfma_f32_16x16x32_bf16 v[104:107], v[142:145], v[186:189], v[104:107]
	s_waitcnt lgkmcnt(11)
	v_mfma_f32_16x16x32_bf16 v[92:95], v[128:131], v[194:197], v[92:95]
	v_mfma_f32_16x16x32_bf16 v[88:91], v[142:145], v[194:197], v[88:91]
	s_waitcnt lgkmcnt(9)
	v_mfma_f32_16x16x32_bf16 v[76:79], v[128:131], v[202:205], v[76:79]
	v_mfma_f32_16x16x32_bf16 v[72:75], v[142:145], v[202:205], v[72:75]
	s_waitcnt lgkmcnt(7)
	v_mfma_f32_16x16x32_bf16 v[60:63], v[128:131], v[218:221], v[60:63]
	v_mfma_f32_16x16x32_bf16 v[56:59], v[142:145], v[218:221], v[56:59]
	s_waitcnt lgkmcnt(5)
	v_mfma_f32_16x16x32_bf16 v[44:47], v[128:131], v[226:229], v[44:47]
	v_mfma_f32_16x16x32_bf16 v[40:43], v[142:145], v[226:229], v[40:43]
	s_waitcnt lgkmcnt(3)
	v_mfma_f32_16x16x32_bf16 v[28:31], v[128:131], v[234:237], v[28:31]
	v_mfma_f32_16x16x32_bf16 v[24:27], v[142:145], v[234:237], v[24:27]
	s_waitcnt lgkmcnt(1)
	v_mfma_f32_16x16x32_bf16 v[12:15], v[128:131], v[242:245], v[12:15]
	v_mfma_f32_16x16x32_bf16 v[8:11], v[142:145], v[242:245], v[8:11]
	v_mfma_f32_16x16x32_bf16 v[124:127], v[132:135], v[182:185], v[124:127]
	v_mfma_f32_16x16x32_bf16 v[120:123], v[166:169], v[182:185], v[120:123]
	v_mfma_f32_16x16x32_bf16 v[108:111], v[132:135], v[190:193], v[108:111]
	v_mfma_f32_16x16x32_bf16 v[104:107], v[166:169], v[190:193], v[104:107]
	v_mfma_f32_16x16x32_bf16 v[92:95], v[132:135], v[198:201], v[92:95]
	v_mfma_f32_16x16x32_bf16 v[88:91], v[166:169], v[198:201], v[88:91]
	v_mfma_f32_16x16x32_bf16 v[76:79], v[132:135], v[214:217], v[76:79]
	v_mfma_f32_16x16x32_bf16 v[72:75], v[166:169], v[214:217], v[72:75]
	v_mfma_f32_16x16x32_bf16 v[60:63], v[132:135], v[222:225], v[60:63]
	v_mfma_f32_16x16x32_bf16 v[56:59], v[166:169], v[222:225], v[56:59]
	v_mfma_f32_16x16x32_bf16 v[44:47], v[132:135], v[230:233], v[44:47]
	v_mfma_f32_16x16x32_bf16 v[40:43], v[166:169], v[230:233], v[40:43]
	v_mfma_f32_16x16x32_bf16 v[28:31], v[132:135], v[238:241], v[28:31]
	v_mfma_f32_16x16x32_bf16 v[24:27], v[166:169], v[238:241], v[24:27]
	s_waitcnt lgkmcnt(0)
	v_mfma_f32_16x16x32_bf16 v[12:15], v[132:135], v[246:249], v[12:15]
	v_mfma_f32_16x16x32_bf16 v[8:11], v[166:169], v[246:249], v[8:11]
	s_barrier
	ds_read_b128 v[128:131], v157
	ds_read_b128 v[132:135], v157 offset:1024
	ds_read_b128 v[142:145], v157 offset:2048
	ds_read_b128 v[166:169], v157 offset:3072
	s_mov_b32 m0, s2
	s_nop 0
	global_load_lds_dwordx4 v147, s[80:81]
	s_mov_b32 m0, s3
	s_nop 0
	global_load_lds_dwordx4 v149, s[80:81]
	s_mov_b32 m0, s88
	s_nop 0
	global_load_lds_dwordx4 v146, s[38:39]
	s_mov_b32 m0, s89
	s_nop 0
	global_load_lds_dwordx4 v148, s[38:39]
	s_add_u32 s4, s4, 0x18080
	s_addc_u32 s5, s5, 0
	s_mov_b32 m0, s37
	s_nop 0
	global_load_lds_dwordx4 v146, s[4:5]
	s_mov_b32 m0, s84
	s_nop 0
	global_load_lds_dwordx4 v148, s[4:5]
	s_waitcnt vmcnt(8)
	s_waitcnt lgkmcnt(0)
	s_barrier
	s_waitcnt lgkmcnt(3)
	v_mfma_f32_16x16x32_bf16 v[116:119], v[128:131], v[178:181], v[116:119]
	s_waitcnt lgkmcnt(1)
	v_mfma_f32_16x16x32_bf16 v[112:115], v[142:145], v[178:181], v[112:115]
	v_mfma_f32_16x16x32_bf16 v[100:103], v[128:131], v[186:189], v[100:103]
	v_mfma_f32_16x16x32_bf16 v[96:99], v[142:145], v[186:189], v[96:99]
	v_mfma_f32_16x16x32_bf16 v[84:87], v[128:131], v[194:197], v[84:87]
	v_mfma_f32_16x16x32_bf16 v[80:83], v[142:145], v[194:197], v[80:83]
	v_mfma_f32_16x16x32_bf16 v[68:71], v[128:131], v[202:205], v[68:71]
	v_mfma_f32_16x16x32_bf16 v[64:67], v[142:145], v[202:205], v[64:67]
	v_mfma_f32_16x16x32_bf16 v[52:55], v[128:131], v[218:221], v[52:55]
	v_mfma_f32_16x16x32_bf16 v[48:51], v[142:145], v[218:221], v[48:51]
	v_mfma_f32_16x16x32_bf16 v[36:39], v[128:131], v[226:229], v[36:39]
	v_mfma_f32_16x16x32_bf16 v[32:35], v[142:145], v[226:229], v[32:35]
	v_mfma_f32_16x16x32_bf16 v[20:23], v[128:131], v[234:237], v[20:23]
	v_mfma_f32_16x16x32_bf16 v[16:19], v[142:145], v[234:237], v[16:19]
	v_mfma_f32_16x16x32_bf16 v[4:7], v[128:131], v[242:245], v[4:7]
	v_mfma_f32_16x16x32_bf16 v[0:3], v[142:145], v[242:245], v[0:3]
	v_mfma_f32_16x16x32_bf16 v[116:119], v[132:135], v[182:185], v[116:119]
	s_waitcnt lgkmcnt(0)
	v_mfma_f32_16x16x32_bf16 v[112:115], v[166:169], v[182:185], v[112:115]
	v_mfma_f32_16x16x32_bf16 v[100:103], v[132:135], v[190:193], v[100:103]
	v_mfma_f32_16x16x32_bf16 v[96:99], v[166:169], v[190:193], v[96:99]
	v_mfma_f32_16x16x32_bf16 v[84:87], v[132:135], v[198:201], v[84:87]
	v_mfma_f32_16x16x32_bf16 v[80:83], v[166:169], v[198:201], v[80:83]
	v_mfma_f32_16x16x32_bf16 v[68:71], v[132:135], v[214:217], v[68:71]
	v_mfma_f32_16x16x32_bf16 v[64:67], v[166:169], v[214:217], v[64:67]
	v_mfma_f32_16x16x32_bf16 v[52:55], v[132:135], v[222:225], v[52:55]
	v_mfma_f32_16x16x32_bf16 v[48:51], v[166:169], v[222:225], v[48:51]
	v_mfma_f32_16x16x32_bf16 v[36:39], v[132:135], v[230:233], v[36:39]
	v_mfma_f32_16x16x32_bf16 v[32:35], v[166:169], v[230:233], v[32:35]
	v_mfma_f32_16x16x32_bf16 v[20:23], v[132:135], v[238:241], v[20:23]
	v_mfma_f32_16x16x32_bf16 v[16:19], v[166:169], v[238:241], v[16:19]
	v_mfma_f32_16x16x32_bf16 v[4:7], v[132:135], v[246:249], v[4:7]
	v_mfma_f32_16x16x32_bf16 v[0:3], v[166:169], v[246:249], v[0:3]
	s_barrier
	s_add_u32 s1, s1, 0x100
	s_addc_u32 s43, s43, 0
	s_add_u32 s50, s50, 0x100
	s_addc_u32 s51, s51, 0
	s_cmp_ge_i32 s52, s86
	s_mov_b32 s4, s52
	s_cbranch_scc0 .LBB0_797
	v_readlane_b32 s52, v252, 7
	v_readlane_b32 s54, v254, 61
	v_readlane_b32 s53, v252, 8
	v_readlane_b32 s55, v254, 62
	v_mov_b32_e32 v246, v141

; #define PG8_STAGE(bufoff, gbase, voff) do { _Pragma("unroll") for (int _i = 0; _i < 2; ++_i) { \
;         const unsigned _m0 = ldsu + (unsigned)(bufoff) + ldsw + (unsigned)(_i * 8192); \
;         asm volatile("s_mov_b32 m0, %2\n\ts_nop 0\n\tglobal_load_lds_dwordx4 %0, %1" :: "v"((voff)[_i]), "s"((const char*)(gbase)), "s"(_m0) : "memory"); } } while (0)
; #define PG8_LDA(dst, b, h) do { _Pragma("unroll") for (int m = 0; m < 4; ++m) _Pragma("unroll") for (int k = 0; k < 2; ++k) dst[m][k] = *(const LAS bf16x8*)(lds + PG8_SA(b, h) + aoff + m * 2048 + k * 1024); } while (0)
; #define PG8_LDB(dst, b, h) do { _Pragma("unroll") for (int n = 0; n < 2; ++n) _Pragma("unroll") for (int k = 0; k < 2; ++k) dst[n][k] = *(const LAS bf16x8*)(lds + bbase[b][h] + n * 2048 + k * 1024); } while (0)
; #define PG8_WAIT_V(n) asm volatile("s_waitcnt vmcnt(" #n ")" ::: "memory")
; #define PG8_WAIT_L(n) asm volatile("s_waitcnt lgkmcnt(" #n ")" ::: "memory")
; #define PG8_BAR __builtin_amdgcn_s_barrier()
; #define PG8_SCHED __builtin_amdgcn_sched_barrier(0)
; template <class Epi>
; __device__ __forceinline__ void gemm_phase(LAS unsigned char* lds, const Gemm g, const StaticOrder& S, const Epi& E) {
;     ...
;             PG8_LDB(B0, 0, 0); PG8_SCHED; PG8_LDA(At, 0, 0); PG8_LDA(At2, 0, 1); PG8_STAGE(PG8_SB(1, 1), b1 + hstepB, voffB);
;             PG8_WAIT_V(8); PG8_WAIT_L(0); PG8_BAR; PG8_MMA2B(0, At, At2, B0); PG8_BAR; PG8_SCHED;
;             PG8_LDB(B0, 0, 1); PG8_STAGE(PG8_SB(0, 0), b2, voffB); PG8_STAGE(PG8_SA(0, 0), a2, voffA); PG8_STAGE(PG8_SA(0, 1), a2 + hstepA, voffA);
;             PG8_WAIT_V(8); PG8_WAIT_L(0); PG8_BAR; PG8_MMA2B(1, At, At2, B0); PG8_BAR; PG8_SCHED;
.LBB0_870:
	ds_read_b128 v[128:131], v140
	ds_read_b128 v[146:149], v140 offset:1024
	ds_read_b128 v[150:153], v140 offset:2048
	ds_read_b128 v[154:157], v140 offset:3072
	s_add_u32 s38, s16, 0x100
	s_addc_u32 s39, s17, 0
	s_cmp_eq_u32 s68, 4
	s_cselect_b32 s42, s65, s67
	s_cselect_b32 s43, s11, s84
	s_cselect_b32 s82, s66, s38
	s_cselect_b32 s83, s9, s39
	s_add_u32 s80, s42, 0x80
	s_addc_u32 s81, s43, 0
	ds_read_b128 v[166:169], v141
	ds_read_b128 v[178:181], v141 offset:1024
	ds_read_b128 v[182:185], v141 offset:2048
	ds_read_b128 v[186:189], v141 offset:3072
	ds_read_b128 v[190:193], v141 offset:4096
	ds_read_b128 v[194:197], v141 offset:5120
	ds_read_b128 v[198:201], v141 offset:6144
	ds_read_b128 v[202:205], v141 offset:7168
	ds_read_b128 v[214:217], v141 offset:16384
	ds_read_b128 v[218:221], v141 offset:17408
	ds_read_b128 v[222:225], v141 offset:18432
	ds_read_b128 v[226:229], v141 offset:19456
	ds_read_b128 v[230:233], v141 offset:20480
	ds_read_b128 v[234:237], v141 offset:21504
	ds_read_b128 v[238:241], v141 offset:22528
	ds_read_b128 v[242:245], v141 offset:23552
	s_add_u32 s16, s16, 0x20080
	s_addc_u32 s17, s17, 0
	s_mov_b32 m0, s60
	s_nop 0
	global_load_lds_dwordx4 v135, s[16:17]
	s_mov_b32 m0, s61
	s_nop 0
	global_load_lds_dwordx4 v137, s[16:17]
	s_waitcnt vmcnt(8)
	s_waitcnt lgkmcnt(0)
	s_barrier
	s_waitcnt lgkmcnt(14)
	v_mfma_f32_16x16x32_bf16 v[124:127], v[128:131], v[166:169], v[124:127]
	v_mfma_f32_16x16x32_bf16 v[120:123], v[150:153], v[166:169], v[120:123]
	s_waitcnt lgkmcnt(13)
	v_mfma_f32_16x16x32_bf16 v[108:111], v[128:131], v[182:185], v[108:111]
	v_mfma_f32_16x16x32_bf16 v[104:107], v[150:153], v[182:185], v[104:107]
	s_waitcnt lgkmcnt(11)
	v_mfma_f32_16x16x32_bf16 v[92:95], v[128:131], v[190:193], v[92:95]
	v_mfma_f32_16x16x32_bf16 v[88:91], v[150:153], v[190:193], v[88:91]
	s_waitcnt lgkmcnt(9)
	v_mfma_f32_16x16x32_bf16 v[76:79], v[128:131], v[198:201], v[76:79]
	v_mfma_f32_16x16x32_bf16 v[72:75], v[150:153], v[198:201], v[72:75]
	s_waitcnt lgkmcnt(7)
	v_mfma_f32_16x16x32_bf16 v[60:63], v[128:131], v[214:217], v[60:63]
	v_mfma_f32_16x16x32_bf16 v[56:59], v[150:153], v[214:217], v[56:59]
	s_waitcnt lgkmcnt(5)
	v_mfma_f32_16x16x32_bf16 v[44:47], v[128:131], v[222:225], v[44:47]
	v_mfma_f32_16x16x32_bf16 v[40:43], v[150:153], v[222:225], v[40:43]
	s_waitcnt lgkmcnt(3)
	v_mfma_f32_16x16x32_bf16 v[28:31], v[128:131], v[230:233], v[28:31]
	v_mfma_f32_16x16x32_bf16 v[24:27], v[150:153], v[230:233], v[24:27]
	s_waitcnt lgkmcnt(1)
	v_mfma_f32_16x16x32_bf16 v[12:15], v[128:131], v[238:241], v[12:15]
	v_mfma_f32_16x16x32_bf16 v[8:11], v[150:153], v[238:241], v[8:11]
	v_mfma_f32_16x16x32_bf16 v[124:127], v[146:149], v[178:181], v[124:127]
	v_mfma_f32_16x16x32_bf16 v[120:123], v[154:157], v[178:181], v[120:123]
	v_mfma_f32_16x16x32_bf16 v[108:111], v[146:149], v[186:189], v[108:111]
	v_mfma_f32_16x16x32_bf16 v[104:107], v[154:157], v[186:189], v[104:107]
	v_mfma_f32_16x16x32_bf16 v[92:95], v[146:149], v[194:197], v[92:95]
	v_mfma_f32_16x16x32_bf16 v[88:91], v[154:157], v[194:197], v[88:91]
	v_mfma_f32_16x16x32_bf16 v[76:79], v[146:149], v[202:205], v[76:79]
	v_mfma_f32_16x16x32_bf16 v[72:75], v[154:157], v[202:205], v[72:75]
	v_mfma_f32_16x16x32_bf16 v[60:63], v[146:149], v[218:221], v[60:63]
	v_mfma_f32_16x16x32_bf16 v[56:59], v[154:157], v[218:221], v[56:59]
	v_mfma_f32_16x16x32_bf16 v[44:47], v[146:149], v[226:229], v[44:47]
	v_mfma_f32_16x16x32_bf16 v[40:43], v[154:157], v[226:229], v[40:43]
	v_mfma_f32_16x16x32_bf16 v[28:31], v[146:149], v[234:237], v[28:31]
	v_mfma_f32_16x16x32_bf16 v[24:27], v[154:157], v[234:237], v[24:27]
	s_waitcnt lgkmcnt(0)
	v_mfma_f32_16x16x32_bf16 v[12:15], v[146:149], v[242:245], v[12:15]
	v_mfma_f32_16x16x32_bf16 v[8:11], v[154:157], v[242:245], v[8:11]
	s_barrier
	ds_read_b128 v[128:131], v142
	ds_read_b128 v[146:149], v142 offset:1024
	ds_read_b128 v[150:153], v142 offset:2048
	ds_read_b128 v[154:157], v142 offset:3072
	s_mov_b32 m0, s47
	s_nop 0
	global_load_lds_dwordx4 v135, s[82:83]
	s_mov_b32 m0, s48
	s_nop 0
	global_load_lds_dwordx4 v137, s[82:83]
	s_mov_b32 m0, s37
	s_nop 0
	global_load_lds_dwordx4 v134, s[42:43]
	s_mov_b32 m0, s49
	s_nop 0
	global_load_lds_dwordx4 v136, s[42:43]
	s_add_u32 s16, s42, 0x20000
	s_addc_u32 s17, s43, 0
	s_mov_b32 m0, s50
	s_nop 0
	global_load_lds_dwordx4 v134, s[16:17]
	s_mov_b32 m0, s51
	s_nop 0
	global_load_lds_dwordx4 v136, s[16:17]
	s_waitcnt vmcnt(8)
	s_waitcnt lgkmcnt(0)
	s_barrier
	s_waitcnt lgkmcnt(3)
	v_mfma_f32_16x16x32_bf16 v[116:119], v[128:131], v[166:169], v[116:119]
	s_waitcnt lgkmcnt(1)
	v_mfma_f32_16x16x32_bf16 v[112:115], v[150:153], v[166:169], v[112:115]
	v_mfma_f32_16x16x32_bf16 v[100:103], v[128:131], v[182:185], v[100:103]
	v_mfma_f32_16x16x32_bf16 v[96:99], v[150:153], v[182:185], v[96:99]
	v_mfma_f32_16x16x32_bf16 v[84:87], v[128:131], v[190:193], v[84:87]
	v_mfma_f32_16x16x32_bf16 v[80:83], v[150:153], v[190:193], v[80:83]
	v_mfma_f32_16x16x32_bf16 v[68:71], v[128:131], v[198:201], v[68:71]
	v_mfma_f32_16x16x32_bf16 v[64:67], v[150:153], v[198:201], v[64:67]
	v_mfma_f32_16x16x32_bf16 v[52:55], v[128:131], v[214:217], v[52:55]
	v_mfma_f32_16x16x32_bf16 v[48:51], v[150:153], v[214:217], v[48:51]
	v_mfma_f32_16x16x32_bf16 v[36:39], v[128:131], v[222:225], v[36:39]
	v_mfma_f32_16x16x32_bf16 v[32:35], v[150:153], v[222:225], v[32:35]
	v_mfma_f32_16x16x32_bf16 v[20:23], v[128:131], v[230:233], v[20:23]
	v_mfma_f32_16x16x32_bf16 v[16:19], v[150:153], v[230:233], v[16:19]
	v_mfma_f32_16x16x32_bf16 v[4:7], v[128:131], v[238:241], v[4:7]
	v_mfma_f32_16x16x32_bf16 v[0:3], v[150:153], v[238:241], v[0:3]
	v_mfma_f32_16x16x32_bf16 v[116:119], v[146:149], v[178:181], v[116:119]
	s_waitcnt lgkmcnt(0)
	v_mfma_f32_16x16x32_bf16 v[112:115], v[154:157], v[178:181], v[112:115]
	v_mfma_f32_16x16x32_bf16 v[100:103], v[146:149], v[186:189], v[100:103]
	v_mfma_f32_16x16x32_bf16 v[96:99], v[154:157], v[186:189], v[96:99]
	v_mfma_f32_16x16x32_bf16 v[84:87], v[146:149], v[194:197], v[84:87]
	v_mfma_f32_16x16x32_bf16 v[80:83], v[154:157], v[194:197], v[80:83]
	v_mfma_f32_16x16x32_bf16 v[68:71], v[146:149], v[202:205], v[68:71]
	v_mfma_f32_16x16x32_bf16 v[64:67], v[154:157], v[202:205], v[64:67]
	v_mfma_f32_16x16x32_bf16 v[52:55], v[146:149], v[218:221], v[52:55]
	v_mfma_f32_16x16x32_bf16 v[48:51], v[154:157], v[218:221], v[48:51]
	v_mfma_f32_16x16x32_bf16 v[36:39], v[146:149], v[226:229], v[36:39]
	v_mfma_f32_16x16x32_bf16 v[32:35], v[154:157], v[226:229], v[32:35]
	v_mfma_f32_16x16x32_bf16 v[20:23], v[146:149], v[234:237], v[20:23]
	v_mfma_f32_16x16x32_bf16 v[16:19], v[154:157], v[234:237], v[16:19]
	v_mfma_f32_16x16x32_bf16 v[4:7], v[146:149], v[242:245], v[4:7]
	v_mfma_f32_16x16x32_bf16 v[0:3], v[154:157], v[242:245], v[0:3]
	s_barrier
; #define PG8_STAGE(bufoff, gbase, voff) do { _Pragma("unroll") for (int _i = 0; _i < 2; ++_i) { \
;         const unsigned _m0 = ldsu + (unsigned)(bufoff) + ldsw + (unsigned)(_i * 8192); \
;         asm volatile("s_mov_b32 m0, %2\n\ts_nop 0\n\tglobal_load_lds_dwordx4 %0, %1" :: "v"((voff)[_i]), "s"((const char*)(gbase)), "s"(_m0) : "memory"); } } while (0)
; #define PG8_LDA(dst, b, h) do { _Pragma("unroll") for (int m = 0; m < 4; ++m) _Pragma("unroll") for (int k = 0; k < 2; ++k) dst[m][k] = *(const LAS bf16x8*)(lds + PG8_SA(b, h) + aoff + m * 2048 + k * 1024); } while (0)
; #define PG8_LDB(dst, b, h) do { _Pragma("unroll") for (int n = 0; n < 2; ++n) _Pragma("unroll") for (int k = 0; k < 2; ++k) dst[n][k] = *(const LAS bf16x8*)(lds + bbase[b][h] + n * 2048 + k * 1024); } while (0)
; #define PG8_WAIT_V(n) asm volatile("s_waitcnt vmcnt(" #n ")" ::: "memory")
; #define PG8_WAIT_L(n) asm volatile("s_waitcnt lgkmcnt(" #n ")" ::: "memory")
; #define PG8_BAR __builtin_amdgcn_s_barrier()
; #define PG8_SCHED __builtin_amdgcn_sched_barrier(0)
; template <class Epi>
; __device__ __forceinline__ void gemm_phase(LAS unsigned char* lds, const Gemm g, const StaticOrder& S, const Epi& E) {
;     ...
;             PG8_LDB(B0, 1, 0); PG8_SCHED; PG8_LDA(At, 1, 0); PG8_LDA(At2, 1, 1); PG8_STAGE(PG8_SB(0, 1), b2 + hstepB, voffB);
;             PG8_WAIT_V(8); PG8_WAIT_L(0); PG8_BAR; PG8_MMA2B(0, At, At2, B0); PG8_BAR; PG8_SCHED;
;             PG8_LDB(B0, 1, 1); PG8_STAGE(PG8_SB(1, 0), b3, voffB); PG8_STAGE(PG8_SA(1, 0), a3, voffA); PG8_STAGE(PG8_SA(1, 1), a3 + hstepA, voffA);
;             PG8_WAIT_V(8); PG8_WAIT_L(0); PG8_BAR; PG8_MMA2B(1, At, At2, B0); PG8_BAR; PG8_SCHED;
;         }
	ds_read_b128 v[128:131], v143
	ds_read_b128 v[146:149], v143 offset:1024
	ds_read_b128 v[150:153], v143 offset:2048
	ds_read_b128 v[154:157], v143 offset:3072
	ds_read_b128 v[166:169], v141 offset:32768
	ds_read_b128 v[178:181], v141 offset:33792
	ds_read_b128 v[182:185], v141 offset:34816
	ds_read_b128 v[186:189], v141 offset:35840
	ds_read_b128 v[190:193], v141 offset:36864
	ds_read_b128 v[194:197], v141 offset:37888
	ds_read_b128 v[198:201], v141 offset:38912
	ds_read_b128 v[202:205], v141 offset:39936
	ds_read_b128 v[214:217], v141 offset:49152
	ds_read_b128 v[218:221], v141 offset:50176
	ds_read_b128 v[222:225], v141 offset:51200
	ds_read_b128 v[226:229], v141 offset:52224
	ds_read_b128 v[230:233], v141 offset:53248
	ds_read_b128 v[234:237], v141 offset:54272
	ds_read_b128 v[238:241], v141 offset:55296
	ds_read_b128 v[242:245], v141 offset:56320
	s_add_u32 s16, s82, 0x20000
	s_addc_u32 s17, s83, 0
	s_mov_b32 m0, s52
	s_nop 0
	global_load_lds_dwordx4 v135, s[16:17]
	s_mov_b32 m0, s53
	s_nop 0
	global_load_lds_dwordx4 v137, s[16:17]
	s_waitcnt vmcnt(8)
	s_waitcnt lgkmcnt(0)
	s_barrier
	s_waitcnt lgkmcnt(14)
	v_mfma_f32_16x16x32_bf16 v[124:127], v[128:131], v[166:169], v[124:127]
	v_mfma_f32_16x16x32_bf16 v[120:123], v[150:153], v[166:169], v[120:123]
	s_waitcnt lgkmcnt(13)
	v_mfma_f32_16x16x32_bf16 v[108:111], v[128:131], v[182:185], v[108:111]
	v_mfma_f32_16x16x32_bf16 v[104:107], v[150:153], v[182:185], v[104:107]
	s_waitcnt lgkmcnt(11)
	v_mfma_f32_16x16x32_bf16 v[92:95], v[128:131], v[190:193], v[92:95]
	v_mfma_f32_16x16x32_bf16 v[88:91], v[150:153], v[190:193], v[88:91]
	s_waitcnt lgkmcnt(9)
	v_mfma_f32_16x16x32_bf16 v[76:79], v[128:131], v[198:201], v[76:79]
	v_mfma_f32_16x16x32_bf16 v[72:75], v[150:153], v[198:201], v[72:75]
	s_waitcnt lgkmcnt(7)
	v_mfma_f32_16x16x32_bf16 v[60:63], v[128:131], v[214:217], v[60:63]
	v_mfma_f32_16x16x32_bf16 v[56:59], v[150:153], v[214:217], v[56:59]
	s_waitcnt lgkmcnt(5)
	v_mfma_f32_16x16x32_bf16 v[44:47], v[128:131], v[222:225], v[44:47]
	v_mfma_f32_16x16x32_bf16 v[40:43], v[150:153], v[222:225], v[40:43]
	s_waitcnt lgkmcnt(3)
	v_mfma_f32_16x16x32_bf16 v[28:31], v[128:131], v[230:233], v[28:31]
	v_mfma_f32_16x16x32_bf16 v[24:27], v[150:153], v[230:233], v[24:27]
	s_waitcnt lgkmcnt(1)
	v_mfma_f32_16x16x32_bf16 v[12:15], v[128:131], v[238:241], v[12:15]
	v_mfma_f32_16x16x32_bf16 v[8:11], v[150:153], v[238:241], v[8:11]
	v_mfma_f32_16x16x32_bf16 v[124:127], v[146:149], v[178:181], v[124:127]
	v_mfma_f32_16x16x32_bf16 v[120:123], v[154:157], v[178:181], v[120:123]
	v_mfma_f32_16x16x32_bf16 v[108:111], v[146:149], v[186:189], v[108:111]
	v_mfma_f32_16x16x32_bf16 v[104:107], v[154:157], v[186:189], v[104:107]
	v_mfma_f32_16x16x32_bf16 v[92:95], v[146:149], v[194:197], v[92:95]
	v_mfma_f32_16x16x32_bf16 v[88:91], v[154:157], v[194:197], v[88:91]
	v_mfma_f32_16x16x32_bf16 v[76:79], v[146:149], v[202:205], v[76:79]
	v_mfma_f32_16x16x32_bf16 v[72:75], v[154:157], v[202:205], v[72:75]
	v_mfma_f32_16x16x32_bf16 v[60:63], v[146:149], v[218:221], v[60:63]
	v_mfma_f32_16x16x32_bf16 v[56:59], v[154:157], v[218:221], v[56:59]
	v_mfma_f32_16x16x32_bf16 v[44:47], v[146:149], v[226:229], v[44:47]
	v_mfma_f32_16x16x32_bf16 v[40:43], v[154:157], v[226:229], v[40:43]
	v_mfma_f32_16x16x32_bf16 v[28:31], v[146:149], v[234:237], v[28:31]
	v_mfma_f32_16x16x32_bf16 v[24:27], v[154:157], v[234:237], v[24:27]
	s_waitcnt lgkmcnt(0)
	v_mfma_f32_16x16x32_bf16 v[12:15], v[146:149], v[242:245], v[12:15]
	v_mfma_f32_16x16x32_bf16 v[8:11], v[154:157], v[242:245], v[8:11]
	s_barrier
	s_add_u32 s16, s82, 0x80
	ds_read_b128 v[128:131], v144
	ds_read_b128 v[146:149], v144 offset:1024
	ds_read_b128 v[150:153], v144 offset:2048
	ds_read_b128 v[154:157], v144 offset:3072
	s_addc_u32 s17, s83, 0
	s_mov_b32 m0, s54
	s_nop 0
	global_load_lds_dwordx4 v135, s[16:17]
	s_mov_b32 m0, s55
	s_nop 0
	global_load_lds_dwordx4 v137, s[16:17]
	s_mov_b32 m0, s56
	s_nop 0
	global_load_lds_dwordx4 v134, s[80:81]
	s_mov_b32 m0, s57
	s_nop 0
	global_load_lds_dwordx4 v136, s[80:81]
	s_add_u32 s16, s42, 0x20080
	s_addc_u32 s17, s43, 0
	s_mov_b32 m0, s58
	s_nop 0
	global_load_lds_dwordx4 v134, s[16:17]
	s_mov_b32 m0, s59
	s_nop 0
	global_load_lds_dwordx4 v136, s[16:17]
	s_waitcnt vmcnt(8)
	s_waitcnt lgkmcnt(0)
	s_barrier
	s_waitcnt lgkmcnt(3)
	v_mfma_f32_16x16x32_bf16 v[116:119], v[128:131], v[166:169], v[116:119]
	s_waitcnt lgkmcnt(1)
	v_mfma_f32_16x16x32_bf16 v[112:115], v[150:153], v[166:169], v[112:115]
	v_mfma_f32_16x16x32_bf16 v[100:103], v[128:131], v[182:185], v[100:103]
	v_mfma_f32_16x16x32_bf16 v[96:99], v[150:153], v[182:185], v[96:99]
	v_mfma_f32_16x16x32_bf16 v[84:87], v[128:131], v[190:193], v[84:87]
	v_mfma_f32_16x16x32_bf16 v[80:83], v[150:153], v[190:193], v[80:83]
	v_mfma_f32_16x16x32_bf16 v[68:71], v[128:131], v[198:201], v[68:71]
	v_mfma_f32_16x16x32_bf16 v[64:67], v[150:153], v[198:201], v[64:67]
	v_mfma_f32_16x16x32_bf16 v[52:55], v[128:131], v[214:217], v[52:55]
	v_mfma_f32_16x16x32_bf16 v[48:51], v[150:153], v[214:217], v[48:51]
	v_mfma_f32_16x16x32_bf16 v[36:39], v[128:131], v[222:225], v[36:39]
	v_mfma_f32_16x16x32_bf16 v[32:35], v[150:153], v[222:225], v[32:35]
	v_mfma_f32_16x16x32_bf16 v[20:23], v[128:131], v[230:233], v[20:23]
	v_mfma_f32_16x16x32_bf16 v[16:19], v[150:153], v[230:233], v[16:19]
	v_mfma_f32_16x16x32_bf16 v[4:7], v[128:131], v[238:241], v[4:7]
	v_mfma_f32_16x16x32_bf16 v[0:3], v[150:153], v[238:241], v[0:3]
	v_mfma_f32_16x16x32_bf16 v[116:119], v[146:149], v[178:181], v[116:119]
	s_waitcnt lgkmcnt(0)
	v_mfma_f32_16x16x32_bf16 v[112:115], v[154:157], v[178:181], v[112:115]
	v_mfma_f32_16x16x32_bf16 v[100:103], v[146:149], v[186:189], v[100:103]
	v_mfma_f32_16x16x32_bf16 v[96:99], v[154:157], v[186:189], v[96:99]
	v_mfma_f32_16x16x32_bf16 v[84:87], v[146:149], v[194:197], v[84:87]
	v_mfma_f32_16x16x32_bf16 v[80:83], v[154:157], v[194:197], v[80:83]
	v_mfma_f32_16x16x32_bf16 v[68:71], v[146:149], v[202:205], v[68:71]
	v_mfma_f32_16x16x32_bf16 v[64:67], v[154:157], v[202:205], v[64:67]
	v_mfma_f32_16x16x32_bf16 v[52:55], v[146:149], v[218:221], v[52:55]
	v_mfma_f32_16x16x32_bf16 v[48:51], v[154:157], v[218:221], v[48:51]
	v_mfma_f32_16x16x32_bf16 v[36:39], v[146:149], v[226:229], v[36:39]
	v_mfma_f32_16x16x32_bf16 v[32:35], v[154:157], v[226:229], v[32:35]
	v_mfma_f32_16x16x32_bf16 v[20:23], v[146:149], v[234:237], v[20:23]
	v_mfma_f32_16x16x32_bf16 v[16:19], v[154:157], v[234:237], v[16:19]
	v_mfma_f32_16x16x32_bf16 v[4:7], v[146:149], v[242:245], v[4:7]
	v_mfma_f32_16x16x32_bf16 v[0:3], v[154:157], v[242:245], v[0:3]
	s_barrier
	s_add_i32 s68, s68, 2
	s_add_u32 s67, s67, 0x100
	s_addc_u32 s84, s84, 0
	s_cmp_gt_u32 s68, 5
	s_mov_b64 s[16:17], s[38:39]
	s_cbranch_scc0 .LBB0_870
	s_and_b64 vcc, exec, s[4:5]
	s_cbranch_vccz .LBB0_873
	s_barrier

; #define PG8_STAGE(bufoff, gbase, voff) do { _Pragma("unroll") for (int _i = 0; _i < 2; ++_i) { \
;         const unsigned _m0 = ldsu + (unsigned)(bufoff) + ldsw + (unsigned)(_i * 8192); \
;         asm volatile("s_mov_b32 m0, %2\n\ts_nop 0\n\tglobal_load_lds_dwordx4 %0, %1" :: "v"((voff)[_i]), "s"((const char*)(gbase)), "s"(_m0) : "memory"); } } while (0)
; #define PG8_LDA(dst, b, h) do { _Pragma("unroll") for (int m = 0; m < 4; ++m) _Pragma("unroll") for (int k = 0; k < 2; ++k) dst[m][k] = *(const LAS bf16x8*)(lds + PG8_SA(b, h) + aoff + m * 2048 + k * 1024); } while (0)
; #define PG8_LDB(dst, b, h) do { _Pragma("unroll") for (int n = 0; n < 2; ++n) _Pragma("unroll") for (int k = 0; k < 2; ++k) dst[n][k] = *(const LAS bf16x8*)(lds + bbase[b][h] + n * 2048 + k * 1024); } while (0)
; #define PG8_WAIT_V(n) asm volatile("s_waitcnt vmcnt(" #n ")" ::: "memory")
; #define PG8_WAIT_L(n) asm volatile("s_waitcnt lgkmcnt(" #n ")" ::: "memory")
; #define PG8_BAR __builtin_amdgcn_s_barrier()
; #define PG8_SCHED __builtin_amdgcn_sched_barrier(0)
; template <class Epi>
; __device__ __forceinline__ void gemm_phase(LAS unsigned char* lds, const Gemm g, const StaticOrder& S, const Epi& E) {
;     ...
;             PG8_LDB(B0, 0, 0); PG8_SCHED; PG8_LDA(At, 0, 0); PG8_LDA(At2, 0, 1); PG8_STAGE(PG8_SB(1, 1), b1 + hstepB, voffB);
;             PG8_WAIT_V(8); PG8_WAIT_L(0); PG8_BAR; PG8_MMA2B(0, At, At2, B0); PG8_BAR; PG8_SCHED;
;             PG8_LDB(B0, 0, 1); PG8_STAGE(PG8_SB(0, 0), b2, voffB); PG8_STAGE(PG8_SA(0, 0), a2, voffA); PG8_STAGE(PG8_SA(0, 1), a2 + hstepA, voffA);
;             PG8_WAIT_V(8); PG8_WAIT_L(0); PG8_BAR; PG8_MMA2B(1, At, At2, B0); PG8_BAR; PG8_SCHED;
.LBB0_943:
	ds_read_b128 v[128:131], v138
	ds_read_b128 v[144:147], v138 offset:1024
	ds_read_b128 v[148:151], v138 offset:2048
	ds_read_b128 v[152:155], v138 offset:3072
	s_cmp_eq_u32 s68, 12
	s_cselect_b32 s38, s66, s84
	s_cselect_b32 s39, s13, s85
	s_cselect_b32 s82, s67, s86
	s_cselect_b32 s83, s5, s87
	s_add_u32 s42, s38, 0x80
	s_addc_u32 s43, s39, 0
	s_add_u32 s80, s82, 0x80
	s_addc_u32 s81, s83, 0
	ds_read_b128 v[156:159], v139
	ds_read_b128 v[166:169], v139 offset:1024
	ds_read_b128 v[178:181], v139 offset:2048
	ds_read_b128 v[182:185], v139 offset:3072
	ds_read_b128 v[186:189], v139 offset:4096
	ds_read_b128 v[190:193], v139 offset:5120
	ds_read_b128 v[194:197], v139 offset:6144
	ds_read_b128 v[198:201], v139 offset:7168
	ds_read_b128 v[202:205], v139 offset:16384
	ds_read_b128 v[214:217], v139 offset:17408
	ds_read_b128 v[218:221], v139 offset:18432
	ds_read_b128 v[222:225], v139 offset:19456
	ds_read_b128 v[226:229], v139 offset:20480
	ds_read_b128 v[230:233], v139 offset:21504
	ds_read_b128 v[234:237], v139 offset:22528
	ds_read_b128 v[238:241], v139 offset:23552
	s_mov_b32 m0, s61
	s_nop 0
	global_load_lds_dwordx4 v133, s[6:7]
	s_mov_b32 m0, s63
	s_nop 0
	global_load_lds_dwordx4 v135, s[6:7]
	s_waitcnt vmcnt(8)
	s_waitcnt lgkmcnt(0)
	s_barrier
	s_waitcnt lgkmcnt(14)
	v_mfma_f32_16x16x32_bf16 v[124:127], v[128:131], v[156:159], v[124:127]
	v_mfma_f32_16x16x32_bf16 v[120:123], v[148:151], v[156:159], v[120:123]
	s_waitcnt lgkmcnt(13)
	v_mfma_f32_16x16x32_bf16 v[108:111], v[128:131], v[178:181], v[108:111]
	v_mfma_f32_16x16x32_bf16 v[104:107], v[148:151], v[178:181], v[104:107]
	s_waitcnt lgkmcnt(11)
	v_mfma_f32_16x16x32_bf16 v[92:95], v[128:131], v[186:189], v[92:95]
	v_mfma_f32_16x16x32_bf16 v[88:91], v[148:151], v[186:189], v[88:91]
	s_waitcnt lgkmcnt(9)
	v_mfma_f32_16x16x32_bf16 v[76:79], v[128:131], v[194:197], v[76:79]
	v_mfma_f32_16x16x32_bf16 v[72:75], v[148:151], v[194:197], v[72:75]
	s_waitcnt lgkmcnt(7)
	v_mfma_f32_16x16x32_bf16 v[60:63], v[128:131], v[202:205], v[60:63]
	v_mfma_f32_16x16x32_bf16 v[56:59], v[148:151], v[202:205], v[56:59]
	s_waitcnt lgkmcnt(5)
	v_mfma_f32_16x16x32_bf16 v[44:47], v[128:131], v[218:221], v[44:47]
	v_mfma_f32_16x16x32_bf16 v[40:43], v[148:151], v[218:221], v[40:43]
	s_waitcnt lgkmcnt(3)
	v_mfma_f32_16x16x32_bf16 v[28:31], v[128:131], v[226:229], v[28:31]
	v_mfma_f32_16x16x32_bf16 v[24:27], v[148:151], v[226:229], v[24:27]
	s_waitcnt lgkmcnt(1)
	v_mfma_f32_16x16x32_bf16 v[12:15], v[128:131], v[234:237], v[12:15]
	v_mfma_f32_16x16x32_bf16 v[8:11], v[148:151], v[234:237], v[8:11]
	v_mfma_f32_16x16x32_bf16 v[124:127], v[144:147], v[166:169], v[124:127]
	v_mfma_f32_16x16x32_bf16 v[120:123], v[152:155], v[166:169], v[120:123]
	v_mfma_f32_16x16x32_bf16 v[108:111], v[144:147], v[182:185], v[108:111]
	v_mfma_f32_16x16x32_bf16 v[104:107], v[152:155], v[182:185], v[104:107]
	v_mfma_f32_16x16x32_bf16 v[92:95], v[144:147], v[190:193], v[92:95]
	v_mfma_f32_16x16x32_bf16 v[88:91], v[152:155], v[190:193], v[88:91]
	v_mfma_f32_16x16x32_bf16 v[76:79], v[144:147], v[198:201], v[76:79]
	v_mfma_f32_16x16x32_bf16 v[72:75], v[152:155], v[198:201], v[72:75]
	v_mfma_f32_16x16x32_bf16 v[60:63], v[144:147], v[214:217], v[60:63]
	v_mfma_f32_16x16x32_bf16 v[56:59], v[152:155], v[214:217], v[56:59]
	v_mfma_f32_16x16x32_bf16 v[44:47], v[144:147], v[222:225], v[44:47]
	v_mfma_f32_16x16x32_bf16 v[40:43], v[152:155], v[222:225], v[40:43]
	v_mfma_f32_16x16x32_bf16 v[28:31], v[144:147], v[230:233], v[28:31]
	v_mfma_f32_16x16x32_bf16 v[24:27], v[152:155], v[230:233], v[24:27]
	s_waitcnt lgkmcnt(0)
	v_mfma_f32_16x16x32_bf16 v[12:15], v[144:147], v[238:241], v[12:15]
	v_mfma_f32_16x16x32_bf16 v[8:11], v[152:155], v[238:241], v[8:11]
	s_barrier
	ds_read_b128 v[128:131], v140
	ds_read_b128 v[144:147], v140 offset:1024
	ds_read_b128 v[148:151], v140 offset:2048
	ds_read_b128 v[152:155], v140 offset:3072
	s_mov_b32 m0, s48
	s_nop 0
	global_load_lds_dwordx4 v133, s[82:83]
	s_mov_b32 m0, s49
	s_nop 0
	global_load_lds_dwordx4 v135, s[82:83]
	s_mov_b32 m0, s47
	s_nop 0
	global_load_lds_dwordx4 v132, s[38:39]
	s_mov_b32 m0, s50
	s_nop 0
	global_load_lds_dwordx4 v134, s[38:39]
	s_add_u32 s88, s38, 0x40000
	s_addc_u32 s89, s39, 0
	s_mov_b32 m0, s51
	s_nop 0
	global_load_lds_dwordx4 v132, s[88:89]
	s_mov_b32 m0, s52
	s_nop 0
	global_load_lds_dwordx4 v134, s[88:89]
	s_waitcnt vmcnt(8)
	s_waitcnt lgkmcnt(0)
	s_barrier
	s_waitcnt lgkmcnt(3)
	v_mfma_f32_16x16x32_bf16 v[116:119], v[128:131], v[156:159], v[116:119]
	s_waitcnt lgkmcnt(1)
	v_mfma_f32_16x16x32_bf16 v[112:115], v[148:151], v[156:159], v[112:115]
	v_mfma_f32_16x16x32_bf16 v[100:103], v[128:131], v[178:181], v[100:103]
	v_mfma_f32_16x16x32_bf16 v[96:99], v[148:151], v[178:181], v[96:99]
	v_mfma_f32_16x16x32_bf16 v[84:87], v[128:131], v[186:189], v[84:87]
	v_mfma_f32_16x16x32_bf16 v[80:83], v[148:151], v[186:189], v[80:83]
	v_mfma_f32_16x16x32_bf16 v[68:71], v[128:131], v[194:197], v[68:71]
	v_mfma_f32_16x16x32_bf16 v[64:67], v[148:151], v[194:197], v[64:67]
	v_mfma_f32_16x16x32_bf16 v[52:55], v[128:131], v[202:205], v[52:55]
	v_mfma_f32_16x16x32_bf16 v[48:51], v[148:151], v[202:205], v[48:51]
	v_mfma_f32_16x16x32_bf16 v[36:39], v[128:131], v[218:221], v[36:39]
	v_mfma_f32_16x16x32_bf16 v[32:35], v[148:151], v[218:221], v[32:35]
	v_mfma_f32_16x16x32_bf16 v[20:23], v[128:131], v[226:229], v[20:23]
	v_mfma_f32_16x16x32_bf16 v[16:19], v[148:151], v[226:229], v[16:19]
	v_mfma_f32_16x16x32_bf16 v[4:7], v[128:131], v[234:237], v[4:7]
	v_mfma_f32_16x16x32_bf16 v[0:3], v[148:151], v[234:237], v[0:3]
	v_mfma_f32_16x16x32_bf16 v[116:119], v[144:147], v[166:169], v[116:119]
	s_waitcnt lgkmcnt(0)
	v_mfma_f32_16x16x32_bf16 v[112:115], v[152:155], v[166:169], v[112:115]
	v_mfma_f32_16x16x32_bf16 v[100:103], v[144:147], v[182:185], v[100:103]
	v_mfma_f32_16x16x32_bf16 v[96:99], v[152:155], v[182:185], v[96:99]
	v_mfma_f32_16x16x32_bf16 v[84:87], v[144:147], v[190:193], v[84:87]
	v_mfma_f32_16x16x32_bf16 v[80:83], v[152:155], v[190:193], v[80:83]
	v_mfma_f32_16x16x32_bf16 v[68:71], v[144:147], v[198:201], v[68:71]
	v_mfma_f32_16x16x32_bf16 v[64:67], v[152:155], v[198:201], v[64:67]
	v_mfma_f32_16x16x32_bf16 v[52:55], v[144:147], v[214:217], v[52:55]
	v_mfma_f32_16x16x32_bf16 v[48:51], v[152:155], v[214:217], v[48:51]
	v_mfma_f32_16x16x32_bf16 v[36:39], v[144:147], v[222:225], v[36:39]
	v_mfma_f32_16x16x32_bf16 v[32:35], v[152:155], v[222:225], v[32:35]
	v_mfma_f32_16x16x32_bf16 v[20:23], v[144:147], v[230:233], v[20:23]
	v_mfma_f32_16x16x32_bf16 v[16:19], v[152:155], v[230:233], v[16:19]
	v_mfma_f32_16x16x32_bf16 v[4:7], v[144:147], v[238:241], v[4:7]
	v_mfma_f32_16x16x32_bf16 v[0:3], v[152:155], v[238:241], v[0:3]
	s_barrier
; #define PG8_STAGE(bufoff, gbase, voff) do { _Pragma("unroll") for (int _i = 0; _i < 2; ++_i) { \
;         const unsigned _m0 = ldsu + (unsigned)(bufoff) + ldsw + (unsigned)(_i * 8192); \
;         asm volatile("s_mov_b32 m0, %2\n\ts_nop 0\n\tglobal_load_lds_dwordx4 %0, %1" :: "v"((voff)[_i]), "s"((const char*)(gbase)), "s"(_m0) : "memory"); } } while (0)
; #define PG8_LDA(dst, b, h) do { _Pragma("unroll") for (int m = 0; m < 4; ++m) _Pragma("unroll") for (int k = 0; k < 2; ++k) dst[m][k] = *(const LAS bf16x8*)(lds + PG8_SA(b, h) + aoff + m * 2048 + k * 1024); } while (0)
; #define PG8_LDB(dst, b, h) do { _Pragma("unroll") for (int n = 0; n < 2; ++n) _Pragma("unroll") for (int k = 0; k < 2; ++k) dst[n][k] = *(const LAS bf16x8*)(lds + bbase[b][h] + n * 2048 + k * 1024); } while (0)
; #define PG8_WAIT_V(n) asm volatile("s_waitcnt vmcnt(" #n ")" ::: "memory")
; #define PG8_WAIT_L(n) asm volatile("s_waitcnt lgkmcnt(" #n ")" ::: "memory")
; #define PG8_BAR __builtin_amdgcn_s_barrier()
; #define PG8_SCHED __builtin_amdgcn_sched_barrier(0)
; template <class Epi>
; __device__ __forceinline__ void gemm_phase(LAS unsigned char* lds, const Gemm g, const StaticOrder& S, const Epi& E) {
;     ...
;             PG8_LDB(B0, 1, 0); PG8_SCHED; PG8_LDA(At, 1, 0); PG8_LDA(At2, 1, 1); PG8_STAGE(PG8_SB(0, 1), b2 + hstepB, voffB);
;             PG8_WAIT_V(8); PG8_WAIT_L(0); PG8_BAR; PG8_MMA2B(0, At, At2, B0); PG8_BAR; PG8_SCHED;
;             PG8_LDB(B0, 1, 1); PG8_STAGE(PG8_SB(1, 0), b3, voffB); PG8_STAGE(PG8_SA(1, 0), a3, voffA); PG8_STAGE(PG8_SA(1, 1), a3 + hstepA, voffA);
;             PG8_WAIT_V(8); PG8_WAIT_L(0); PG8_BAR; PG8_MMA2B(1, At, At2, B0); PG8_BAR; PG8_SCHED;
;         }
	ds_read_b128 v[128:131], v141
	ds_read_b128 v[144:147], v141 offset:1024
	ds_read_b128 v[148:151], v141 offset:2048
	ds_read_b128 v[152:155], v141 offset:3072
	ds_read_b128 v[156:159], v139 offset:32768
	ds_read_b128 v[166:169], v139 offset:33792
	ds_read_b128 v[178:181], v139 offset:34816
	ds_read_b128 v[182:185], v139 offset:35840
	ds_read_b128 v[186:189], v139 offset:36864
	ds_read_b128 v[190:193], v139 offset:37888
	ds_read_b128 v[194:197], v139 offset:38912
	ds_read_b128 v[198:201], v139 offset:39936
	ds_read_b128 v[202:205], v139 offset:49152
	ds_read_b128 v[214:217], v139 offset:50176
	ds_read_b128 v[218:221], v139 offset:51200
	ds_read_b128 v[222:225], v139 offset:52224
	ds_read_b128 v[226:229], v139 offset:53248
	ds_read_b128 v[230:233], v139 offset:54272
	ds_read_b128 v[234:237], v139 offset:55296
	ds_read_b128 v[238:241], v139 offset:56320
	s_add_u32 s82, s82, 0x40000
	s_addc_u32 s83, s83, 0
	s_mov_b32 m0, s53
	s_nop 0
	global_load_lds_dwordx4 v133, s[82:83]
	s_mov_b32 m0, s54
	s_nop 0
	global_load_lds_dwordx4 v135, s[82:83]
	s_waitcnt vmcnt(8)
	s_waitcnt lgkmcnt(0)
	s_barrier
	s_waitcnt lgkmcnt(14)
	v_mfma_f32_16x16x32_bf16 v[124:127], v[128:131], v[156:159], v[124:127]
	v_mfma_f32_16x16x32_bf16 v[120:123], v[148:151], v[156:159], v[120:123]
	s_waitcnt lgkmcnt(13)
	v_mfma_f32_16x16x32_bf16 v[108:111], v[128:131], v[178:181], v[108:111]
	v_mfma_f32_16x16x32_bf16 v[104:107], v[148:151], v[178:181], v[104:107]
	s_waitcnt lgkmcnt(11)
	v_mfma_f32_16x16x32_bf16 v[92:95], v[128:131], v[186:189], v[92:95]
	v_mfma_f32_16x16x32_bf16 v[88:91], v[148:151], v[186:189], v[88:91]
	s_waitcnt lgkmcnt(9)
	v_mfma_f32_16x16x32_bf16 v[76:79], v[128:131], v[194:197], v[76:79]
	v_mfma_f32_16x16x32_bf16 v[72:75], v[148:151], v[194:197], v[72:75]
	s_waitcnt lgkmcnt(7)
	v_mfma_f32_16x16x32_bf16 v[60:63], v[128:131], v[202:205], v[60:63]
	v_mfma_f32_16x16x32_bf16 v[56:59], v[148:151], v[202:205], v[56:59]
	s_waitcnt lgkmcnt(5)
	v_mfma_f32_16x16x32_bf16 v[44:47], v[128:131], v[218:221], v[44:47]
	v_mfma_f32_16x16x32_bf16 v[40:43], v[148:151], v[218:221], v[40:43]
	s_waitcnt lgkmcnt(3)
	v_mfma_f32_16x16x32_bf16 v[28:31], v[128:131], v[226:229], v[28:31]
	v_mfma_f32_16x16x32_bf16 v[24:27], v[148:151], v[226:229], v[24:27]
	s_waitcnt lgkmcnt(1)
	v_mfma_f32_16x16x32_bf16 v[12:15], v[128:131], v[234:237], v[12:15]
	v_mfma_f32_16x16x32_bf16 v[8:11], v[148:151], v[234:237], v[8:11]
	v_mfma_f32_16x16x32_bf16 v[124:127], v[144:147], v[166:169], v[124:127]
	v_mfma_f32_16x16x32_bf16 v[120:123], v[152:155], v[166:169], v[120:123]
	v_mfma_f32_16x16x32_bf16 v[108:111], v[144:147], v[182:185], v[108:111]
	v_mfma_f32_16x16x32_bf16 v[104:107], v[152:155], v[182:185], v[104:107]
	v_mfma_f32_16x16x32_bf16 v[92:95], v[144:147], v[190:193], v[92:95]
	v_mfma_f32_16x16x32_bf16 v[88:91], v[152:155], v[190:193], v[88:91]
	v_mfma_f32_16x16x32_bf16 v[76:79], v[144:147], v[198:201], v[76:79]
	v_mfma_f32_16x16x32_bf16 v[72:75], v[152:155], v[198:201], v[72:75]
	v_mfma_f32_16x16x32_bf16 v[60:63], v[144:147], v[214:217], v[60:63]
	v_mfma_f32_16x16x32_bf16 v[56:59], v[152:155], v[214:217], v[56:59]
	v_mfma_f32_16x16x32_bf16 v[44:47], v[144:147], v[222:225], v[44:47]
	v_mfma_f32_16x16x32_bf16 v[40:43], v[152:155], v[222:225], v[40:43]
	v_mfma_f32_16x16x32_bf16 v[28:31], v[144:147], v[230:233], v[28:31]
	v_mfma_f32_16x16x32_bf16 v[24:27], v[152:155], v[230:233], v[24:27]
	s_waitcnt lgkmcnt(0)
	v_mfma_f32_16x16x32_bf16 v[12:15], v[144:147], v[238:241], v[12:15]
	v_mfma_f32_16x16x32_bf16 v[8:11], v[152:155], v[238:241], v[8:11]
	s_barrier
	ds_read_b128 v[128:131], v142
	ds_read_b128 v[144:147], v142 offset:1024
	ds_read_b128 v[148:151], v142 offset:2048
	ds_read_b128 v[152:155], v142 offset:3072
	s_mov_b32 m0, s55
	s_nop 0
	global_load_lds_dwordx4 v133, s[80:81]
	s_mov_b32 m0, s56
	s_nop 0
	global_load_lds_dwordx4 v135, s[80:81]
	s_mov_b32 m0, s57
	s_nop 0
	global_load_lds_dwordx4 v132, s[42:43]
	s_mov_b32 m0, s58
	s_nop 0
	global_load_lds_dwordx4 v134, s[42:43]
	s_add_u32 s38, s38, 0x40080
	s_addc_u32 s39, s39, 0
	s_mov_b32 m0, s59
	s_nop 0
	global_load_lds_dwordx4 v132, s[38:39]
	s_mov_b32 m0, s60
	s_nop 0
	global_load_lds_dwordx4 v134, s[38:39]
	s_waitcnt vmcnt(8)
	s_waitcnt lgkmcnt(0)
	s_barrier
	s_waitcnt lgkmcnt(3)
	v_mfma_f32_16x16x32_bf16 v[116:119], v[128:131], v[156:159], v[116:119]
	s_waitcnt lgkmcnt(1)
	v_mfma_f32_16x16x32_bf16 v[112:115], v[148:151], v[156:159], v[112:115]
	v_mfma_f32_16x16x32_bf16 v[100:103], v[128:131], v[178:181], v[100:103]
	v_mfma_f32_16x16x32_bf16 v[96:99], v[148:151], v[178:181], v[96:99]
	v_mfma_f32_16x16x32_bf16 v[84:87], v[128:131], v[186:189], v[84:87]
	v_mfma_f32_16x16x32_bf16 v[80:83], v[148:151], v[186:189], v[80:83]
	v_mfma_f32_16x16x32_bf16 v[68:71], v[128:131], v[194:197], v[68:71]
	v_mfma_f32_16x16x32_bf16 v[64:67], v[148:151], v[194:197], v[64:67]
	v_mfma_f32_16x16x32_bf16 v[52:55], v[128:131], v[202:205], v[52:55]
	v_mfma_f32_16x16x32_bf16 v[48:51], v[148:151], v[202:205], v[48:51]
	v_mfma_f32_16x16x32_bf16 v[36:39], v[128:131], v[218:221], v[36:39]
	v_mfma_f32_16x16x32_bf16 v[32:35], v[148:151], v[218:221], v[32:35]
	v_mfma_f32_16x16x32_bf16 v[20:23], v[128:131], v[226:229], v[20:23]
	v_mfma_f32_16x16x32_bf16 v[16:19], v[148:151], v[226:229], v[16:19]
	v_mfma_f32_16x16x32_bf16 v[4:7], v[128:131], v[234:237], v[4:7]
	v_mfma_f32_16x16x32_bf16 v[0:3], v[148:151], v[234:237], v[0:3]
	v_mfma_f32_16x16x32_bf16 v[116:119], v[144:147], v[166:169], v[116:119]
	s_waitcnt lgkmcnt(0)
	v_mfma_f32_16x16x32_bf16 v[112:115], v[152:155], v[166:169], v[112:115]
	v_mfma_f32_16x16x32_bf16 v[100:103], v[144:147], v[182:185], v[100:103]
	v_mfma_f32_16x16x32_bf16 v[96:99], v[152:155], v[182:185], v[96:99]
	v_mfma_f32_16x16x32_bf16 v[84:87], v[144:147], v[190:193], v[84:87]
	v_mfma_f32_16x16x32_bf16 v[80:83], v[152:155], v[190:193], v[80:83]
	v_mfma_f32_16x16x32_bf16 v[68:71], v[144:147], v[198:201], v[68:71]
	v_mfma_f32_16x16x32_bf16 v[64:67], v[152:155], v[198:201], v[64:67]
	v_mfma_f32_16x16x32_bf16 v[52:55], v[144:147], v[214:217], v[52:55]
	v_mfma_f32_16x16x32_bf16 v[48:51], v[152:155], v[214:217], v[48:51]
	v_mfma_f32_16x16x32_bf16 v[36:39], v[144:147], v[222:225], v[36:39]
	v_mfma_f32_16x16x32_bf16 v[32:35], v[152:155], v[222:225], v[32:35]
	v_mfma_f32_16x16x32_bf16 v[20:23], v[144:147], v[230:233], v[20:23]
	v_mfma_f32_16x16x32_bf16 v[16:19], v[152:155], v[230:233], v[16:19]
	v_mfma_f32_16x16x32_bf16 v[4:7], v[144:147], v[238:241], v[4:7]
	v_mfma_f32_16x16x32_bf16 v[0:3], v[152:155], v[238:241], v[0:3]
	s_barrier
	s_add_i32 s68, s68, 2
	s_add_u32 s6, s6, 0x100
	s_addc_u32 s7, s7, 0
	s_add_u32 s84, s84, 0x100
	s_addc_u32 s85, s85, 0
	s_add_u32 s86, s86, 0x100
	s_addc_u32 s87, s87, 0
	s_cmp_gt_u32 s68, 13
	s_cbranch_scc0 .LBB0_943
	s_and_b64 vcc, exec, s[2:3]
	s_cbranch_vccz .LBB0_946
	s_barrier

; #define PG8_STAGE(bufoff, gbase, voff) do { _Pragma("unroll") for (int _i = 0; _i < 2; ++_i) { \
;         const unsigned _m0 = ldsu + (unsigned)(bufoff) + ldsw + (unsigned)(_i * 8192); \
;         asm volatile("s_mov_b32 m0, %2\n\ts_nop 0\n\tglobal_load_lds_dwordx4 %0, %1" :: "v"((voff)[_i]), "s"((const char*)(gbase)), "s"(_m0) : "memory"); } } while (0)
; #define PG8_LDA(dst, b, h) do { _Pragma("unroll") for (int m = 0; m < 4; ++m) _Pragma("unroll") for (int k = 0; k < 2; ++k) dst[m][k] = *(const LAS bf16x8*)(lds + PG8_SA(b, h) + aoff + m * 2048 + k * 1024); } while (0)
; #define PG8_LDB(dst, b, h) do { _Pragma("unroll") for (int n = 0; n < 2; ++n) _Pragma("unroll") for (int k = 0; k < 2; ++k) dst[n][k] = *(const LAS bf16x8*)(lds + bbase[b][h] + n * 2048 + k * 1024); } while (0)
; #define PG8_WAIT_V(n) asm volatile("s_waitcnt vmcnt(" #n ")" ::: "memory")
; #define PG8_WAIT_L(n) asm volatile("s_waitcnt lgkmcnt(" #n ")" ::: "memory")
; #define PG8_BAR __builtin_amdgcn_s_barrier()
; #define PG8_SCHED __builtin_amdgcn_sched_barrier(0)
; template <class Epi>
; __device__ __forceinline__ void gemm_phase(LAS unsigned char* lds, const Gemm g, const StaticOrder& S, const Epi& E) {
;     ...
;             PG8_LDB(B0, 0, 0); PG8_SCHED; PG8_LDA(At, 0, 0); PG8_LDA(At2, 0, 1); PG8_STAGE(PG8_SB(1, 1), b1 + hstepB, voffB);
;             PG8_WAIT_V(8); PG8_WAIT_L(0); PG8_BAR; PG8_MMA2B(0, At, At2, B0); PG8_BAR; PG8_SCHED;
;             PG8_LDB(B0, 0, 1); PG8_STAGE(PG8_SB(0, 0), b2, voffB); PG8_STAGE(PG8_SA(0, 0), a2, voffA); PG8_STAGE(PG8_SA(0, 1), a2 + hstepA, voffA);
;             PG8_WAIT_V(8); PG8_WAIT_L(0); PG8_BAR; PG8_MMA2B(1, At, At2, B0); PG8_BAR; PG8_SCHED;
.LBB0_1027:
	ds_read_b128 v[68:71], v220
	ds_read_b128 v[84:87], v220 offset:1024
	ds_read_b128 v[88:91], v220 offset:2048
	ds_read_b128 v[92:95], v220 offset:3072
	s_add_u32 s12, s10, 0x100
	s_addc_u32 s13, s11, 0
	s_cmp_eq_u32 s69, 12
	s_cselect_b32 s14, s97, vcc_hi
	s_cselect_b32 s15, s7, s68
	s_cselect_b32 s84, vcc_lo, s12
	s_cselect_b32 s85, s39, s13
	s_add_u32 s16, s14, 0x80
	s_addc_u32 s17, s15, 0
	ds_read_b128 v[96:99], v221
	ds_read_b128 v[100:103], v221 offset:1024
	ds_read_b128 v[152:155], v221 offset:2048
	ds_read_b128 v[156:159], v221 offset:3072
	ds_read_b128 v[166:169], v221 offset:4096
	ds_read_b128 v[178:181], v221 offset:5120
	ds_read_b128 v[182:185], v221 offset:6144
	ds_read_b128 v[186:189], v221 offset:7168
	ds_read_b128 v[190:193], v221 offset:16384
	ds_read_b128 v[194:197], v221 offset:17408
	ds_read_b128 v[198:201], v221 offset:18432
	ds_read_b128 v[202:205], v221 offset:19456
	ds_read_b128 v[226:229], v221 offset:20480
	ds_read_b128 v[230:233], v221 offset:21504
	ds_read_b128 v[234:237], v221 offset:22528
	ds_read_b128 v[238:241], v221 offset:23552
	s_add_u32 s10, s10, 0x40080
	s_addc_u32 s11, s11, 0
	s_mov_b32 m0, s58
	s_nop 0
	global_load_lds_dwordx4 v217, s[10:11]
	s_mov_b32 m0, s60
	s_nop 0
	global_load_lds_dwordx4 v219, s[10:11]
	s_waitcnt vmcnt(8)
	s_waitcnt lgkmcnt(0)
	s_barrier
	s_waitcnt lgkmcnt(14)
	v_mfma_f32_16x16x32_bf16 v[80:83], v[68:71], v[96:99], v[80:83]
	v_mfma_f32_16x16x32_bf16 v[76:79], v[88:91], v[96:99], v[76:79]
	s_waitcnt lgkmcnt(13)
	v_mfma_f32_16x16x32_bf16 v[148:151], v[68:71], v[152:155], v[148:151]
	v_mfma_f32_16x16x32_bf16 v[52:55], v[88:91], v[152:155], v[52:55]
	s_waitcnt lgkmcnt(11)
	v_mfma_f32_16x16x32_bf16 v[144:147], v[68:71], v[166:169], v[144:147]
	v_mfma_f32_16x16x32_bf16 v[48:51], v[88:91], v[166:169], v[48:51]
	s_waitcnt lgkmcnt(9)
	v_mfma_f32_16x16x32_bf16 v[136:139], v[68:71], v[182:185], v[136:139]
	v_mfma_f32_16x16x32_bf16 v[40:43], v[88:91], v[182:185], v[40:43]
	s_waitcnt lgkmcnt(7)
	v_mfma_f32_16x16x32_bf16 v[124:127], v[68:71], v[190:193], v[124:127]
	v_mfma_f32_16x16x32_bf16 v[28:31], v[88:91], v[190:193], v[28:31]
	s_waitcnt lgkmcnt(5)
	v_mfma_f32_16x16x32_bf16 v[120:123], v[68:71], v[198:201], v[120:123]
	v_mfma_f32_16x16x32_bf16 v[24:27], v[88:91], v[198:201], v[24:27]
	s_waitcnt lgkmcnt(3)
	v_mfma_f32_16x16x32_bf16 v[112:115], v[68:71], v[226:229], v[112:115]
	v_mfma_f32_16x16x32_bf16 v[16:19], v[88:91], v[226:229], v[16:19]
	s_waitcnt lgkmcnt(1)
	v_mfma_f32_16x16x32_bf16 v[64:67], v[68:71], v[234:237], v[64:67]
	v_mfma_f32_16x16x32_bf16 v[4:7], v[88:91], v[234:237], v[4:7]
	v_mfma_f32_16x16x32_bf16 v[80:83], v[84:87], v[100:103], v[80:83]
	v_mfma_f32_16x16x32_bf16 v[76:79], v[92:95], v[100:103], v[76:79]
	v_mfma_f32_16x16x32_bf16 v[148:151], v[84:87], v[156:159], v[148:151]
	v_mfma_f32_16x16x32_bf16 v[52:55], v[92:95], v[156:159], v[52:55]
	v_mfma_f32_16x16x32_bf16 v[144:147], v[84:87], v[178:181], v[144:147]
	v_mfma_f32_16x16x32_bf16 v[48:51], v[92:95], v[178:181], v[48:51]
	v_mfma_f32_16x16x32_bf16 v[136:139], v[84:87], v[186:189], v[136:139]
	v_mfma_f32_16x16x32_bf16 v[40:43], v[92:95], v[186:189], v[40:43]
	v_mfma_f32_16x16x32_bf16 v[124:127], v[84:87], v[194:197], v[124:127]
	v_mfma_f32_16x16x32_bf16 v[28:31], v[92:95], v[194:197], v[28:31]
	v_mfma_f32_16x16x32_bf16 v[120:123], v[84:87], v[202:205], v[120:123]
	v_mfma_f32_16x16x32_bf16 v[24:27], v[92:95], v[202:205], v[24:27]
	v_mfma_f32_16x16x32_bf16 v[112:115], v[84:87], v[230:233], v[112:115]
	v_mfma_f32_16x16x32_bf16 v[16:19], v[92:95], v[230:233], v[16:19]
	s_waitcnt lgkmcnt(0)
	v_mfma_f32_16x16x32_bf16 v[64:67], v[84:87], v[238:241], v[64:67]
	v_mfma_f32_16x16x32_bf16 v[4:7], v[92:95], v[238:241], v[4:7]
	s_barrier
	ds_read_b128 v[68:71], v222
	ds_read_b128 v[84:87], v222 offset:1024
	ds_read_b128 v[88:91], v222 offset:2048
	ds_read_b128 v[92:95], v222 offset:3072
	s_mov_b32 m0, s48
	s_nop 0
	global_load_lds_dwordx4 v217, s[84:85]
	s_mov_b32 m0, s49
	s_nop 0
	global_load_lds_dwordx4 v219, s[84:85]
	s_mov_b32 m0, s47
	s_nop 0
	global_load_lds_dwordx4 v216, s[14:15]
	s_mov_b32 m0, s50
	s_nop 0
	global_load_lds_dwordx4 v218, s[14:15]
	s_add_u32 s10, s14, 0x40000
	s_addc_u32 s11, s15, 0
	s_mov_b32 m0, s51
	s_nop 0
	global_load_lds_dwordx4 v216, s[10:11]
	s_mov_b32 m0, s52
	s_nop 0
	global_load_lds_dwordx4 v218, s[10:11]
	s_waitcnt vmcnt(8)
	s_waitcnt lgkmcnt(0)
	s_barrier
	s_waitcnt lgkmcnt(3)
	v_mfma_f32_16x16x32_bf16 v[72:75], v[68:71], v[96:99], v[72:75]
	s_waitcnt lgkmcnt(1)
	v_mfma_f32_16x16x32_bf16 v[56:59], v[88:91], v[96:99], v[56:59]
	v_mfma_f32_16x16x32_bf16 v[44:47], v[88:91], v[152:155], v[44:47]
	v_mfma_f32_16x16x32_bf16 v[36:39], v[88:91], v[166:169], v[36:39]
	v_mfma_f32_16x16x32_bf16 v[128:131], v[68:71], v[182:185], v[128:131]
	v_mfma_f32_16x16x32_bf16 v[32:35], v[88:91], v[182:185], v[32:35]
	v_mfma_f32_16x16x32_bf16 v[116:119], v[68:71], v[190:193], v[116:119]
	v_mfma_f32_16x16x32_bf16 v[20:23], v[88:91], v[190:193], v[20:23]
	v_mfma_f32_16x16x32_bf16 v[108:111], v[68:71], v[198:201], v[108:111]
	v_mfma_f32_16x16x32_bf16 v[12:15], v[88:91], v[198:201], v[12:15]
	v_mfma_f32_16x16x32_bf16 v[104:107], v[68:71], v[226:229], v[104:107]
	v_mfma_f32_16x16x32_bf16 v[8:11], v[88:91], v[226:229], v[8:11]
	v_mfma_f32_16x16x32_bf16 v[60:63], v[68:71], v[234:237], v[60:63]
	v_mfma_f32_16x16x32_bf16 v[0:3], v[88:91], v[234:237], v[0:3]
	v_mfma_f32_16x16x32_bf16 v[72:75], v[84:87], v[100:103], v[72:75]
	s_waitcnt lgkmcnt(0)
	v_mfma_f32_16x16x32_bf16 v[56:59], v[92:95], v[100:103], v[56:59]
	v_mfma_f32_16x16x32_bf16 v[96:99], v[68:71], v[152:155], v[140:143]
	v_mfma_f32_16x16x32_bf16 v[44:47], v[92:95], v[156:159], v[44:47]
	v_mfma_f32_16x16x32_bf16 v[100:103], v[68:71], v[166:169], v[132:135]
	v_mfma_f32_16x16x32_bf16 v[36:39], v[92:95], v[178:181], v[36:39]
	v_mfma_f32_16x16x32_bf16 v[128:131], v[84:87], v[186:189], v[128:131]
	v_mfma_f32_16x16x32_bf16 v[32:35], v[92:95], v[186:189], v[32:35]
	v_mfma_f32_16x16x32_bf16 v[116:119], v[84:87], v[194:197], v[116:119]
	v_mfma_f32_16x16x32_bf16 v[20:23], v[92:95], v[194:197], v[20:23]
	v_mfma_f32_16x16x32_bf16 v[108:111], v[84:87], v[202:205], v[108:111]
	v_mfma_f32_16x16x32_bf16 v[12:15], v[92:95], v[202:205], v[12:15]
	v_mfma_f32_16x16x32_bf16 v[104:107], v[84:87], v[230:233], v[104:107]
	v_mfma_f32_16x16x32_bf16 v[8:11], v[92:95], v[230:233], v[8:11]
	v_mfma_f32_16x16x32_bf16 v[60:63], v[84:87], v[238:241], v[60:63]
	v_mfma_f32_16x16x32_bf16 v[0:3], v[92:95], v[238:241], v[0:3]
	v_mfma_f32_16x16x32_bf16 v[96:99], v[84:87], v[156:159], v[96:99]
	v_mfma_f32_16x16x32_bf16 v[100:103], v[84:87], v[178:181], v[100:103]
	s_barrier
; #define PG8_STAGE(bufoff, gbase, voff) do { _Pragma("unroll") for (int _i = 0; _i < 2; ++_i) { \
;         const unsigned _m0 = ldsu + (unsigned)(bufoff) + ldsw + (unsigned)(_i * 8192); \
;         asm volatile("s_mov_b32 m0, %2\n\ts_nop 0\n\tglobal_load_lds_dwordx4 %0, %1" :: "v"((voff)[_i]), "s"((const char*)(gbase)), "s"(_m0) : "memory"); } } while (0)
; #define PG8_LDA(dst, b, h) do { _Pragma("unroll") for (int m = 0; m < 4; ++m) _Pragma("unroll") for (int k = 0; k < 2; ++k) dst[m][k] = *(const LAS bf16x8*)(lds + PG8_SA(b, h) + aoff + m * 2048 + k * 1024); } while (0)
; #define PG8_LDB(dst, b, h) do { _Pragma("unroll") for (int n = 0; n < 2; ++n) _Pragma("unroll") for (int k = 0; k < 2; ++k) dst[n][k] = *(const LAS bf16x8*)(lds + bbase[b][h] + n * 2048 + k * 1024); } while (0)
; #define PG8_WAIT_V(n) asm volatile("s_waitcnt vmcnt(" #n ")" ::: "memory")
; #define PG8_WAIT_L(n) asm volatile("s_waitcnt lgkmcnt(" #n ")" ::: "memory")
; #define PG8_BAR __builtin_amdgcn_s_barrier()
; #define PG8_SCHED __builtin_amdgcn_sched_barrier(0)
; template <class Epi>
; __device__ __forceinline__ void gemm_phase(LAS unsigned char* lds, const Gemm g, const StaticOrder& S, const Epi& E) {
;     ...
;             PG8_LDB(B0, 1, 0); PG8_SCHED; PG8_LDA(At, 1, 0); PG8_LDA(At2, 1, 1); PG8_STAGE(PG8_SB(0, 1), b2 + hstepB, voffB);
;             PG8_WAIT_V(8); PG8_WAIT_L(0); PG8_BAR; PG8_MMA2B(0, At, At2, B0); PG8_BAR; PG8_SCHED;
	ds_read_b128 v[68:71], v223
	ds_read_b128 v[84:87], v223 offset:1024
	ds_read_b128 v[88:91], v223 offset:2048
	ds_read_b128 v[92:95], v223 offset:3072
	ds_read_b128 v[132:135], v221 offset:32768
	ds_read_b128 v[140:143], v221 offset:33792
	ds_read_b128 v[152:155], v221 offset:34816
	ds_read_b128 v[156:159], v221 offset:35840
	ds_read_b128 v[166:169], v221 offset:36864
	ds_read_b128 v[178:181], v221 offset:37888
	ds_read_b128 v[182:185], v221 offset:38912
	ds_read_b128 v[186:189], v221 offset:39936
	ds_read_b128 v[190:193], v221 offset:49152
	ds_read_b128 v[194:197], v221 offset:50176
	ds_read_b128 v[198:201], v221 offset:51200
	ds_read_b128 v[202:205], v221 offset:52224
	ds_read_b128 v[226:229], v221 offset:53248
	ds_read_b128 v[230:233], v221 offset:54272
	ds_read_b128 v[234:237], v221 offset:55296
	ds_read_b128 v[238:241], v221 offset:56320
	s_add_u32 s10, s84, 0x40000
	s_addc_u32 s11, s85, 0
	s_mov_b32 m0, s53
	s_nop 0
	global_load_lds_dwordx4 v217, s[10:11]
	s_mov_b32 m0, s54
	s_nop 0
	global_load_lds_dwordx4 v219, s[10:11]
	s_waitcnt vmcnt(8)
	s_waitcnt lgkmcnt(0)
	s_barrier
	s_waitcnt lgkmcnt(14)
	v_mfma_f32_16x16x32_bf16 v[80:83], v[68:71], v[132:135], v[80:83]
	v_mfma_f32_16x16x32_bf16 v[76:79], v[88:91], v[132:135], v[76:79]
	s_waitcnt lgkmcnt(13)
	v_mfma_f32_16x16x32_bf16 v[148:151], v[68:71], v[152:155], v[148:151]
	v_mfma_f32_16x16x32_bf16 v[52:55], v[88:91], v[152:155], v[52:55]
	s_waitcnt lgkmcnt(11)
	v_mfma_f32_16x16x32_bf16 v[144:147], v[68:71], v[166:169], v[144:147]
	v_mfma_f32_16x16x32_bf16 v[48:51], v[88:91], v[166:169], v[48:51]
	s_waitcnt lgkmcnt(9)
	v_mfma_f32_16x16x32_bf16 v[136:139], v[68:71], v[182:185], v[136:139]
	v_mfma_f32_16x16x32_bf16 v[40:43], v[88:91], v[182:185], v[40:43]
	s_waitcnt lgkmcnt(7)
	v_mfma_f32_16x16x32_bf16 v[124:127], v[68:71], v[190:193], v[124:127]
	v_mfma_f32_16x16x32_bf16 v[28:31], v[88:91], v[190:193], v[28:31]
	s_waitcnt lgkmcnt(5)
	v_mfma_f32_16x16x32_bf16 v[120:123], v[68:71], v[198:201], v[120:123]
	v_mfma_f32_16x16x32_bf16 v[24:27], v[88:91], v[198:201], v[24:27]
	s_waitcnt lgkmcnt(3)
	v_mfma_f32_16x16x32_bf16 v[112:115], v[68:71], v[226:229], v[112:115]
	v_mfma_f32_16x16x32_bf16 v[16:19], v[88:91], v[226:229], v[16:19]
	s_waitcnt lgkmcnt(1)
	v_mfma_f32_16x16x32_bf16 v[64:67], v[68:71], v[234:237], v[64:67]
	v_mfma_f32_16x16x32_bf16 v[4:7], v[88:91], v[234:237], v[4:7]
	v_mfma_f32_16x16x32_bf16 v[80:83], v[84:87], v[140:143], v[80:83]
	v_mfma_f32_16x16x32_bf16 v[76:79], v[92:95], v[140:143], v[76:79]
	v_mfma_f32_16x16x32_bf16 v[148:151], v[84:87], v[156:159], v[148:151]
	v_mfma_f32_16x16x32_bf16 v[52:55], v[92:95], v[156:159], v[52:55]
	v_mfma_f32_16x16x32_bf16 v[144:147], v[84:87], v[178:181], v[144:147]
	v_mfma_f32_16x16x32_bf16 v[48:51], v[92:95], v[178:181], v[48:51]
	v_mfma_f32_16x16x32_bf16 v[136:139], v[84:87], v[186:189], v[136:139]
	v_mfma_f32_16x16x32_bf16 v[40:43], v[92:95], v[186:189], v[40:43]
	v_mfma_f32_16x16x32_bf16 v[124:127], v[84:87], v[194:197], v[124:127]
	v_mfma_f32_16x16x32_bf16 v[28:31], v[92:95], v[194:197], v[28:31]
	v_mfma_f32_16x16x32_bf16 v[120:123], v[84:87], v[202:205], v[120:123]
	v_mfma_f32_16x16x32_bf16 v[24:27], v[92:95], v[202:205], v[24:27]
	v_mfma_f32_16x16x32_bf16 v[112:115], v[84:87], v[230:233], v[112:115]
	v_mfma_f32_16x16x32_bf16 v[16:19], v[92:95], v[230:233], v[16:19]
	s_waitcnt lgkmcnt(0)
	v_mfma_f32_16x16x32_bf16 v[64:67], v[84:87], v[238:241], v[64:67]
	v_mfma_f32_16x16x32_bf16 v[4:7], v[92:95], v[238:241], v[4:7]
	s_barrier
; #define PG8_STAGE(bufoff, gbase, voff) do { _Pragma("unroll") for (int _i = 0; _i < 2; ++_i) { \
;         const unsigned _m0 = ldsu + (unsigned)(bufoff) + ldsw + (unsigned)(_i * 8192); \
;         asm volatile("s_mov_b32 m0, %2\n\ts_nop 0\n\tglobal_load_lds_dwordx4 %0, %1" :: "v"((voff)[_i]), "s"((const char*)(gbase)), "s"(_m0) : "memory"); } } while (0)
; #define PG8_LDB(dst, b, h) do { _Pragma("unroll") for (int n = 0; n < 2; ++n) _Pragma("unroll") for (int k = 0; k < 2; ++k) dst[n][k] = *(const LAS bf16x8*)(lds + bbase[b][h] + n * 2048 + k * 1024); } while (0)
; #define PG8_WAIT_V(n) asm volatile("s_waitcnt vmcnt(" #n ")" ::: "memory")
; #define PG8_WAIT_L(n) asm volatile("s_waitcnt lgkmcnt(" #n ")" ::: "memory")
; #define PG8_BAR __builtin_amdgcn_s_barrier()
; #define PG8_SCHED __builtin_amdgcn_sched_barrier(0)
; template <class Epi>
; __device__ __forceinline__ void gemm_phase(LAS unsigned char* lds, const Gemm g, const StaticOrder& S, const Epi& E) {
;     ...
;             PG8_LDB(B0, 1, 1); PG8_STAGE(PG8_SB(1, 0), b3, voffB); PG8_STAGE(PG8_SA(1, 0), a3, voffA); PG8_STAGE(PG8_SA(1, 1), a3 + hstepA, voffA);
;             PG8_WAIT_V(8); PG8_WAIT_L(0); PG8_BAR; PG8_MMA2B(1, At, At2, B0); PG8_BAR; PG8_SCHED;
;         }
;         if (wr == 0) PG8_BAR;
;         E(acc, cur, wr, wc, fr, fq);
;     __device__ __forceinline__ void operator()(f32x4 (&acc)[2][2][4][2], const Unit& u, int wr, int wc, int fr, int fq) const {
;     ...
;         { const int t = (wc * 4 + fq) * 16 + fr;
;           if (wr == 0) { const float* sp = ssq + ((size_t)u.pm * 256 + t) * 16; const f32x4 a = *(const f32x4*)sp, b = *(const f32x4*)(sp + 4), c = *(const f32x4*)(sp + 8), d = *(const f32x4*)(sp + 12);
	s_add_u32 s10, s84, 0x80
	ds_read_b128 v[68:71], v224
	ds_read_b128 v[84:87], v224 offset:1024
	ds_read_b128 v[88:91], v224 offset:2048
	ds_read_b128 v[92:95], v224 offset:3072
	s_addc_u32 s11, s85, 0
	s_mov_b32 m0, s88
	s_nop 0
	global_load_lds_dwordx4 v217, s[10:11]
	s_mov_b32 m0, s89
	s_nop 0
	global_load_lds_dwordx4 v219, s[10:11]
	s_mov_b32 m0, s95
	s_nop 0
	global_load_lds_dwordx4 v216, s[16:17]
	s_mov_b32 m0, s37
	s_nop 0
	global_load_lds_dwordx4 v218, s[16:17]
	s_add_u32 s10, s14, 0x40080
	s_addc_u32 s11, s15, 0
	s_mov_b32 m0, s56
	s_nop 0
	global_load_lds_dwordx4 v216, s[10:11]
	s_mov_b32 m0, s57
	s_nop 0
	global_load_lds_dwordx4 v218, s[10:11]
	s_waitcnt vmcnt(8)
	s_waitcnt lgkmcnt(0)
	s_barrier
	s_waitcnt lgkmcnt(3)
	v_mfma_f32_16x16x32_bf16 v[72:75], v[68:71], v[132:135], v[72:75]
	s_waitcnt lgkmcnt(1)
	v_mfma_f32_16x16x32_bf16 v[56:59], v[88:91], v[132:135], v[56:59]
	v_mfma_f32_16x16x32_bf16 v[96:99], v[68:71], v[152:155], v[96:99]
	v_mfma_f32_16x16x32_bf16 v[72:75], v[84:87], v[140:143], v[72:75]
	s_waitcnt lgkmcnt(0)
	v_mfma_f32_16x16x32_bf16 v[56:59], v[92:95], v[140:143], v[56:59]
	v_mfma_f32_16x16x32_bf16 v[140:143], v[84:87], v[156:159], v[96:99]
	v_mfma_f32_16x16x32_bf16 v[96:99], v[68:71], v[166:169], v[100:103]
	v_mfma_f32_16x16x32_bf16 v[132:135], v[84:87], v[178:181], v[96:99]
	v_mfma_f32_16x16x32_bf16 v[96:99], v[68:71], v[182:185], v[128:131]
	v_mfma_f32_16x16x32_bf16 v[128:131], v[84:87], v[186:189], v[96:99]
	v_mfma_f32_16x16x32_bf16 v[96:99], v[68:71], v[190:193], v[116:119]
	v_mfma_f32_16x16x32_bf16 v[116:119], v[84:87], v[194:197], v[96:99]
	v_mfma_f32_16x16x32_bf16 v[96:99], v[68:71], v[198:201], v[108:111]
	v_mfma_f32_16x16x32_bf16 v[44:47], v[88:91], v[152:155], v[44:47]
	v_mfma_f32_16x16x32_bf16 v[36:39], v[88:91], v[166:169], v[36:39]
	v_mfma_f32_16x16x32_bf16 v[32:35], v[88:91], v[182:185], v[32:35]
	v_mfma_f32_16x16x32_bf16 v[20:23], v[88:91], v[190:193], v[20:23]
	v_mfma_f32_16x16x32_bf16 v[108:111], v[84:87], v[202:205], v[96:99]
	v_mfma_f32_16x16x32_bf16 v[12:15], v[88:91], v[198:201], v[12:15]
	v_mfma_f32_16x16x32_bf16 v[96:99], v[68:71], v[226:229], v[104:107]
	v_mfma_f32_16x16x32_bf16 v[8:11], v[88:91], v[226:229], v[8:11]
	v_mfma_f32_16x16x32_bf16 v[60:63], v[68:71], v[234:237], v[60:63]
	v_mfma_f32_16x16x32_bf16 v[0:3], v[88:91], v[234:237], v[0:3]
	v_mfma_f32_16x16x32_bf16 v[44:47], v[92:95], v[156:159], v[44:47]
	v_mfma_f32_16x16x32_bf16 v[36:39], v[92:95], v[178:181], v[36:39]
	v_mfma_f32_16x16x32_bf16 v[32:35], v[92:95], v[186:189], v[32:35]
	v_mfma_f32_16x16x32_bf16 v[20:23], v[92:95], v[194:197], v[20:23]
	v_mfma_f32_16x16x32_bf16 v[12:15], v[92:95], v[202:205], v[12:15]
	v_mfma_f32_16x16x32_bf16 v[104:107], v[84:87], v[230:233], v[96:99]
	v_mfma_f32_16x16x32_bf16 v[8:11], v[92:95], v[230:233], v[8:11]
	v_mfma_f32_16x16x32_bf16 v[60:63], v[84:87], v[238:241], v[60:63]
	v_mfma_f32_16x16x32_bf16 v[0:3], v[92:95], v[238:241], v[0:3]
	s_barrier
	s_add_i32 s69, s69, 2
	s_add_u32 vcc_hi, vcc_hi, 0x100
	s_addc_u32 s68, s68, 0
	s_cmp_gt_u32 s69, 13
	s_mov_b64 s[10:11], s[12:13]
	s_cbranch_scc0 .LBB0_1027
	s_and_b64 vcc, exec, s[90:91]
	s_cbranch_vccz .LBB0_1030
	v_lshlrev_b32_e32 v68, 4, v215
	v_add3_u32 v68, v214, s59, v68
	s_ashr_i32 s97, s96, 31
	s_lshl_b64 s[12:13], s[96:97], 14
	v_ashrrev_i32_e32 v69, 31, v68
	s_add_u32 s12, s18, s12
	s_addc_u32 s13, s19, s13
	v_lshlrev_b64 v[70:71], 6, v[68:69]
	v_lshl_add_u64 v[70:71], s[12:13], 0, v[70:71]
	global_load_dwordx4 v[86:89], v[70:71], off
	global_load_dwordx4 v[90:93], v[70:71], off offset:16
	global_load_dwordx4 v[94:97], v[70:71], off offset:32
	global_load_dwordx4 v[98:101], v[70:71], off offset:48
	s_barrier

; #define PG8_STAGE(bufoff, gbase, voff) do { _Pragma("unroll") for (int _i = 0; _i < 2; ++_i) { \
;         const unsigned _m0 = ldsu + (unsigned)(bufoff) + ldsw + (unsigned)(_i * 8192); \
;         asm volatile("s_mov_b32 m0, %2\n\ts_nop 0\n\tglobal_load_lds_dwordx4 %0, %1" :: "v"((voff)[_i]), "s"((const char*)(gbase)), "s"(_m0) : "memory"); } } while (0)
; #define PG8_LDA(dst, b, h) do { _Pragma("unroll") for (int m = 0; m < 4; ++m) _Pragma("unroll") for (int k = 0; k < 2; ++k) dst[m][k] = *(const LAS bf16x8*)(lds + PG8_SA(b, h) + aoff + m * 2048 + k * 1024); } while (0)
; #define PG8_LDB(dst, b, h) do { _Pragma("unroll") for (int n = 0; n < 2; ++n) _Pragma("unroll") for (int k = 0; k < 2; ++k) dst[n][k] = *(const LAS bf16x8*)(lds + bbase[b][h] + n * 2048 + k * 1024); } while (0)
; #define PG8_WAIT_V(n) asm volatile("s_waitcnt vmcnt(" #n ")" ::: "memory")
; #define PG8_WAIT_L(n) asm volatile("s_waitcnt lgkmcnt(" #n ")" ::: "memory")
; #define PG8_BAR __builtin_amdgcn_s_barrier()
; #define PG8_SCHED __builtin_amdgcn_sched_barrier(0)
; template <class Epi>
; __device__ __forceinline__ void gemm_phase(LAS unsigned char* lds, const Gemm g, const StaticOrder& S, const Epi& E) {
;     ...
;             PG8_LDB(B0, 0, 0); PG8_SCHED; PG8_LDA(At, 0, 0); PG8_LDA(At2, 0, 1); PG8_STAGE(PG8_SB(1, 1), b1 + hstepB, voffB);
;             PG8_WAIT_V(8); PG8_WAIT_L(0); PG8_BAR; PG8_MMA2B(0, At, At2, B0); PG8_BAR; PG8_SCHED;
;             PG8_LDB(B0, 0, 1); PG8_STAGE(PG8_SB(0, 0), b2, voffB); PG8_STAGE(PG8_SA(0, 0), a2, voffA); PG8_STAGE(PG8_SA(0, 1), a2 + hstepA, voffA);
;             PG8_WAIT_V(8); PG8_WAIT_L(0); PG8_BAR; PG8_MMA2B(1, At, At2, B0); PG8_BAR; PG8_SCHED;
.LBB0_1140:
	ds_read_b128 v[128:131], v138
	ds_read_b128 v[144:147], v138 offset:1024
	ds_read_b128 v[148:151], v138 offset:2048
	ds_read_b128 v[152:155], v138 offset:3072
	s_cmp_eq_u32 s68, 40
	s_cselect_b32 s14, s4, s80
	s_cselect_b32 s15, s5, s81
	s_cselect_b32 s42, s10, s82
	s_cselect_b32 s43, s11, s83
	s_add_u32 s16, s14, 0x80
	s_addc_u32 s17, s15, 0
	s_add_u32 s38, s42, 0x80
	s_addc_u32 s39, s43, 0
	ds_read_b128 v[156:159], v139
	ds_read_b128 v[166:169], v139 offset:1024
	ds_read_b128 v[178:181], v139 offset:2048
	ds_read_b128 v[182:185], v139 offset:3072
	ds_read_b128 v[186:189], v139 offset:4096
	ds_read_b128 v[190:193], v139 offset:5120
	ds_read_b128 v[194:197], v139 offset:6144
	ds_read_b128 v[198:201], v139 offset:7168
	ds_read_b128 v[202:205], v139 offset:16384
	ds_read_b128 v[214:217], v139 offset:17408
	ds_read_b128 v[218:221], v139 offset:18432
	ds_read_b128 v[222:225], v139 offset:19456
	ds_read_b128 v[226:229], v139 offset:20480
	ds_read_b128 v[230:233], v139 offset:21504
	ds_read_b128 v[234:237], v139 offset:22528
	ds_read_b128 v[238:241], v139 offset:23552
	s_mov_b32 m0, s61
	s_nop 0
	global_load_lds_dwordx4 v133, s[12:13]
	s_mov_b32 m0, s63
	s_nop 0
	global_load_lds_dwordx4 v135, s[12:13]
	s_waitcnt vmcnt(8)
	s_waitcnt lgkmcnt(0)
	s_barrier
	s_waitcnt lgkmcnt(14)
	v_mfma_f32_16x16x32_bf16 v[124:127], v[128:131], v[156:159], v[124:127]
	v_mfma_f32_16x16x32_bf16 v[120:123], v[148:151], v[156:159], v[120:123]
	s_waitcnt lgkmcnt(13)
	v_mfma_f32_16x16x32_bf16 v[108:111], v[128:131], v[178:181], v[108:111]
	v_mfma_f32_16x16x32_bf16 v[104:107], v[148:151], v[178:181], v[104:107]
	s_waitcnt lgkmcnt(11)
	v_mfma_f32_16x16x32_bf16 v[92:95], v[128:131], v[186:189], v[92:95]
	v_mfma_f32_16x16x32_bf16 v[88:91], v[148:151], v[186:189], v[88:91]
	s_waitcnt lgkmcnt(9)
	v_mfma_f32_16x16x32_bf16 v[76:79], v[128:131], v[194:197], v[76:79]
	v_mfma_f32_16x16x32_bf16 v[72:75], v[148:151], v[194:197], v[72:75]
	s_waitcnt lgkmcnt(7)
	v_mfma_f32_16x16x32_bf16 v[60:63], v[128:131], v[202:205], v[60:63]
	v_mfma_f32_16x16x32_bf16 v[56:59], v[148:151], v[202:205], v[56:59]
	s_waitcnt lgkmcnt(5)
	v_mfma_f32_16x16x32_bf16 v[44:47], v[128:131], v[218:221], v[44:47]
	v_mfma_f32_16x16x32_bf16 v[40:43], v[148:151], v[218:221], v[40:43]
	s_waitcnt lgkmcnt(3)
	v_mfma_f32_16x16x32_bf16 v[28:31], v[128:131], v[226:229], v[28:31]
	v_mfma_f32_16x16x32_bf16 v[24:27], v[148:151], v[226:229], v[24:27]
	s_waitcnt lgkmcnt(1)
	v_mfma_f32_16x16x32_bf16 v[12:15], v[128:131], v[234:237], v[12:15]
	v_mfma_f32_16x16x32_bf16 v[8:11], v[148:151], v[234:237], v[8:11]
	v_mfma_f32_16x16x32_bf16 v[124:127], v[144:147], v[166:169], v[124:127]
	v_mfma_f32_16x16x32_bf16 v[120:123], v[152:155], v[166:169], v[120:123]
	v_mfma_f32_16x16x32_bf16 v[108:111], v[144:147], v[182:185], v[108:111]
	v_mfma_f32_16x16x32_bf16 v[104:107], v[152:155], v[182:185], v[104:107]
	v_mfma_f32_16x16x32_bf16 v[92:95], v[144:147], v[190:193], v[92:95]
	v_mfma_f32_16x16x32_bf16 v[88:91], v[152:155], v[190:193], v[88:91]
	v_mfma_f32_16x16x32_bf16 v[76:79], v[144:147], v[198:201], v[76:79]
	v_mfma_f32_16x16x32_bf16 v[72:75], v[152:155], v[198:201], v[72:75]
	v_mfma_f32_16x16x32_bf16 v[60:63], v[144:147], v[214:217], v[60:63]
	v_mfma_f32_16x16x32_bf16 v[56:59], v[152:155], v[214:217], v[56:59]
	v_mfma_f32_16x16x32_bf16 v[44:47], v[144:147], v[222:225], v[44:47]
	v_mfma_f32_16x16x32_bf16 v[40:43], v[152:155], v[222:225], v[40:43]
	v_mfma_f32_16x16x32_bf16 v[28:31], v[144:147], v[230:233], v[28:31]
	v_mfma_f32_16x16x32_bf16 v[24:27], v[152:155], v[230:233], v[24:27]
	s_waitcnt lgkmcnt(0)
	v_mfma_f32_16x16x32_bf16 v[12:15], v[144:147], v[238:241], v[12:15]
	v_mfma_f32_16x16x32_bf16 v[8:11], v[152:155], v[238:241], v[8:11]
	s_barrier
	ds_read_b128 v[128:131], v140
	ds_read_b128 v[144:147], v140 offset:1024
	ds_read_b128 v[148:151], v140 offset:2048
	ds_read_b128 v[152:155], v140 offset:3072
	s_mov_b32 m0, s48
	s_nop 0
	global_load_lds_dwordx4 v133, s[42:43]
	s_mov_b32 m0, s49
	s_nop 0
	global_load_lds_dwordx4 v135, s[42:43]
	s_mov_b32 m0, s47
	s_nop 0
	global_load_lds_dwordx4 v132, s[14:15]
	s_mov_b32 m0, s50
	s_nop 0
	global_load_lds_dwordx4 v134, s[14:15]
	s_add_u32 s84, s14, 0xb0000
	s_addc_u32 s85, s15, 0
	s_mov_b32 m0, s51
	s_nop 0
	global_load_lds_dwordx4 v132, s[84:85]
	s_mov_b32 m0, s52
	s_nop 0
	global_load_lds_dwordx4 v134, s[84:85]
	s_waitcnt vmcnt(8)
	s_waitcnt lgkmcnt(0)
	s_barrier
	s_waitcnt lgkmcnt(3)
	v_mfma_f32_16x16x32_bf16 v[116:119], v[128:131], v[156:159], v[116:119]
	s_waitcnt lgkmcnt(1)
	v_mfma_f32_16x16x32_bf16 v[112:115], v[148:151], v[156:159], v[112:115]
	v_mfma_f32_16x16x32_bf16 v[100:103], v[128:131], v[178:181], v[100:103]
	v_mfma_f32_16x16x32_bf16 v[96:99], v[148:151], v[178:181], v[96:99]
	v_mfma_f32_16x16x32_bf16 v[84:87], v[128:131], v[186:189], v[84:87]
	v_mfma_f32_16x16x32_bf16 v[80:83], v[148:151], v[186:189], v[80:83]
	v_mfma_f32_16x16x32_bf16 v[68:71], v[128:131], v[194:197], v[68:71]
	v_mfma_f32_16x16x32_bf16 v[64:67], v[148:151], v[194:197], v[64:67]
	v_mfma_f32_16x16x32_bf16 v[52:55], v[128:131], v[202:205], v[52:55]
	v_mfma_f32_16x16x32_bf16 v[48:51], v[148:151], v[202:205], v[48:51]
	v_mfma_f32_16x16x32_bf16 v[36:39], v[128:131], v[218:221], v[36:39]
	v_mfma_f32_16x16x32_bf16 v[32:35], v[148:151], v[218:221], v[32:35]
	v_mfma_f32_16x16x32_bf16 v[20:23], v[128:131], v[226:229], v[20:23]
	v_mfma_f32_16x16x32_bf16 v[16:19], v[148:151], v[226:229], v[16:19]
	v_mfma_f32_16x16x32_bf16 v[4:7], v[128:131], v[234:237], v[4:7]
	v_mfma_f32_16x16x32_bf16 v[0:3], v[148:151], v[234:237], v[0:3]
	v_mfma_f32_16x16x32_bf16 v[116:119], v[144:147], v[166:169], v[116:119]
	s_waitcnt lgkmcnt(0)
	v_mfma_f32_16x16x32_bf16 v[112:115], v[152:155], v[166:169], v[112:115]
	v_mfma_f32_16x16x32_bf16 v[100:103], v[144:147], v[182:185], v[100:103]
	v_mfma_f32_16x16x32_bf16 v[96:99], v[152:155], v[182:185], v[96:99]
	v_mfma_f32_16x16x32_bf16 v[84:87], v[144:147], v[190:193], v[84:87]
	v_mfma_f32_16x16x32_bf16 v[80:83], v[152:155], v[190:193], v[80:83]
	v_mfma_f32_16x16x32_bf16 v[68:71], v[144:147], v[198:201], v[68:71]
	v_mfma_f32_16x16x32_bf16 v[64:67], v[152:155], v[198:201], v[64:67]
	v_mfma_f32_16x16x32_bf16 v[52:55], v[144:147], v[214:217], v[52:55]
	v_mfma_f32_16x16x32_bf16 v[48:51], v[152:155], v[214:217], v[48:51]
	v_mfma_f32_16x16x32_bf16 v[36:39], v[144:147], v[222:225], v[36:39]
	v_mfma_f32_16x16x32_bf16 v[32:35], v[152:155], v[222:225], v[32:35]
	v_mfma_f32_16x16x32_bf16 v[20:23], v[144:147], v[230:233], v[20:23]
	v_mfma_f32_16x16x32_bf16 v[16:19], v[152:155], v[230:233], v[16:19]
	v_mfma_f32_16x16x32_bf16 v[4:7], v[144:147], v[238:241], v[4:7]
	v_mfma_f32_16x16x32_bf16 v[0:3], v[152:155], v[238:241], v[0:3]
	s_barrier
; #define PG8_STAGE(bufoff, gbase, voff) do { _Pragma("unroll") for (int _i = 0; _i < 2; ++_i) { \
;         const unsigned _m0 = ldsu + (unsigned)(bufoff) + ldsw + (unsigned)(_i * 8192); \
;         asm volatile("s_mov_b32 m0, %2\n\ts_nop 0\n\tglobal_load_lds_dwordx4 %0, %1" :: "v"((voff)[_i]), "s"((const char*)(gbase)), "s"(_m0) : "memory"); } } while (0)
; #define PG8_LDA(dst, b, h) do { _Pragma("unroll") for (int m = 0; m < 4; ++m) _Pragma("unroll") for (int k = 0; k < 2; ++k) dst[m][k] = *(const LAS bf16x8*)(lds + PG8_SA(b, h) + aoff + m * 2048 + k * 1024); } while (0)
; #define PG8_LDB(dst, b, h) do { _Pragma("unroll") for (int n = 0; n < 2; ++n) _Pragma("unroll") for (int k = 0; k < 2; ++k) dst[n][k] = *(const LAS bf16x8*)(lds + bbase[b][h] + n * 2048 + k * 1024); } while (0)
; #define PG8_WAIT_V(n) asm volatile("s_waitcnt vmcnt(" #n ")" ::: "memory")
; #define PG8_WAIT_L(n) asm volatile("s_waitcnt lgkmcnt(" #n ")" ::: "memory")
; #define PG8_BAR __builtin_amdgcn_s_barrier()
; #define PG8_SCHED __builtin_amdgcn_sched_barrier(0)
; template <class Epi>
; __device__ __forceinline__ void gemm_phase(LAS unsigned char* lds, const Gemm g, const StaticOrder& S, const Epi& E) {
;     ...
;             PG8_LDB(B0, 1, 0); PG8_SCHED; PG8_LDA(At, 1, 0); PG8_LDA(At2, 1, 1); PG8_STAGE(PG8_SB(0, 1), b2 + hstepB, voffB);
;             PG8_WAIT_V(8); PG8_WAIT_L(0); PG8_BAR; PG8_MMA2B(0, At, At2, B0); PG8_BAR; PG8_SCHED;
;             PG8_LDB(B0, 1, 1); PG8_STAGE(PG8_SB(1, 0), b3, voffB); PG8_STAGE(PG8_SA(1, 0), a3, voffA); PG8_STAGE(PG8_SA(1, 1), a3 + hstepA, voffA);
;             PG8_WAIT_V(8); PG8_WAIT_L(0); PG8_BAR; PG8_MMA2B(1, At, At2, B0); PG8_BAR; PG8_SCHED;
;         }
	ds_read_b128 v[128:131], v141
	ds_read_b128 v[144:147], v141 offset:1024
	ds_read_b128 v[148:151], v141 offset:2048
	ds_read_b128 v[152:155], v141 offset:3072
	ds_read_b128 v[156:159], v139 offset:32768
	ds_read_b128 v[166:169], v139 offset:33792
	ds_read_b128 v[178:181], v139 offset:34816
	ds_read_b128 v[182:185], v139 offset:35840
	ds_read_b128 v[186:189], v139 offset:36864
	ds_read_b128 v[190:193], v139 offset:37888
	ds_read_b128 v[194:197], v139 offset:38912
	ds_read_b128 v[198:201], v139 offset:39936
	ds_read_b128 v[202:205], v139 offset:49152
	ds_read_b128 v[214:217], v139 offset:50176
	ds_read_b128 v[218:221], v139 offset:51200
	ds_read_b128 v[222:225], v139 offset:52224
	ds_read_b128 v[226:229], v139 offset:53248
	ds_read_b128 v[230:233], v139 offset:54272
	ds_read_b128 v[234:237], v139 offset:55296
	ds_read_b128 v[238:241], v139 offset:56320
	s_add_u32 s42, s42, 0xb0000
	s_addc_u32 s43, s43, 0
	s_mov_b32 m0, s53
	s_nop 0
	global_load_lds_dwordx4 v133, s[42:43]
	s_mov_b32 m0, s54
	s_nop 0
	global_load_lds_dwordx4 v135, s[42:43]
	s_waitcnt vmcnt(8)
	s_waitcnt lgkmcnt(0)
	s_barrier
	s_waitcnt lgkmcnt(14)
	v_mfma_f32_16x16x32_bf16 v[124:127], v[128:131], v[156:159], v[124:127]
	v_mfma_f32_16x16x32_bf16 v[120:123], v[148:151], v[156:159], v[120:123]
	s_waitcnt lgkmcnt(13)
	v_mfma_f32_16x16x32_bf16 v[108:111], v[128:131], v[178:181], v[108:111]
	v_mfma_f32_16x16x32_bf16 v[104:107], v[148:151], v[178:181], v[104:107]
	s_waitcnt lgkmcnt(11)
	v_mfma_f32_16x16x32_bf16 v[92:95], v[128:131], v[186:189], v[92:95]
	v_mfma_f32_16x16x32_bf16 v[88:91], v[148:151], v[186:189], v[88:91]
	s_waitcnt lgkmcnt(9)
	v_mfma_f32_16x16x32_bf16 v[76:79], v[128:131], v[194:197], v[76:79]
	v_mfma_f32_16x16x32_bf16 v[72:75], v[148:151], v[194:197], v[72:75]
	s_waitcnt lgkmcnt(7)
	v_mfma_f32_16x16x32_bf16 v[60:63], v[128:131], v[202:205], v[60:63]
	v_mfma_f32_16x16x32_bf16 v[56:59], v[148:151], v[202:205], v[56:59]
	s_waitcnt lgkmcnt(5)
	v_mfma_f32_16x16x32_bf16 v[44:47], v[128:131], v[218:221], v[44:47]
	v_mfma_f32_16x16x32_bf16 v[40:43], v[148:151], v[218:221], v[40:43]
	s_waitcnt lgkmcnt(3)
	v_mfma_f32_16x16x32_bf16 v[28:31], v[128:131], v[226:229], v[28:31]
	v_mfma_f32_16x16x32_bf16 v[24:27], v[148:151], v[226:229], v[24:27]
	s_waitcnt lgkmcnt(1)
	v_mfma_f32_16x16x32_bf16 v[12:15], v[128:131], v[234:237], v[12:15]
	v_mfma_f32_16x16x32_bf16 v[8:11], v[148:151], v[234:237], v[8:11]
	v_mfma_f32_16x16x32_bf16 v[124:127], v[144:147], v[166:169], v[124:127]
	v_mfma_f32_16x16x32_bf16 v[120:123], v[152:155], v[166:169], v[120:123]
	v_mfma_f32_16x16x32_bf16 v[108:111], v[144:147], v[182:185], v[108:111]
	v_mfma_f32_16x16x32_bf16 v[104:107], v[152:155], v[182:185], v[104:107]
	v_mfma_f32_16x16x32_bf16 v[92:95], v[144:147], v[190:193], v[92:95]
	v_mfma_f32_16x16x32_bf16 v[88:91], v[152:155], v[190:193], v[88:91]
	v_mfma_f32_16x16x32_bf16 v[76:79], v[144:147], v[198:201], v[76:79]
	v_mfma_f32_16x16x32_bf16 v[72:75], v[152:155], v[198:201], v[72:75]
	v_mfma_f32_16x16x32_bf16 v[60:63], v[144:147], v[214:217], v[60:63]
	v_mfma_f32_16x16x32_bf16 v[56:59], v[152:155], v[214:217], v[56:59]
	v_mfma_f32_16x16x32_bf16 v[44:47], v[144:147], v[222:225], v[44:47]
	v_mfma_f32_16x16x32_bf16 v[40:43], v[152:155], v[222:225], v[40:43]
	v_mfma_f32_16x16x32_bf16 v[28:31], v[144:147], v[230:233], v[28:31]
	v_mfma_f32_16x16x32_bf16 v[24:27], v[152:155], v[230:233], v[24:27]
	s_waitcnt lgkmcnt(0)
	v_mfma_f32_16x16x32_bf16 v[12:15], v[144:147], v[238:241], v[12:15]
	v_mfma_f32_16x16x32_bf16 v[8:11], v[152:155], v[238:241], v[8:11]
	s_barrier
	ds_read_b128 v[128:131], v142
	ds_read_b128 v[144:147], v142 offset:1024
	ds_read_b128 v[148:151], v142 offset:2048
	ds_read_b128 v[152:155], v142 offset:3072
	s_mov_b32 m0, s55
	s_nop 0
	global_load_lds_dwordx4 v133, s[38:39]
	s_mov_b32 m0, s56
	s_nop 0
	global_load_lds_dwordx4 v135, s[38:39]
	s_mov_b32 m0, s57
	s_nop 0
	global_load_lds_dwordx4 v132, s[16:17]
	s_mov_b32 m0, s58
	s_nop 0
	global_load_lds_dwordx4 v134, s[16:17]
	s_add_u32 s14, s14, 0xb0080
	s_addc_u32 s15, s15, 0
	s_mov_b32 m0, s59
	s_nop 0
	global_load_lds_dwordx4 v132, s[14:15]
	s_mov_b32 m0, s60
	s_nop 0
	global_load_lds_dwordx4 v134, s[14:15]
	s_waitcnt vmcnt(8)
	s_waitcnt lgkmcnt(0)
	s_barrier
	s_waitcnt lgkmcnt(3)
	v_mfma_f32_16x16x32_bf16 v[116:119], v[128:131], v[156:159], v[116:119]
	s_waitcnt lgkmcnt(1)
	v_mfma_f32_16x16x32_bf16 v[112:115], v[148:151], v[156:159], v[112:115]
	v_mfma_f32_16x16x32_bf16 v[100:103], v[128:131], v[178:181], v[100:103]
	v_mfma_f32_16x16x32_bf16 v[96:99], v[148:151], v[178:181], v[96:99]
	v_mfma_f32_16x16x32_bf16 v[84:87], v[128:131], v[186:189], v[84:87]
	v_mfma_f32_16x16x32_bf16 v[80:83], v[148:151], v[186:189], v[80:83]
	v_mfma_f32_16x16x32_bf16 v[68:71], v[128:131], v[194:197], v[68:71]
	v_mfma_f32_16x16x32_bf16 v[64:67], v[148:151], v[194:197], v[64:67]
	v_mfma_f32_16x16x32_bf16 v[52:55], v[128:131], v[202:205], v[52:55]
	v_mfma_f32_16x16x32_bf16 v[48:51], v[148:151], v[202:205], v[48:51]
	v_mfma_f32_16x16x32_bf16 v[36:39], v[128:131], v[218:221], v[36:39]
	v_mfma_f32_16x16x32_bf16 v[32:35], v[148:151], v[218:221], v[32:35]
	v_mfma_f32_16x16x32_bf16 v[20:23], v[128:131], v[226:229], v[20:23]
	v_mfma_f32_16x16x32_bf16 v[16:19], v[148:151], v[226:229], v[16:19]
	v_mfma_f32_16x16x32_bf16 v[4:7], v[128:131], v[234:237], v[4:7]
	v_mfma_f32_16x16x32_bf16 v[0:3], v[148:151], v[234:237], v[0:3]
	v_mfma_f32_16x16x32_bf16 v[116:119], v[144:147], v[166:169], v[116:119]
	s_waitcnt lgkmcnt(0)
	v_mfma_f32_16x16x32_bf16 v[112:115], v[152:155], v[166:169], v[112:115]
	v_mfma_f32_16x16x32_bf16 v[100:103], v[144:147], v[182:185], v[100:103]
	v_mfma_f32_16x16x32_bf16 v[96:99], v[152:155], v[182:185], v[96:99]
	v_mfma_f32_16x16x32_bf16 v[84:87], v[144:147], v[190:193], v[84:87]
	v_mfma_f32_16x16x32_bf16 v[80:83], v[152:155], v[190:193], v[80:83]
	v_mfma_f32_16x16x32_bf16 v[68:71], v[144:147], v[198:201], v[68:71]
	v_mfma_f32_16x16x32_bf16 v[64:67], v[152:155], v[198:201], v[64:67]
	v_mfma_f32_16x16x32_bf16 v[52:55], v[144:147], v[214:217], v[52:55]
	v_mfma_f32_16x16x32_bf16 v[48:51], v[152:155], v[214:217], v[48:51]
	v_mfma_f32_16x16x32_bf16 v[36:39], v[144:147], v[222:225], v[36:39]
	v_mfma_f32_16x16x32_bf16 v[32:35], v[152:155], v[222:225], v[32:35]
	v_mfma_f32_16x16x32_bf16 v[20:23], v[144:147], v[230:233], v[20:23]
	v_mfma_f32_16x16x32_bf16 v[16:19], v[152:155], v[230:233], v[16:19]
	v_mfma_f32_16x16x32_bf16 v[4:7], v[144:147], v[238:241], v[4:7]
	v_mfma_f32_16x16x32_bf16 v[0:3], v[152:155], v[238:241], v[0:3]
	s_barrier
	s_add_i32 s68, s68, 2
	s_add_u32 s12, s12, 0x100
	s_addc_u32 s13, s13, 0
	s_add_u32 s80, s80, 0x100
	s_addc_u32 s81, s81, 0
	s_add_u32 s82, s82, 0x100
	s_addc_u32 s83, s83, 0
	s_cmp_gt_u32 s68, 41
	s_cbranch_scc0 .LBB0_1140
	s_and_b64 vcc, exec, s[2:3]
	s_cbranch_vccz .LBB0_1143
	s_barrier
